# speedup vs baseline: 1.0171x; 1.0015x over previous
; #define PG8_STAGE(bufoff, gbase, voff) do { _Pragma("unroll") for (int _i = 0; _i < 2; ++_i) \
;     __builtin_amdgcn_global_load_lds((const unsigned*)((const char*)(gbase) + (voff)[_i]), (LAS unsigned*)(lds + (bufoff) + ldsw + _i * 8192), 16, 0, 0); } while (0)
; #define PG8_LDA(dst, b, h) do { _Pragma("unroll") for (int m = 0; m < 4; ++m) _Pragma("unroll") for (int k = 0; k < 2; ++k) dst[m][k] = *(const LAS bf16x8*)(lds + PG8_SA(b, h) + aoff + m * 2048 + k * 1024); } while (0)
; #define PG8_LDB(dst, b, h) do { _Pragma("unroll") for (int n = 0; n < 2; ++n) _Pragma("unroll") for (int k = 0; k < 2; ++k) dst[n][k] = *(const LAS bf16x8*)(lds + PG8_SB(b, h) + boff + n * 2048 + k * 1024); } while (0)
; #define PG8_WAIT_L(n) asm volatile("s_waitcnt lgkmcnt(" #n ")" ::: "memory")
; #define PG8_BAR __builtin_amdgcn_s_barrier()
; #define PG8_SCHED __builtin_amdgcn_sched_barrier(0)
; template <class Epi, bool SPLITA = false>
; __device__ __forceinline__ void gemm_phase(const int tid, LAS unsigned char* lds, const Gemm g, const Order& S, const Epi& E) {
;     ...
;     const bool has_next = S.next(ui + 1, nxt);
;     const char* nA = has_next ? (const char*)g.A + (size_t)nxt.pm * tstepA + (size_t)nxt.pn * apn : cA; const char* nA2 = (SPLITA && has_next) ? (const char*)g.A2 + (size_t)nxt.pm * tstepA : cA2; const char* nB = has_next ? (const char*)g.Bt + (size_t)nxt.pn * tstepB : cB;
;     for (int t = 0; t < nt; t += 2) {
;       const bool last = (t == nt - 2);
;       if constexpr (SPLITA) { if (t == nt1) E.mid(acc, cur, wr, wc, fr, fq); }
;       const char* a1 = PG8_TA(t + 1);
;       const char* a2 = last ? nA : PG8_TA(t + 2); const char* b2 = last ? nB : cB + (size_t)(t + 2) * kstep;
;       const char* a3 = last ? nA + kstep : PG8_TA(t + 3); const char* b3 = b2 + kstep;
;       PG8_LDB(B0, 0, 0); PG8_SCHED; PG8_LDA(At, 0, 0); PG8_STAGE(PG8_SA(1, 1), a1 + hstepA, voffA);
;       PG8_WAIT_L(8); PG8_BAR; PG8_WAIT_L(0); PG8_MMA(0, 0, At, B0); PG8_BAR; PG8_SCHED;
;       PG8_LDB(B1, 0, 1); PG8_STAGE(PG8_SB(0, 0), b2, voffB);
;       PG8_BAR; PG8_WAIT_L(0); PG8_MMA(0, 1, At, B1); PG8_BAR;
;       PG8_LDA(At, 0, 1); PG8_STAGE(PG8_SA(0, 0), a2, voffA);
;       PG8_BAR; PG8_WAIT_L(0); PG8_MMA(1, 0, At, B0); PG8_BAR; PG8_SCHED;
.LBB0_57:
	s_add_u32 s8, s12, s16
	s_addc_u32 s9, s13, s17
	s_add_u32 s20, s8, 0x100
	s_addc_u32 s21, s9, 0
	s_add_u32 s18, s53, s16
	s_addc_u32 s19, s54, s17
	s_add_u32 s8, s8, 0x180
	s_addc_u32 s9, s9, 0
	s_add_i32 s55, 0, 0x10000
	v_add_u32_e32 v146, s55, v172
	ds_read_b128 v[134:137], v146
	ds_read_b128 v[138:141], v146 offset:1024
	ds_read_b128 v[142:145], v146 offset:2048
	ds_read_b128 v[146:149], v146 offset:3072
	s_cmpk_eq_i32 s16, 0x2b00
	s_cselect_b32 s23, s7, s9
	s_cselect_b32 s22, s6, s8
	s_cselect_b32 s19, s11, s19
	s_cselect_b32 s18, s10, s18
	s_cselect_b32 s41, s1, s21
	s_cselect_b32 s40, s0, s20
	v_lshl_add_u64 v[168:169], v[130:131], 0, s[16:17]
	s_add_i32 m0, s4, 0xc000
	ds_read_b128 v[160:163], v173
	ds_read_b128 v[164:167], v173 offset:1024
	ds_read_b128 v[174:177], v173 offset:2048
	ds_read_b128 v[178:181], v173 offset:3072
	ds_read_b128 v[182:185], v173 offset:4096
	ds_read_b128 v[186:189], v173 offset:5120
	ds_read_b128 v[190:193], v173 offset:6144
	ds_read_b128 v[210:213], v173 offset:7168
	global_load_lds_dwordx4 v[168:169], off
	v_lshl_add_u64 v[168:169], v[132:133], 0, s[16:17]
	s_add_i32 m0, s4, 0xe000
	s_nop 0
	global_load_lds_dwordx4 v[168:169], off
	s_waitcnt lgkmcnt(8)
	s_barrier
	s_waitcnt lgkmcnt(0)
	s_setprio 1
	s_waitcnt lgkmcnt(0)
	v_mfma_f32_16x16x32_bf16 v[126:129], v[134:137], v[160:163], v[126:129]
	v_mfma_f32_16x16x32_bf16 v[122:125], v[142:145], v[160:163], v[122:125]
	v_mfma_f32_16x16x32_bf16 v[118:121], v[134:137], v[174:177], v[118:121]
	v_mfma_f32_16x16x32_bf16 v[114:117], v[142:145], v[174:177], v[114:117]
	v_mfma_f32_16x16x32_bf16 v[98:101], v[134:137], v[182:185], v[98:101]
	v_mfma_f32_16x16x32_bf16 v[90:93], v[142:145], v[182:185], v[90:93]
	v_mfma_f32_16x16x32_bf16 v[82:85], v[134:137], v[190:193], v[82:85]
	v_mfma_f32_16x16x32_bf16 v[74:77], v[142:145], v[190:193], v[74:77]
	v_mfma_f32_16x16x32_bf16 v[126:129], v[138:141], v[164:167], v[126:129]
	v_mfma_f32_16x16x32_bf16 v[122:125], v[146:149], v[164:167], v[122:125]
	v_mfma_f32_16x16x32_bf16 v[118:121], v[138:141], v[178:181], v[118:121]
	v_mfma_f32_16x16x32_bf16 v[114:117], v[146:149], v[178:181], v[114:117]
	v_mfma_f32_16x16x32_bf16 v[98:101], v[138:141], v[186:189], v[98:101]
	v_mfma_f32_16x16x32_bf16 v[90:93], v[146:149], v[186:189], v[90:93]
	v_mfma_f32_16x16x32_bf16 v[82:85], v[138:141], v[210:213], v[82:85]
	v_mfma_f32_16x16x32_bf16 v[74:77], v[146:149], v[210:213], v[74:77]
	s_setprio 0
	s_barrier
	s_add_i32 s8, 0, 0x14000
	v_add_u32_e32 v168, s8, v172
	s_add_i32 s9, s55, s3
	ds_read_b128 v[214:217], v168
	ds_read_b128 v[218:221], v168 offset:1024
	ds_read_b128 v[222:225], v168 offset:2048
	ds_read_b128 v[226:229], v168 offset:3072
	s_mov_b32 m0, s9
	s_nop 0
	global_load_lds_dwordx4 v0, s[18:19]
	s_add_i32 m0, s9, 0x2000
	s_nop 0
	global_load_lds_dwordx4 v150, s[18:19]
	s_barrier
	s_waitcnt lgkmcnt(0)
	s_setprio 1
	s_waitcnt lgkmcnt(0)
	v_mfma_f32_16x16x32_bf16 v[110:113], v[214:217], v[160:163], v[110:113]
	v_mfma_f32_16x16x32_bf16 v[106:109], v[222:225], v[160:163], v[106:109]
	v_mfma_f32_16x16x32_bf16 v[102:105], v[214:217], v[174:177], v[102:105]
	v_mfma_f32_16x16x32_bf16 v[94:97], v[222:225], v[174:177], v[94:97]
	v_mfma_f32_16x16x32_bf16 v[86:89], v[214:217], v[182:185], v[86:89]
	v_mfma_f32_16x16x32_bf16 v[78:81], v[222:225], v[182:185], v[78:81]
	v_mfma_f32_16x16x32_bf16 v[70:73], v[214:217], v[190:193], v[70:73]
	v_mfma_f32_16x16x32_bf16 v[66:69], v[222:225], v[190:193], v[66:69]
	v_mfma_f32_16x16x32_bf16 v[110:113], v[218:221], v[164:167], v[110:113]
	v_mfma_f32_16x16x32_bf16 v[106:109], v[226:229], v[164:167], v[106:109]
	v_mfma_f32_16x16x32_bf16 v[102:105], v[218:221], v[178:181], v[102:105]
	v_mfma_f32_16x16x32_bf16 v[94:97], v[226:229], v[178:181], v[94:97]
	v_mfma_f32_16x16x32_bf16 v[86:89], v[218:221], v[186:189], v[86:89]
	v_mfma_f32_16x16x32_bf16 v[78:81], v[226:229], v[186:189], v[78:81]
	v_mfma_f32_16x16x32_bf16 v[70:73], v[218:221], v[210:213], v[70:73]
	v_mfma_f32_16x16x32_bf16 v[66:69], v[226:229], v[210:213], v[66:69]
	s_setprio 0
	s_mov_b32 m0, s4
	s_barrier
	ds_read_b128 v[160:163], v173 offset:16384
	ds_read_b128 v[164:167], v173 offset:17408
	ds_read_b128 v[174:177], v173 offset:18432
	ds_read_b128 v[178:181], v173 offset:19456
	ds_read_b128 v[182:185], v173 offset:20480
	ds_read_b128 v[186:189], v173 offset:21504
	ds_read_b128 v[190:193], v173 offset:22528
	ds_read_b128 v[210:213], v173 offset:23552
	global_load_lds_dwordx4 v154, s[40:41]
	s_mov_b32 m0, s28
	s_nop 0
	global_load_lds_dwordx4 v152, s[40:41]
	s_barrier
	s_waitcnt lgkmcnt(0)
	s_setprio 1
	s_waitcnt lgkmcnt(0)
	v_mfma_f32_16x16x32_bf16 v[62:65], v[134:137], v[160:163], v[62:65]
	v_mfma_f32_16x16x32_bf16 v[58:61], v[142:145], v[160:163], v[58:61]
	v_mfma_f32_16x16x32_bf16 v[50:53], v[134:137], v[174:177], v[50:53]
	v_mfma_f32_16x16x32_bf16 v[42:45], v[142:145], v[174:177], v[42:45]
	v_mfma_f32_16x16x32_bf16 v[34:37], v[134:137], v[182:185], v[34:37]
	v_mfma_f32_16x16x32_bf16 v[26:29], v[142:145], v[182:185], v[26:29]
	v_mfma_f32_16x16x32_bf16 v[18:21], v[134:137], v[190:193], v[18:21]
	v_mfma_f32_16x16x32_bf16 v[10:13], v[142:145], v[190:193], v[10:13]
	v_mfma_f32_16x16x32_bf16 v[62:65], v[138:141], v[164:167], v[62:65]
	v_mfma_f32_16x16x32_bf16 v[58:61], v[146:149], v[164:167], v[58:61]
	v_mfma_f32_16x16x32_bf16 v[50:53], v[138:141], v[178:181], v[50:53]
	v_mfma_f32_16x16x32_bf16 v[42:45], v[146:149], v[178:181], v[42:45]
	v_mfma_f32_16x16x32_bf16 v[34:37], v[138:141], v[186:189], v[34:37]
	v_mfma_f32_16x16x32_bf16 v[26:29], v[146:149], v[186:189], v[26:29]
	v_mfma_f32_16x16x32_bf16 v[18:21], v[138:141], v[210:213], v[18:21]
	v_mfma_f32_16x16x32_bf16 v[10:13], v[146:149], v[210:213], v[10:13]
	s_setprio 0
	s_barrier
; #define PG8_STAGE(bufoff, gbase, voff) do { _Pragma("unroll") for (int _i = 0; _i < 2; ++_i) \
;     __builtin_amdgcn_global_load_lds((const unsigned*)((const char*)(gbase) + (voff)[_i]), (LAS unsigned*)(lds + (bufoff) + ldsw + _i * 8192), 16, 0, 0); } while (0)
; #define PG8_LDA(dst, b, h) do { _Pragma("unroll") for (int m = 0; m < 4; ++m) _Pragma("unroll") for (int k = 0; k < 2; ++k) dst[m][k] = *(const LAS bf16x8*)(lds + PG8_SA(b, h) + aoff + m * 2048 + k * 1024); } while (0)
; #define PG8_LDB(dst, b, h) do { _Pragma("unroll") for (int n = 0; n < 2; ++n) _Pragma("unroll") for (int k = 0; k < 2; ++k) dst[n][k] = *(const LAS bf16x8*)(lds + PG8_SB(b, h) + boff + n * 2048 + k * 1024); } while (0)
; #define PG8_MMA(ai, bj, At, Bt) do { __builtin_amdgcn_s_setprio(1); _Pragma("unroll") for (int m = 0; m < 4; ++m) _Pragma("unroll") for (int n = 0; n < 2; ++n) _Pragma("unroll") for (int k = 0; k < 2; ++k) \
;     acc[ai][bj][m][n] = __builtin_amdgcn_mfma_f32_16x16x32_bf16(Bt[n][k], At[m][k], acc[ai][bj][m][n], 0, 0, 0); __builtin_amdgcn_s_setprio(0); } while (0)
; #define PG8_WAIT_V(n) asm volatile("s_waitcnt vmcnt(" #n ")" ::: "memory")
; #define PG8_WAIT_L(n) asm volatile("s_waitcnt lgkmcnt(" #n ")" ::: "memory")
; #define PG8_BAR __builtin_amdgcn_s_barrier()
; #define PG8_SCHED __builtin_amdgcn_sched_barrier(0)
; template <class Epi, bool SPLITA = false>
; __device__ __forceinline__ void gemm_phase(const int tid, LAS unsigned char* lds, const Gemm g, const Order& S, const Epi& E) {
;     ...
;       PG8_STAGE(PG8_SB(0, 1), b2 + hstepB, voffB);
;       PG8_WAIT_V(6); PG8_BAR; PG8_MMA(1, 1, At, B1); PG8_BAR;
;       PG8_LDB(B0, 1, 0); PG8_SCHED; PG8_LDA(At, 1, 0); PG8_STAGE(PG8_SA(0, 1), a2 + hstepA, voffA);
;       PG8_WAIT_L(8); PG8_BAR; PG8_WAIT_L(0); PG8_MMA(0, 0, At, B0); PG8_BAR; PG8_SCHED;
;       PG8_LDB(B1, 1, 1); PG8_STAGE(PG8_SB(1, 0), b3, voffB);
;       PG8_BAR; PG8_WAIT_L(0); PG8_MMA(0, 1, At, B1); PG8_BAR;
;       PG8_LDA(At, 1, 1); PG8_STAGE(PG8_SA(1, 0), a3, voffA);
	s_add_u32 s20, s18, 0x160000
	s_addc_u32 s21, s19, 0
	s_add_i32 s8, s8, s3
	s_mov_b32 m0, s8
	s_nop 0
	global_load_lds_dwordx4 v0, s[20:21]
	s_add_i32 m0, s8, 0x2000
	s_nop 0
	global_load_lds_dwordx4 v150, s[20:21]
	s_waitcnt vmcnt(6)
	s_barrier
	s_setprio 1
	v_mfma_f32_16x16x32_bf16 v[54:57], v[214:217], v[160:163], v[54:57]
	v_mfma_f32_16x16x32_bf16 v[46:49], v[222:225], v[160:163], v[46:49]
	v_mfma_f32_16x16x32_bf16 v[38:41], v[214:217], v[174:177], v[38:41]
	v_mfma_f32_16x16x32_bf16 v[30:33], v[222:225], v[174:177], v[30:33]
	v_mfma_f32_16x16x32_bf16 v[22:25], v[214:217], v[182:185], v[22:25]
	v_mfma_f32_16x16x32_bf16 v[14:17], v[222:225], v[182:185], v[14:17]
	v_mfma_f32_16x16x32_bf16 v[6:9], v[214:217], v[190:193], v[6:9]
	v_mfma_f32_16x16x32_bf16 v[2:5], v[222:225], v[190:193], v[2:5]
	v_mfma_f32_16x16x32_bf16 v[54:57], v[218:221], v[164:167], v[54:57]
	v_mfma_f32_16x16x32_bf16 v[46:49], v[226:229], v[164:167], v[46:49]
	v_mfma_f32_16x16x32_bf16 v[38:41], v[218:221], v[178:181], v[38:41]
	v_mfma_f32_16x16x32_bf16 v[30:33], v[226:229], v[178:181], v[30:33]
	v_mfma_f32_16x16x32_bf16 v[22:25], v[218:221], v[186:189], v[22:25]
	v_mfma_f32_16x16x32_bf16 v[14:17], v[226:229], v[186:189], v[14:17]
	v_mfma_f32_16x16x32_bf16 v[6:9], v[218:221], v[210:213], v[6:9]
	v_mfma_f32_16x16x32_bf16 v[2:5], v[226:229], v[210:213], v[2:5]
	s_setprio 0
	s_add_i32 s8, 0, 0x18000
	v_add_u32_e32 v146, s8, v172
	s_barrier
	ds_read_b128 v[134:137], v146
	ds_read_b128 v[138:141], v146 offset:1024
	ds_read_b128 v[142:145], v146 offset:2048
	ds_read_b128 v[146:149], v146 offset:3072
	s_add_u32 s20, s40, 0x160000
	s_addc_u32 s21, s41, 0
	s_mov_b32 m0, s30
	ds_read_b128 v[160:163], v173 offset:32768
	ds_read_b128 v[164:167], v173 offset:33792
	ds_read_b128 v[174:177], v173 offset:34816
	ds_read_b128 v[178:181], v173 offset:35840
	ds_read_b128 v[182:185], v173 offset:36864
	ds_read_b128 v[186:189], v173 offset:37888
	ds_read_b128 v[190:193], v173 offset:38912
	ds_read_b128 v[210:213], v173 offset:39936
	global_load_lds_dwordx4 v154, s[20:21]
	s_mov_b32 m0, s31
	s_nop 0
	global_load_lds_dwordx4 v152, s[20:21]
	s_waitcnt lgkmcnt(8)
	s_barrier
	s_waitcnt lgkmcnt(0)
	s_setprio 1
	s_waitcnt lgkmcnt(0)
	v_mfma_f32_16x16x32_bf16 v[126:129], v[134:137], v[160:163], v[126:129]
	v_mfma_f32_16x16x32_bf16 v[122:125], v[142:145], v[160:163], v[122:125]
	v_mfma_f32_16x16x32_bf16 v[118:121], v[134:137], v[174:177], v[118:121]
	v_mfma_f32_16x16x32_bf16 v[114:117], v[142:145], v[174:177], v[114:117]
	v_mfma_f32_16x16x32_bf16 v[98:101], v[134:137], v[182:185], v[98:101]
	v_mfma_f32_16x16x32_bf16 v[90:93], v[142:145], v[182:185], v[90:93]
	v_mfma_f32_16x16x32_bf16 v[82:85], v[134:137], v[190:193], v[82:85]
	v_mfma_f32_16x16x32_bf16 v[74:77], v[142:145], v[190:193], v[74:77]
	v_mfma_f32_16x16x32_bf16 v[126:129], v[138:141], v[164:167], v[126:129]
	v_mfma_f32_16x16x32_bf16 v[122:125], v[146:149], v[164:167], v[122:125]
	v_mfma_f32_16x16x32_bf16 v[118:121], v[138:141], v[178:181], v[118:121]
	v_mfma_f32_16x16x32_bf16 v[114:117], v[146:149], v[178:181], v[114:117]
	v_mfma_f32_16x16x32_bf16 v[98:101], v[138:141], v[186:189], v[98:101]
	v_mfma_f32_16x16x32_bf16 v[90:93], v[146:149], v[186:189], v[90:93]
	v_mfma_f32_16x16x32_bf16 v[82:85], v[138:141], v[210:213], v[82:85]
	v_mfma_f32_16x16x32_bf16 v[74:77], v[146:149], v[210:213], v[74:77]
	s_setprio 0
	s_barrier
	s_add_i32 s9, 0, 0x1c000
	s_add_i32 s8, s8, s3
	v_add_u32_e32 v195, s9, v172
	s_add_i32 m0, s8, 0xffffff80
	ds_read_b128 v[214:217], v195
	ds_read_b128 v[218:221], v195 offset:1024
	ds_read_b128 v[222:225], v195 offset:2048
	ds_read_b128 v[226:229], v195 offset:3072
	global_load_lds_dwordx4 v0, s[18:19] offset:128
	s_add_i32 m0, s8, 0x1f80
	s_nop 0
	global_load_lds_dwordx4 v150, s[18:19] offset:128
	s_barrier
	s_waitcnt lgkmcnt(0)
	s_setprio 1
	s_waitcnt lgkmcnt(0)
	v_mfma_f32_16x16x32_bf16 v[110:113], v[214:217], v[160:163], v[110:113]
	v_mfma_f32_16x16x32_bf16 v[106:109], v[222:225], v[160:163], v[106:109]
	v_mfma_f32_16x16x32_bf16 v[102:105], v[214:217], v[174:177], v[102:105]
	v_mfma_f32_16x16x32_bf16 v[94:97], v[222:225], v[174:177], v[94:97]
	v_mfma_f32_16x16x32_bf16 v[86:89], v[214:217], v[182:185], v[86:89]
	v_mfma_f32_16x16x32_bf16 v[78:81], v[222:225], v[182:185], v[78:81]
	v_mfma_f32_16x16x32_bf16 v[70:73], v[214:217], v[190:193], v[70:73]
	v_mfma_f32_16x16x32_bf16 v[66:69], v[222:225], v[190:193], v[66:69]
	v_mfma_f32_16x16x32_bf16 v[110:113], v[218:221], v[164:167], v[110:113]
	v_mfma_f32_16x16x32_bf16 v[106:109], v[226:229], v[164:167], v[106:109]
	v_mfma_f32_16x16x32_bf16 v[102:105], v[218:221], v[178:181], v[102:105]
	v_mfma_f32_16x16x32_bf16 v[94:97], v[226:229], v[178:181], v[94:97]
	v_mfma_f32_16x16x32_bf16 v[86:89], v[218:221], v[186:189], v[86:89]
	v_mfma_f32_16x16x32_bf16 v[78:81], v[226:229], v[186:189], v[78:81]
	v_mfma_f32_16x16x32_bf16 v[70:73], v[218:221], v[210:213], v[70:73]
	v_mfma_f32_16x16x32_bf16 v[66:69], v[226:229], v[210:213], v[66:69]
	s_setprio 0
	s_mov_b32 m0, s44
	s_barrier
	ds_read_b128 v[160:163], v173 offset:49152
	ds_read_b128 v[164:167], v173 offset:50176
	ds_read_b128 v[174:177], v173 offset:51200
	ds_read_b128 v[178:181], v173 offset:52224
	ds_read_b128 v[182:185], v173 offset:53248
	ds_read_b128 v[186:189], v173 offset:54272
	ds_read_b128 v[190:193], v173 offset:55296
	ds_read_b128 v[210:213], v173 offset:56320
	global_load_lds_dwordx4 v154, s[22:23]
	s_mov_b32 m0, s45
	s_nop 0
	global_load_lds_dwordx4 v152, s[22:23]
	s_barrier
; #define PG8_STAGE(bufoff, gbase, voff) do { _Pragma("unroll") for (int _i = 0; _i < 2; ++_i) \
;     __builtin_amdgcn_global_load_lds((const unsigned*)((const char*)(gbase) + (voff)[_i]), (LAS unsigned*)(lds + (bufoff) + ldsw + _i * 8192), 16, 0, 0); } while (0)
; #define PG8_LDA(dst, b, h) do { _Pragma("unroll") for (int m = 0; m < 4; ++m) _Pragma("unroll") for (int k = 0; k < 2; ++k) dst[m][k] = *(const LAS bf16x8*)(lds + PG8_SA(b, h) + aoff + m * 2048 + k * 1024); } while (0)
; #define PG8_MMA(ai, bj, At, Bt) do { __builtin_amdgcn_s_setprio(1); _Pragma("unroll") for (int m = 0; m < 4; ++m) _Pragma("unroll") for (int n = 0; n < 2; ++n) _Pragma("unroll") for (int k = 0; k < 2; ++k) \
;     acc[ai][bj][m][n] = __builtin_amdgcn_mfma_f32_16x16x32_bf16(Bt[n][k], At[m][k], acc[ai][bj][m][n], 0, 0, 0); __builtin_amdgcn_s_setprio(0); } while (0)
; #define PG8_WAIT_V(n) asm volatile("s_waitcnt vmcnt(" #n ")" ::: "memory")
; #define PG8_WAIT_L(n) asm volatile("s_waitcnt lgkmcnt(" #n ")" ::: "memory")
; #define PG8_BAR __builtin_amdgcn_s_barrier()
; #define PG8_SCHED __builtin_amdgcn_sched_barrier(0)
; template <class Epi, bool SPLITA = false>
; __device__ __forceinline__ void gemm_phase(const int tid, LAS unsigned char* lds, const Gemm g, const Order& S, const Epi& E) {
;     ...
;       PG8_BAR; PG8_WAIT_L(0); PG8_MMA(0, 1, At, B1); PG8_BAR;
;       PG8_LDA(At, 1, 1); PG8_STAGE(PG8_SA(1, 0), a3, voffA);
;       PG8_BAR; PG8_WAIT_L(0); PG8_MMA(1, 0, At, B0); PG8_BAR; PG8_SCHED;
;       PG8_STAGE(PG8_SB(1, 1), b3 + hstepB, voffB);
;       PG8_WAIT_V(6); PG8_BAR; PG8_MMA(1, 1, At, B1); PG8_BAR;
;     }
;   __device__ __forceinline__ void operator()(const Acc& acc, const Unit& u, int wr, int wc, int fr_, int fq_) const {
;     int fr = fr_, fq = fq_; asm volatile("" : "+v"(fr), "+v"(fq));
;     const int lane = fq * 16 + fr;
;     const int row0 = u.pm * BM + wr * 64 + fr, col0 = u.pn * BM + wc * 32 + 8 * fq;
; #pragma unroll
;     for (int ai = 0; ai < 2; ++ai) {
;       u32x4 hv[4][2];
; #pragma unroll
;       for (int m = 0; m < 4; ++m)
; #pragma unroll
;         for (int bj = 0; bj < 2; ++bj) hv[m][bj] = *(const u32x4*)(rin + (size_t)(row0 + ai * HALF + m * 16) * DM + col0 + bj * HALF);
	s_waitcnt lgkmcnt(0)
	s_setprio 1
	s_waitcnt lgkmcnt(0)
	v_mfma_f32_16x16x32_bf16 v[62:65], v[134:137], v[160:163], v[62:65]
	v_mfma_f32_16x16x32_bf16 v[58:61], v[142:145], v[160:163], v[58:61]
	v_mfma_f32_16x16x32_bf16 v[50:53], v[134:137], v[174:177], v[50:53]
	v_mfma_f32_16x16x32_bf16 v[42:45], v[142:145], v[174:177], v[42:45]
	v_mfma_f32_16x16x32_bf16 v[34:37], v[134:137], v[182:185], v[34:37]
	v_mfma_f32_16x16x32_bf16 v[26:29], v[142:145], v[182:185], v[26:29]
	v_mfma_f32_16x16x32_bf16 v[18:21], v[134:137], v[190:193], v[18:21]
	v_mfma_f32_16x16x32_bf16 v[10:13], v[142:145], v[190:193], v[10:13]
	v_mfma_f32_16x16x32_bf16 v[62:65], v[138:141], v[164:167], v[62:65]
	v_mfma_f32_16x16x32_bf16 v[58:61], v[146:149], v[164:167], v[58:61]
	v_mfma_f32_16x16x32_bf16 v[50:53], v[138:141], v[178:181], v[50:53]
	v_mfma_f32_16x16x32_bf16 v[42:45], v[146:149], v[178:181], v[42:45]
	v_mfma_f32_16x16x32_bf16 v[34:37], v[138:141], v[186:189], v[34:37]
	v_mfma_f32_16x16x32_bf16 v[26:29], v[146:149], v[186:189], v[26:29]
	v_mfma_f32_16x16x32_bf16 v[18:21], v[138:141], v[210:213], v[18:21]
	v_mfma_f32_16x16x32_bf16 v[10:13], v[146:149], v[210:213], v[10:13]
	s_setprio 0
	s_barrier
	s_add_u32 s18, s18, 0x160080
	s_addc_u32 s19, s19, 0
	s_add_i32 s8, s9, s3
	s_mov_b32 m0, s8
	s_nop 0
	global_load_lds_dwordx4 v0, s[18:19]
	s_add_i32 m0, s8, 0x2000
	s_nop 0
	global_load_lds_dwordx4 v150, s[18:19]
	s_waitcnt vmcnt(6)
	s_barrier
	s_setprio 1
	v_mfma_f32_16x16x32_bf16 v[54:57], v[214:217], v[160:163], v[54:57]
	v_mfma_f32_16x16x32_bf16 v[46:49], v[222:225], v[160:163], v[46:49]
	v_mfma_f32_16x16x32_bf16 v[38:41], v[214:217], v[174:177], v[38:41]
	v_mfma_f32_16x16x32_bf16 v[30:33], v[222:225], v[174:177], v[30:33]
	v_mfma_f32_16x16x32_bf16 v[22:25], v[214:217], v[182:185], v[22:25]
	v_mfma_f32_16x16x32_bf16 v[14:17], v[222:225], v[182:185], v[14:17]
	v_mfma_f32_16x16x32_bf16 v[6:9], v[214:217], v[190:193], v[6:9]
	v_mfma_f32_16x16x32_bf16 v[2:5], v[222:225], v[190:193], v[2:5]
	v_mfma_f32_16x16x32_bf16 v[54:57], v[218:221], v[164:167], v[54:57]
	v_mfma_f32_16x16x32_bf16 v[46:49], v[226:229], v[164:167], v[46:49]
	v_mfma_f32_16x16x32_bf16 v[38:41], v[218:221], v[178:181], v[38:41]
	v_mfma_f32_16x16x32_bf16 v[30:33], v[226:229], v[178:181], v[30:33]
	v_mfma_f32_16x16x32_bf16 v[22:25], v[218:221], v[186:189], v[22:25]
	v_mfma_f32_16x16x32_bf16 v[14:17], v[226:229], v[186:189], v[14:17]
	v_mfma_f32_16x16x32_bf16 v[6:9], v[218:221], v[210:213], v[6:9]
	v_mfma_f32_16x16x32_bf16 v[2:5], v[226:229], v[210:213], v[2:5]
	s_setprio 0
	s_add_i32 s29, s29, 2
	s_add_u32 s16, s16, 0x100
	s_addc_u32 s17, s17, 0
	s_cmpk_gt_u32 s29, 0x55
	s_barrier
	s_cbranch_scc0 .LBB0_57
	s_lshl_b32 s6, s51, 8
	v_mov_b32_e32 v130, v171
	v_mov_b32_e32 v131, v170
	s_add_i32 s6, s6, s42
	v_readlane_b32 s40, v255, 9
	v_add_u32_e32 v160, s6, v130
	s_lshl_b32 s6, s52, 8
	s_or_b32 s6, s6, s43
	v_lshl_add_u32 v186, v131, 3, s6
	v_readlane_b32 s6, v255, 5
	v_ashrrev_i32_e32 v187, 31, v186
	v_readlane_b32 s7, v255, 6
	v_ashrrev_i32_e32 v161, 31, v160
	v_lshlrev_b64 v[130:131], 12, v[160:161]
	v_lshl_add_u64 v[162:163], v[186:187], 1, s[6:7]
	v_lshl_add_u64 v[130:131], v[162:163], 0, v[130:131]
	global_load_dwordx4 v[174:177], v[130:131], off
	global_load_dwordx4 v[178:181], v[130:131], off offset:256
	v_add_u32_e32 v168, 16, v160
	v_ashrrev_i32_e32 v169, 31, v168
	v_lshlrev_b64 v[130:131], 12, v[168:169]
	v_lshl_add_u64 v[130:131], v[162:163], 0, v[130:131]
	global_load_dwordx4 v[182:185], v[130:131], off
	global_load_dwordx4 v[146:149], v[130:131], off offset:256
	v_add_u32_e32 v166, 32, v160
	v_ashrrev_i32_e32 v167, 31, v166
	v_lshlrev_b64 v[130:131], 12, v[166:167]
	v_lshl_add_u64 v[130:131], v[162:163], 0, v[130:131]
	global_load_dwordx4 v[142:145], v[130:131], off
	global_load_dwordx4 v[138:141], v[130:131], off offset:256
	v_add_u32_e32 v164, 48, v160
	v_ashrrev_i32_e32 v165, 31, v164
	v_lshlrev_b64 v[130:131], 12, v[164:165]
	v_lshl_add_u64 v[130:131], v[162:163], 0, v[130:131]
	global_load_dwordx4 v[134:137], v[130:131], off
	s_nop 0
	global_load_dwordx4 v[130:133], v[130:131], off offset:256
	s_and_b64 vcc, exec, s[38:39]
	s_mov_b32 s52, s48
	s_mov_b32 s51, s49
	s_mov_b64 s[16:17], s[10:11]
	s_mov_b64 s[12:13], s[0:1]
	s_mov_b64 s[20:21], s[34:35]
	v_readlane_b32 s41, v255, 10
	s_waitcnt vmcnt(0)
; __device__ __forceinline__ float bflo(unsigned w) { return __uint_as_float(w << 16); }
; __device__ __forceinline__ float bfhi(unsigned w) { return __uint_as_float(w & 0xffff0000u); }
;   __device__ __forceinline__ void operator()(const Acc& acc, const Unit& u, int wr, int wc, int fr_, int fq_) const {
;     ...
;         for (int bj = 0; bj < 2; ++bj) hv[m][bj] = *(const u32x4*)(rin + (size_t)(row0 + ai * HALF + m * 16) * DM + col0 + bj * HALF);
; #pragma unroll
;       for (int m = 0; m < 4; ++m) { const size_t ro = (size_t)(row0 + ai * HALF + m * 16) * DM + col0; float ss = 0.f;
; #pragma unroll
;         for (int bj = 0; bj < 2; ++bj) { const u32x4 h = hv[m][bj];
;           f32x4 v0 = acc[ai][bj][m][0], v1 = acc[ai][bj][m][1];
;           v0[0] += bflo(h.x); v0[1] += bfhi(h.x); v0[2] += bflo(h.y); v0[3] += bfhi(h.y);
;           v1[0] += bflo(h.z); v1[1] += bfhi(h.z); v1[2] += bflo(h.w); v1[3] += bfhi(h.w);
;           if (FINAL) { *(f32x4*)(outf + ro + bj * HALF) = v0; *(f32x4*)(outf + ro + bj * HALF + 4) = v1; }
	v_lshlrev_b32_e32 v188, 16, v174
	v_and_b32_e32 v189, 0xffff0000, v174
	v_lshlrev_b32_e32 v174, 16, v175
	v_and_b32_e32 v175, 0xffff0000, v175
	v_pk_add_f32 v[128:129], v[128:129], v[174:175]
	v_lshlrev_b32_e32 v174, 16, v176
	v_and_b32_e32 v175, 0xffff0000, v176
	v_pk_add_f32 v[174:175], v[122:123], v[174:175]
	v_lshlrev_b32_e32 v122, 16, v177
	v_and_b32_e32 v123, 0xffff0000, v177
	v_pk_add_f32 v[176:177], v[124:125], v[122:123]
	v_lshlrev_b64 v[122:123], 13, v[160:161]
	v_lshl_add_u64 v[124:125], s[86:87], 0, v[122:123]
	v_lshlrev_b64 v[122:123], 2, v[186:187]
	v_pk_add_f32 v[126:127], v[126:127], v[188:189]
	v_lshl_add_u64 v[124:125], v[124:125], 0, v[122:123]
	global_store_dwordx4 v[124:125], v[126:129], off
	global_store_dwordx4 v[124:125], v[174:177], off offset:16
	s_nop 0
	v_lshlrev_b32_e32 v126, 16, v178
	v_and_b32_e32 v127, 0xffff0000, v178
	v_pk_add_f32 v[110:111], v[110:111], v[126:127]
	v_lshlrev_b32_e32 v126, 16, v179
	v_and_b32_e32 v127, 0xffff0000, v179
	v_pk_add_f32 v[112:113], v[112:113], v[126:127]
	v_lshlrev_b32_e32 v126, 16, v180
	v_and_b32_e32 v127, 0xffff0000, v180
	v_pk_add_f32 v[106:107], v[106:107], v[126:127]
	v_lshlrev_b32_e32 v126, 16, v181
	v_and_b32_e32 v127, 0xffff0000, v181
	v_pk_add_f32 v[108:109], v[108:109], v[126:127]
	global_store_dwordx4 v[124:125], v[110:113], off offset:512
	global_store_dwordx4 v[124:125], v[106:109], off offset:528
	s_nop 0
	v_lshlrev_b32_e32 v110, 16, v184
	v_and_b32_e32 v111, 0xffff0000, v184
	v_pk_add_f32 v[110:111], v[114:115], v[110:111]
	v_lshlrev_b64 v[114:115], 13, v[168:169]
	v_lshlrev_b32_e32 v106, 16, v182
	v_and_b32_e32 v107, 0xffff0000, v182
	v_lshlrev_b32_e32 v108, 16, v183
	v_and_b32_e32 v109, 0xffff0000, v183
	v_lshl_add_u64 v[114:115], s[86:87], 0, v[114:115]
	v_pk_add_f32 v[106:107], v[118:119], v[106:107]
	v_pk_add_f32 v[108:109], v[120:121], v[108:109]
	v_lshlrev_b32_e32 v112, 16, v185
	v_and_b32_e32 v113, 0xffff0000, v185
	v_lshl_add_u64 v[114:115], v[114:115], 0, v[122:123]
	v_pk_add_f32 v[112:113], v[116:117], v[112:113]
	global_store_dwordx4 v[114:115], v[106:109], off
	global_store_dwordx4 v[114:115], v[110:113], off offset:16
	s_nop 0
	v_lshlrev_b32_e32 v106, 16, v146
	v_and_b32_e32 v107, 0xffff0000, v146
	v_pk_add_f32 v[102:103], v[102:103], v[106:107]
	v_lshlrev_b32_e32 v106, 16, v147
	v_and_b32_e32 v107, 0xffff0000, v147
	v_pk_add_f32 v[104:105], v[104:105], v[106:107]
	v_lshlrev_b32_e32 v106, 16, v148
	v_and_b32_e32 v107, 0xffff0000, v148
	v_pk_add_f32 v[94:95], v[94:95], v[106:107]
	v_lshlrev_b32_e32 v106, 16, v149
	v_and_b32_e32 v107, 0xffff0000, v149
	v_pk_add_f32 v[96:97], v[96:97], v[106:107]
	global_store_dwordx4 v[114:115], v[102:105], off offset:512
	global_store_dwordx4 v[114:115], v[94:97], off offset:528
	s_nop 0
	v_add_u32_e32 v102, 0xa0, v160
	v_lshlrev_b32_e32 v94, 16, v142
	v_and_b32_e32 v95, 0xffff0000, v142
	v_pk_add_f32 v[94:95], v[98:99], v[94:95]
	v_lshlrev_b32_e32 v98, 16, v144
	v_and_b32_e32 v99, 0xffff0000, v144
	v_pk_add_f32 v[90:91], v[90:91], v[98:99]
	v_lshlrev_b32_e32 v98, 16, v145
	v_and_b32_e32 v99, 0xffff0000, v145
	v_pk_add_f32 v[92:93], v[92:93], v[98:99]
	v_lshlrev_b64 v[98:99], 13, v[166:167]
	v_lshlrev_b32_e32 v96, 16, v143
	v_and_b32_e32 v97, 0xffff0000, v143
	v_lshl_add_u64 v[98:99], s[86:87], 0, v[98:99]
	v_pk_add_f32 v[96:97], v[100:101], v[96:97]
	v_lshl_add_u64 v[98:99], v[98:99], 0, v[122:123]
	global_store_dwordx4 v[98:99], v[94:97], off
	global_store_dwordx4 v[98:99], v[90:93], off offset:16
	v_add_u32_e32 v100, 0x90, v160
	v_ashrrev_i32_e32 v101, 31, v100
	v_lshlrev_b32_e32 v90, 16, v138
	v_and_b32_e32 v91, 0xffff0000, v138
	v_pk_add_f32 v[86:87], v[86:87], v[90:91]
	v_lshlrev_b32_e32 v90, 16, v139
	v_and_b32_e32 v91, 0xffff0000, v139
	v_pk_add_f32 v[88:89], v[88:89], v[90:91]
	v_lshlrev_b32_e32 v90, 16, v140
	v_and_b32_e32 v91, 0xffff0000, v140
	v_pk_add_f32 v[78:79], v[78:79], v[90:91]
	v_lshlrev_b32_e32 v90, 16, v141
	v_and_b32_e32 v91, 0xffff0000, v141
	v_pk_add_f32 v[80:81], v[80:81], v[90:91]
	global_store_dwordx4 v[98:99], v[86:89], off offset:512
	global_store_dwordx4 v[98:99], v[78:81], off offset:528
	v_add_u32_e32 v98, 0x80, v160
	v_ashrrev_i32_e32 v99, 31, v98
	v_lshlrev_b32_e32 v78, 16, v134
	v_and_b32_e32 v79, 0xffff0000, v134
	v_pk_add_f32 v[78:79], v[82:83], v[78:79]
	v_lshlrev_b32_e32 v82, 16, v136
	v_and_b32_e32 v83, 0xffff0000, v136
	v_pk_add_f32 v[74:75], v[74:75], v[82:83]
	v_lshlrev_b32_e32 v82, 16, v137
	v_and_b32_e32 v83, 0xffff0000, v137
	v_pk_add_f32 v[76:77], v[76:77], v[82:83]
	v_lshlrev_b64 v[82:83], 13, v[164:165]
	v_lshlrev_b32_e32 v80, 16, v135
	v_and_b32_e32 v81, 0xffff0000, v135
	v_lshl_add_u64 v[82:83], s[86:87], 0, v[82:83]
	v_pk_add_f32 v[80:81], v[84:85], v[80:81]
	v_lshl_add_u64 v[82:83], v[82:83], 0, v[122:123]
	global_store_dwordx4 v[82:83], v[78:81], off
	global_store_dwordx4 v[82:83], v[74:77], off offset:16
	v_ashrrev_i32_e32 v103, 31, v102
	v_add_u32_e32 v104, 0xb0, v160
	v_lshlrev_b32_e32 v74, 16, v130
	v_and_b32_e32 v75, 0xffff0000, v130
	v_pk_add_f32 v[70:71], v[70:71], v[74:75]
	v_lshlrev_b32_e32 v74, 16, v131
	v_and_b32_e32 v75, 0xffff0000, v131
	v_pk_add_f32 v[72:73], v[72:73], v[74:75]
	v_lshlrev_b32_e32 v74, 16, v132
	v_and_b32_e32 v75, 0xffff0000, v132
	v_pk_add_f32 v[66:67], v[66:67], v[74:75]
	v_lshlrev_b32_e32 v74, 16, v133
	v_and_b32_e32 v75, 0xffff0000, v133
	v_pk_add_f32 v[68:69], v[68:69], v[74:75]
	global_store_dwordx4 v[82:83], v[70:73], off offset:512
	global_store_dwordx4 v[82:83], v[66:69], off offset:528
	v_ashrrev_i32_e32 v105, 31, v104
	s_nop 0
	v_lshlrev_b64 v[66:67], 12, v[98:99]
	v_lshl_add_u64 v[66:67], v[162:163], 0, v[66:67]
	global_load_dwordx4 v[70:73], v[66:67], off
	global_load_dwordx4 v[74:77], v[66:67], off offset:256
	v_lshlrev_b64 v[66:67], 12, v[100:101]
	v_lshl_add_u64 v[66:67], v[162:163], 0, v[66:67]
	global_load_dwordx4 v[78:81], v[66:67], off
	global_load_dwordx4 v[82:85], v[66:67], off offset:256
	v_lshlrev_b64 v[66:67], 12, v[102:103]
	v_lshl_add_u64 v[66:67], v[162:163], 0, v[66:67]
	global_load_dwordx4 v[86:89], v[66:67], off
	global_load_dwordx4 v[90:93], v[66:67], off offset:256
	v_lshlrev_b64 v[66:67], 12, v[104:105]
	v_lshl_add_u64 v[66:67], v[162:163], 0, v[66:67]
	global_load_dwordx4 v[94:97], v[66:67], off
	s_nop 0
	global_load_dwordx4 v[66:69], v[66:67], off offset:256
	s_waitcnt vmcnt(0)
; __device__ __forceinline__ float bflo(unsigned w) { return __uint_as_float(w << 16); }
; __device__ __forceinline__ float bfhi(unsigned w) { return __uint_as_float(w & 0xffff0000u); }
; #define PG8_WAIT_V(n) asm volatile("s_waitcnt vmcnt(" #n ")" ::: "memory")
; #define PG8_BAR __builtin_amdgcn_s_barrier()
; template <class Epi, bool SPLITA = false>
; __device__ __forceinline__ void gemm_phase(const int tid, LAS unsigned char* lds, const Gemm g, const Order& S, const Epi& E) {
;     ...
;     E(acc, cur, wr, wc, fr, fq);
;     if (!has_next) break;
; #pragma unroll
;     for (int a = 0; a < 2; ++a)
; #pragma unroll
;       for (int b = 0; b < 2; ++b)
; #pragma unroll
;         for (int m = 0; m < 4; ++m)
; #pragma unroll
;           for (int n = 0; n < 2; ++n) acc[a][b][m][n] = (f32x4){0.f, 0.f, 0.f, 0.f};
;     cur = nxt; cA = nA; cA2 = nA2; cB = nB; ++ui;
;   }
;   PG8_WAIT_V(0);
;   if (wr == 0) PG8_BAR;
;   PG8_BAR;
;   __device__ __forceinline__ void operator()(const Acc& acc, const Unit& u, int wr, int wc, int fr_, int fq_) const {
;     ...
;         for (int bj = 0; bj < 2; ++bj) hv[m][bj] = *(const u32x4*)(rin + (size_t)(row0 + ai * HALF + m * 16) * DM + col0 + bj * HALF);
; #pragma unroll
;       for (int m = 0; m < 4; ++m) { const size_t ro = (size_t)(row0 + ai * HALF + m * 16) * DM + col0; float ss = 0.f;
; #pragma unroll
;         for (int bj = 0; bj < 2; ++bj) { const u32x4 h = hv[m][bj];
;           f32x4 v0 = acc[ai][bj][m][0], v1 = acc[ai][bj][m][1];
;           v0[0] += bflo(h.x); v0[1] += bfhi(h.x); v0[2] += bflo(h.y); v0[3] += bfhi(h.y);
;           v1[0] += bflo(h.z); v1[1] += bfhi(h.z); v1[2] += bflo(h.w); v1[3] += bfhi(h.w);
;           if (FINAL) { *(f32x4*)(outf + ro + bj * HALF) = v0; *(f32x4*)(outf + ro + bj * HALF + 4) = v1; }
	v_lshlrev_b32_e32 v106, 16, v70
	v_and_b32_e32 v107, 0xffff0000, v70
	v_lshlrev_b32_e32 v70, 16, v71
	v_and_b32_e32 v71, 0xffff0000, v71
	v_pk_add_f32 v[64:65], v[64:65], v[70:71]
	v_lshlrev_b32_e32 v70, 16, v72
	v_and_b32_e32 v71, 0xffff0000, v72
	v_pk_add_f32 v[58:59], v[58:59], v[70:71]
	v_lshlrev_b32_e32 v70, 16, v73
	v_and_b32_e32 v71, 0xffff0000, v73
	v_pk_add_f32 v[60:61], v[60:61], v[70:71]
	v_lshlrev_b64 v[70:71], 13, v[98:99]
	v_lshl_add_u64 v[70:71], s[86:87], 0, v[70:71]
	v_pk_add_f32 v[62:63], v[62:63], v[106:107]
	v_lshl_add_u64 v[70:71], v[70:71], 0, v[122:123]
	global_store_dwordx4 v[70:71], v[62:65], off
	global_store_dwordx4 v[70:71], v[58:61], off offset:16
	s_nop 1
	v_lshlrev_b32_e32 v58, 16, v74
	v_and_b32_e32 v59, 0xffff0000, v74
	v_pk_add_f32 v[54:55], v[54:55], v[58:59]
	v_lshlrev_b32_e32 v58, 16, v75
	v_and_b32_e32 v59, 0xffff0000, v75
	v_pk_add_f32 v[56:57], v[56:57], v[58:59]
	v_lshlrev_b32_e32 v58, 16, v76
	v_and_b32_e32 v59, 0xffff0000, v76
	v_pk_add_f32 v[46:47], v[46:47], v[58:59]
	v_lshlrev_b32_e32 v58, 16, v77
	v_and_b32_e32 v59, 0xffff0000, v77
	v_pk_add_f32 v[48:49], v[48:49], v[58:59]
	global_store_dwordx4 v[70:71], v[54:57], off offset:512
	global_store_dwordx4 v[70:71], v[46:49], off offset:528
	s_nop 1
	v_lshlrev_b32_e32 v46, 16, v78
	v_and_b32_e32 v47, 0xffff0000, v78
	v_pk_add_f32 v[46:47], v[50:51], v[46:47]
	v_lshlrev_b32_e32 v50, 16, v80
	v_and_b32_e32 v51, 0xffff0000, v80
	v_pk_add_f32 v[42:43], v[42:43], v[50:51]
	v_lshlrev_b32_e32 v50, 16, v81
	v_and_b32_e32 v51, 0xffff0000, v81
	v_pk_add_f32 v[44:45], v[44:45], v[50:51]
	v_lshlrev_b64 v[50:51], 13, v[100:101]
	v_lshlrev_b32_e32 v48, 16, v79
	v_and_b32_e32 v49, 0xffff0000, v79
	v_lshl_add_u64 v[50:51], s[86:87], 0, v[50:51]
	v_pk_add_f32 v[48:49], v[52:53], v[48:49]
	v_lshl_add_u64 v[50:51], v[50:51], 0, v[122:123]
	global_store_dwordx4 v[50:51], v[46:49], off
	global_store_dwordx4 v[50:51], v[42:45], off offset:16
	s_nop 1
	v_lshlrev_b32_e32 v42, 16, v82
	v_and_b32_e32 v43, 0xffff0000, v82
	v_pk_add_f32 v[38:39], v[38:39], v[42:43]
	v_lshlrev_b32_e32 v42, 16, v83
	v_and_b32_e32 v43, 0xffff0000, v83
	v_pk_add_f32 v[40:41], v[40:41], v[42:43]
	v_lshlrev_b32_e32 v42, 16, v84
	v_and_b32_e32 v43, 0xffff0000, v84
	v_pk_add_f32 v[30:31], v[30:31], v[42:43]
	v_lshlrev_b32_e32 v42, 16, v85
	v_and_b32_e32 v43, 0xffff0000, v85
	v_pk_add_f32 v[32:33], v[32:33], v[42:43]
	global_store_dwordx4 v[50:51], v[38:41], off offset:512
	global_store_dwordx4 v[50:51], v[30:33], off offset:528
	s_nop 1
	v_lshlrev_b32_e32 v30, 16, v86
	v_and_b32_e32 v31, 0xffff0000, v86
	v_pk_add_f32 v[30:31], v[34:35], v[30:31]
	v_lshlrev_b32_e32 v34, 16, v88
	v_and_b32_e32 v35, 0xffff0000, v88
	v_pk_add_f32 v[26:27], v[26:27], v[34:35]
	v_lshlrev_b32_e32 v34, 16, v89
	v_and_b32_e32 v35, 0xffff0000, v89
	v_pk_add_f32 v[28:29], v[28:29], v[34:35]
	v_lshlrev_b64 v[34:35], 13, v[102:103]
	v_lshlrev_b32_e32 v32, 16, v87
	v_and_b32_e32 v33, 0xffff0000, v87
	v_lshl_add_u64 v[34:35], s[86:87], 0, v[34:35]
	v_pk_add_f32 v[32:33], v[36:37], v[32:33]
	v_lshl_add_u64 v[34:35], v[34:35], 0, v[122:123]
	global_store_dwordx4 v[34:35], v[30:33], off
	global_store_dwordx4 v[34:35], v[26:29], off offset:16
	s_nop 1
	v_lshlrev_b32_e32 v26, 16, v90
	v_and_b32_e32 v27, 0xffff0000, v90
	v_pk_add_f32 v[22:23], v[22:23], v[26:27]
	v_lshlrev_b32_e32 v26, 16, v91
	v_and_b32_e32 v27, 0xffff0000, v91
	v_pk_add_f32 v[24:25], v[24:25], v[26:27]
	v_lshlrev_b32_e32 v26, 16, v92
	v_and_b32_e32 v27, 0xffff0000, v92
	v_pk_add_f32 v[14:15], v[14:15], v[26:27]
	v_lshlrev_b32_e32 v26, 16, v93
	v_and_b32_e32 v27, 0xffff0000, v93
	v_pk_add_f32 v[16:17], v[16:17], v[26:27]
	global_store_dwordx4 v[34:35], v[22:25], off offset:512
	global_store_dwordx4 v[34:35], v[14:17], off offset:528
	s_nop 1
	v_lshlrev_b32_e32 v14, 16, v94
	v_and_b32_e32 v15, 0xffff0000, v94
	v_pk_add_f32 v[14:15], v[18:19], v[14:15]
	v_lshlrev_b32_e32 v18, 16, v96
	v_and_b32_e32 v19, 0xffff0000, v96
	v_pk_add_f32 v[10:11], v[10:11], v[18:19]
	v_lshlrev_b32_e32 v18, 16, v97
	v_and_b32_e32 v19, 0xffff0000, v97
	v_pk_add_f32 v[12:13], v[12:13], v[18:19]
	v_lshlrev_b64 v[18:19], 13, v[104:105]
	v_lshlrev_b32_e32 v16, 16, v95
	v_and_b32_e32 v17, 0xffff0000, v95
	v_lshl_add_u64 v[18:19], s[86:87], 0, v[18:19]
	v_pk_add_f32 v[16:17], v[20:21], v[16:17]
	v_lshl_add_u64 v[18:19], v[18:19], 0, v[122:123]
	global_store_dwordx4 v[18:19], v[14:17], off
	global_store_dwordx4 v[18:19], v[10:13], off offset:16
	s_nop 1
	v_lshlrev_b32_e32 v10, 16, v66
	v_and_b32_e32 v11, 0xffff0000, v66
	v_pk_add_f32 v[6:7], v[6:7], v[10:11]
	v_lshlrev_b32_e32 v10, 16, v67
	v_and_b32_e32 v11, 0xffff0000, v67
	v_pk_add_f32 v[8:9], v[8:9], v[10:11]
	v_lshlrev_b32_e32 v10, 16, v68
	v_and_b32_e32 v11, 0xffff0000, v68
	v_pk_add_f32 v[2:3], v[2:3], v[10:11]
	v_lshlrev_b32_e32 v10, 16, v69
	v_and_b32_e32 v11, 0xffff0000, v69
	v_pk_add_f32 v[4:5], v[4:5], v[10:11]
	global_store_dwordx4 v[18:19], v[6:9], off offset:512
	global_store_dwordx4 v[18:19], v[2:5], off offset:528
	s_cbranch_vccz .LBB0_46
	s_waitcnt vmcnt(0)
	v_mov_b32_e32 v219, v196
	s_cmpk_gt_u32 s2, 0xff
	s_cbranch_scc1 .LBB0_61
	s_barrier

; #define PG8_STAGE(bufoff, gbase, voff) do { _Pragma("unroll") for (int _i = 0; _i < 2; ++_i) \
;     __builtin_amdgcn_global_load_lds((const unsigned*)((const char*)(gbase) + (voff)[_i]), (LAS unsigned*)(lds + (bufoff) + ldsw + _i * 8192), 16, 0, 0); } while (0)
; #define PG8_LDA(dst, b, h) do { _Pragma("unroll") for (int m = 0; m < 4; ++m) _Pragma("unroll") for (int k = 0; k < 2; ++k) dst[m][k] = *(const LAS bf16x8*)(lds + PG8_SA(b, h) + aoff + m * 2048 + k * 1024); } while (0)
; #define PG8_LDB(dst, b, h) do { _Pragma("unroll") for (int n = 0; n < 2; ++n) _Pragma("unroll") for (int k = 0; k < 2; ++k) dst[n][k] = *(const LAS bf16x8*)(lds + PG8_SB(b, h) + boff + n * 2048 + k * 1024); } while (0)
; #define PG8_WAIT_L(n) asm volatile("s_waitcnt lgkmcnt(" #n ")" ::: "memory")
; #define PG8_BAR __builtin_amdgcn_s_barrier()
; #define PG8_SCHED __builtin_amdgcn_sched_barrier(0)
; template <class Epi, bool SPLITA = false>
; __device__ __forceinline__ void gemm_phase(const int tid, LAS unsigned char* lds, const Gemm g, const Order& S, const Epi& E) {
;     ...
;     const bool has_next = S.next(ui + 1, nxt);
;     const char* nA = has_next ? (const char*)g.A + (size_t)nxt.pm * tstepA + (size_t)nxt.pn * apn : cA; const char* nA2 = (SPLITA && has_next) ? (const char*)g.A2 + (size_t)nxt.pm * tstepA : cA2; const char* nB = has_next ? (const char*)g.Bt + (size_t)nxt.pn * tstepB : cB;
;     for (int t = 0; t < nt; t += 2) {
;       const bool last = (t == nt - 2);
;       if constexpr (SPLITA) { if (t == nt1) E.mid(acc, cur, wr, wc, fr, fq); }
;       const char* a1 = PG8_TA(t + 1);
;       const char* a2 = last ? nA : PG8_TA(t + 2); const char* b2 = last ? nB : cB + (size_t)(t + 2) * kstep;
;       const char* a3 = last ? nA + kstep : PG8_TA(t + 3); const char* b3 = b2 + kstep;
;       PG8_LDB(B0, 0, 0); PG8_SCHED; PG8_LDA(At, 0, 0); PG8_STAGE(PG8_SA(1, 1), a1 + hstepA, voffA);
;       PG8_WAIT_L(8); PG8_BAR; PG8_WAIT_L(0); PG8_MMA(0, 0, At, B0); PG8_BAR; PG8_SCHED;
;       PG8_LDB(B1, 0, 1); PG8_STAGE(PG8_SB(0, 0), b2, voffB);
;       PG8_BAR; PG8_WAIT_L(0); PG8_MMA(0, 1, At, B1); PG8_BAR;
;       PG8_LDA(At, 0, 1); PG8_STAGE(PG8_SA(0, 0), a2, voffA);
;       PG8_BAR; PG8_WAIT_L(0); PG8_MMA(1, 0, At, B0); PG8_BAR; PG8_SCHED;
.LBB0_87:
	s_add_u32 s8, s12, s16
	s_addc_u32 s9, s13, s17
	s_add_u32 s20, s8, 0x100
	s_addc_u32 s21, s9, 0
	s_add_u32 s18, s54, s16
	s_addc_u32 s19, s55, s17
	s_add_u32 s8, s8, 0x180
	s_addc_u32 s9, s9, 0
	s_add_i32 s90, 0, 0x10000
	v_add_u32_e32 v146, s90, v188
	ds_read_b128 v[134:137], v146
	ds_read_b128 v[138:141], v146 offset:1024
	ds_read_b128 v[142:145], v146 offset:2048
	ds_read_b128 v[146:149], v146 offset:3072
	s_cmpk_eq_i32 s16, 0x2b00
	s_cselect_b32 s23, s7, s9
	s_cselect_b32 s22, s6, s8
	s_cselect_b32 s19, s11, s19
	s_cselect_b32 s18, s10, s18
	s_cselect_b32 s41, s1, s21
	s_cselect_b32 s40, s0, s20
	v_lshl_add_u64 v[184:185], v[130:131], 0, s[16:17]
	s_add_i32 m0, s30, 0xc000
	ds_read_b128 v[150:153], v189
	ds_read_b128 v[154:157], v189 offset:1024
	ds_read_b128 v[168:171], v189 offset:2048
	ds_read_b128 v[172:175], v189 offset:3072
	ds_read_b128 v[176:179], v189 offset:4096
	ds_read_b128 v[180:183], v189 offset:5120
	ds_read_b128 v[190:193], v189 offset:6144
	ds_read_b128 v[212:215], v189 offset:7168
	global_load_lds_dwordx4 v[184:185], off
	v_lshl_add_u64 v[184:185], v[132:133], 0, s[16:17]
	s_add_i32 m0, s30, 0xe000
	s_nop 0
	global_load_lds_dwordx4 v[184:185], off
	s_waitcnt lgkmcnt(8)
	s_barrier
	s_waitcnt lgkmcnt(0)
	s_setprio 1
	s_waitcnt lgkmcnt(0)
	v_mfma_f32_16x16x32_bf16 v[126:129], v[134:137], v[150:153], v[126:129]
	v_mfma_f32_16x16x32_bf16 v[122:125], v[142:145], v[150:153], v[122:125]
	v_mfma_f32_16x16x32_bf16 v[110:113], v[134:137], v[168:171], v[110:113]
	v_mfma_f32_16x16x32_bf16 v[106:109], v[142:145], v[168:171], v[106:109]
	v_mfma_f32_16x16x32_bf16 v[94:97], v[134:137], v[176:179], v[94:97]
	v_mfma_f32_16x16x32_bf16 v[90:93], v[142:145], v[176:179], v[90:93]
	v_mfma_f32_16x16x32_bf16 v[78:81], v[134:137], v[190:193], v[78:81]
	v_mfma_f32_16x16x32_bf16 v[74:77], v[142:145], v[190:193], v[74:77]
	v_mfma_f32_16x16x32_bf16 v[126:129], v[138:141], v[154:157], v[126:129]
	v_mfma_f32_16x16x32_bf16 v[122:125], v[146:149], v[154:157], v[122:125]
	v_mfma_f32_16x16x32_bf16 v[110:113], v[138:141], v[172:175], v[110:113]
	v_mfma_f32_16x16x32_bf16 v[106:109], v[146:149], v[172:175], v[106:109]
	v_mfma_f32_16x16x32_bf16 v[94:97], v[138:141], v[180:183], v[94:97]
	v_mfma_f32_16x16x32_bf16 v[90:93], v[146:149], v[180:183], v[90:93]
	v_mfma_f32_16x16x32_bf16 v[78:81], v[138:141], v[212:215], v[78:81]
	v_mfma_f32_16x16x32_bf16 v[74:77], v[146:149], v[212:215], v[74:77]
	s_setprio 0
	s_barrier
	s_add_i32 s8, 0, 0x14000
	v_add_u32_e32 v184, s8, v188
	s_add_i32 s9, s90, s3
	ds_read_b128 v[216:219], v184
	ds_read_b128 v[220:223], v184 offset:1024
	ds_read_b128 v[224:227], v184 offset:2048
	ds_read_b128 v[228:231], v184 offset:3072
	s_mov_b32 m0, s9
	s_nop 0
	global_load_lds_dwordx4 v0, s[18:19]
	s_add_i32 m0, s9, 0x2000
	s_nop 0
	global_load_lds_dwordx4 v162, s[18:19]
	s_barrier
	s_waitcnt lgkmcnt(0)
	s_setprio 1
	s_waitcnt lgkmcnt(0)
	v_mfma_f32_16x16x32_bf16 v[118:121], v[216:219], v[150:153], v[118:121]
	v_mfma_f32_16x16x32_bf16 v[114:117], v[224:227], v[150:153], v[114:117]
	v_mfma_f32_16x16x32_bf16 v[102:105], v[216:219], v[168:171], v[102:105]
	v_mfma_f32_16x16x32_bf16 v[98:101], v[224:227], v[168:171], v[98:101]
	v_mfma_f32_16x16x32_bf16 v[86:89], v[216:219], v[176:179], v[86:89]
	v_mfma_f32_16x16x32_bf16 v[82:85], v[224:227], v[176:179], v[82:85]
	v_mfma_f32_16x16x32_bf16 v[70:73], v[216:219], v[190:193], v[70:73]
	v_mfma_f32_16x16x32_bf16 v[66:69], v[224:227], v[190:193], v[66:69]
	v_mfma_f32_16x16x32_bf16 v[118:121], v[220:223], v[154:157], v[118:121]
	v_mfma_f32_16x16x32_bf16 v[114:117], v[228:231], v[154:157], v[114:117]
	v_mfma_f32_16x16x32_bf16 v[102:105], v[220:223], v[172:175], v[102:105]
	v_mfma_f32_16x16x32_bf16 v[98:101], v[228:231], v[172:175], v[98:101]
	v_mfma_f32_16x16x32_bf16 v[86:89], v[220:223], v[180:183], v[86:89]
	v_mfma_f32_16x16x32_bf16 v[82:85], v[228:231], v[180:183], v[82:85]
	v_mfma_f32_16x16x32_bf16 v[70:73], v[220:223], v[212:215], v[70:73]
	v_mfma_f32_16x16x32_bf16 v[66:69], v[228:231], v[212:215], v[66:69]
	s_setprio 0
	s_mov_b32 m0, s30
	s_barrier
	ds_read_b128 v[150:153], v189 offset:16384
	ds_read_b128 v[154:157], v189 offset:17408
	ds_read_b128 v[168:171], v189 offset:18432
	ds_read_b128 v[172:175], v189 offset:19456
	ds_read_b128 v[176:179], v189 offset:20480
	ds_read_b128 v[180:183], v189 offset:21504
	ds_read_b128 v[190:193], v189 offset:22528
	ds_read_b128 v[212:215], v189 offset:23552
	global_load_lds_dwordx4 v158, s[40:41]
	s_mov_b32 m0, s31
	s_nop 0
	global_load_lds_dwordx4 v160, s[40:41]
	s_barrier
	s_waitcnt lgkmcnt(0)
	s_setprio 1
	s_waitcnt lgkmcnt(0)
	v_mfma_f32_16x16x32_bf16 v[62:65], v[134:137], v[150:153], v[62:65]
	v_mfma_f32_16x16x32_bf16 v[58:61], v[142:145], v[150:153], v[58:61]
	v_mfma_f32_16x16x32_bf16 v[46:49], v[134:137], v[168:171], v[46:49]
	v_mfma_f32_16x16x32_bf16 v[42:45], v[142:145], v[168:171], v[42:45]
	v_mfma_f32_16x16x32_bf16 v[30:33], v[134:137], v[176:179], v[30:33]
	v_mfma_f32_16x16x32_bf16 v[26:29], v[142:145], v[176:179], v[26:29]
	v_mfma_f32_16x16x32_bf16 v[14:17], v[134:137], v[190:193], v[14:17]
	v_mfma_f32_16x16x32_bf16 v[10:13], v[142:145], v[190:193], v[10:13]
	v_mfma_f32_16x16x32_bf16 v[62:65], v[138:141], v[154:157], v[62:65]
	v_mfma_f32_16x16x32_bf16 v[58:61], v[146:149], v[154:157], v[58:61]
	v_mfma_f32_16x16x32_bf16 v[46:49], v[138:141], v[172:175], v[46:49]
	v_mfma_f32_16x16x32_bf16 v[42:45], v[146:149], v[172:175], v[42:45]
	v_mfma_f32_16x16x32_bf16 v[30:33], v[138:141], v[180:183], v[30:33]
	v_mfma_f32_16x16x32_bf16 v[26:29], v[146:149], v[180:183], v[26:29]
	v_mfma_f32_16x16x32_bf16 v[14:17], v[138:141], v[212:215], v[14:17]
	v_mfma_f32_16x16x32_bf16 v[10:13], v[146:149], v[212:215], v[10:13]
	s_setprio 0
	s_barrier
; #define PG8_STAGE(bufoff, gbase, voff) do { _Pragma("unroll") for (int _i = 0; _i < 2; ++_i) \
;     __builtin_amdgcn_global_load_lds((const unsigned*)((const char*)(gbase) + (voff)[_i]), (LAS unsigned*)(lds + (bufoff) + ldsw + _i * 8192), 16, 0, 0); } while (0)
; #define PG8_LDA(dst, b, h) do { _Pragma("unroll") for (int m = 0; m < 4; ++m) _Pragma("unroll") for (int k = 0; k < 2; ++k) dst[m][k] = *(const LAS bf16x8*)(lds + PG8_SA(b, h) + aoff + m * 2048 + k * 1024); } while (0)
; #define PG8_LDB(dst, b, h) do { _Pragma("unroll") for (int n = 0; n < 2; ++n) _Pragma("unroll") for (int k = 0; k < 2; ++k) dst[n][k] = *(const LAS bf16x8*)(lds + PG8_SB(b, h) + boff + n * 2048 + k * 1024); } while (0)
; #define PG8_MMA(ai, bj, At, Bt) do { __builtin_amdgcn_s_setprio(1); _Pragma("unroll") for (int m = 0; m < 4; ++m) _Pragma("unroll") for (int n = 0; n < 2; ++n) _Pragma("unroll") for (int k = 0; k < 2; ++k) \
;     acc[ai][bj][m][n] = __builtin_amdgcn_mfma_f32_16x16x32_bf16(Bt[n][k], At[m][k], acc[ai][bj][m][n], 0, 0, 0); __builtin_amdgcn_s_setprio(0); } while (0)
; #define PG8_WAIT_V(n) asm volatile("s_waitcnt vmcnt(" #n ")" ::: "memory")
; #define PG8_WAIT_L(n) asm volatile("s_waitcnt lgkmcnt(" #n ")" ::: "memory")
; #define PG8_BAR __builtin_amdgcn_s_barrier()
; #define PG8_SCHED __builtin_amdgcn_sched_barrier(0)
; template <class Epi, bool SPLITA = false>
; __device__ __forceinline__ void gemm_phase(const int tid, LAS unsigned char* lds, const Gemm g, const Order& S, const Epi& E) {
;     ...
;       PG8_STAGE(PG8_SB(0, 1), b2 + hstepB, voffB);
;       PG8_WAIT_V(6); PG8_BAR; PG8_MMA(1, 1, At, B1); PG8_BAR;
;       PG8_LDB(B0, 1, 0); PG8_SCHED; PG8_LDA(At, 1, 0); PG8_STAGE(PG8_SA(0, 1), a2 + hstepA, voffA);
;       PG8_WAIT_L(8); PG8_BAR; PG8_WAIT_L(0); PG8_MMA(0, 0, At, B0); PG8_BAR; PG8_SCHED;
;       PG8_LDB(B1, 1, 1); PG8_STAGE(PG8_SB(1, 0), b3, voffB);
;       PG8_BAR; PG8_WAIT_L(0); PG8_MMA(0, 1, At, B1); PG8_BAR;
;       PG8_LDA(At, 1, 1); PG8_STAGE(PG8_SA(1, 0), a3, voffA);
	s_add_u32 s20, s18, 0x160000
	s_addc_u32 s21, s19, 0
	s_add_i32 s8, s8, s3
	s_mov_b32 m0, s8
	s_nop 0
	global_load_lds_dwordx4 v0, s[20:21]
	s_add_i32 m0, s8, 0x2000
	s_nop 0
	global_load_lds_dwordx4 v162, s[20:21]
	s_waitcnt vmcnt(6)
	s_barrier
	s_setprio 1
	v_mfma_f32_16x16x32_bf16 v[54:57], v[216:219], v[150:153], v[54:57]
	v_mfma_f32_16x16x32_bf16 v[50:53], v[224:227], v[150:153], v[50:53]
	v_mfma_f32_16x16x32_bf16 v[38:41], v[216:219], v[168:171], v[38:41]
	v_mfma_f32_16x16x32_bf16 v[34:37], v[224:227], v[168:171], v[34:37]
	v_mfma_f32_16x16x32_bf16 v[22:25], v[216:219], v[176:179], v[22:25]
	v_mfma_f32_16x16x32_bf16 v[18:21], v[224:227], v[176:179], v[18:21]
	v_mfma_f32_16x16x32_bf16 v[6:9], v[216:219], v[190:193], v[6:9]
	v_mfma_f32_16x16x32_bf16 v[2:5], v[224:227], v[190:193], v[2:5]
	v_mfma_f32_16x16x32_bf16 v[54:57], v[220:223], v[154:157], v[54:57]
	v_mfma_f32_16x16x32_bf16 v[50:53], v[228:231], v[154:157], v[50:53]
	v_mfma_f32_16x16x32_bf16 v[38:41], v[220:223], v[172:175], v[38:41]
	v_mfma_f32_16x16x32_bf16 v[34:37], v[228:231], v[172:175], v[34:37]
	v_mfma_f32_16x16x32_bf16 v[22:25], v[220:223], v[180:183], v[22:25]
	v_mfma_f32_16x16x32_bf16 v[18:21], v[228:231], v[180:183], v[18:21]
	v_mfma_f32_16x16x32_bf16 v[6:9], v[220:223], v[212:215], v[6:9]
	v_mfma_f32_16x16x32_bf16 v[2:5], v[228:231], v[212:215], v[2:5]
	s_setprio 0
	s_add_i32 s8, 0, 0x18000
	v_add_u32_e32 v146, s8, v188
	s_barrier
	ds_read_b128 v[134:137], v146
	ds_read_b128 v[138:141], v146 offset:1024
	ds_read_b128 v[142:145], v146 offset:2048
	ds_read_b128 v[146:149], v146 offset:3072
	s_add_u32 s20, s40, 0x160000
	s_addc_u32 s21, s41, 0
	s_mov_b32 m0, s42
	ds_read_b128 v[150:153], v189 offset:32768
	ds_read_b128 v[154:157], v189 offset:33792
	ds_read_b128 v[168:171], v189 offset:34816
	ds_read_b128 v[172:175], v189 offset:35840
	ds_read_b128 v[176:179], v189 offset:36864
	ds_read_b128 v[180:183], v189 offset:37888
	ds_read_b128 v[190:193], v189 offset:38912
	ds_read_b128 v[212:215], v189 offset:39936
	global_load_lds_dwordx4 v158, s[20:21]
	s_mov_b32 m0, s43
	s_nop 0
	global_load_lds_dwordx4 v160, s[20:21]
	s_waitcnt lgkmcnt(8)
	s_barrier
	s_waitcnt lgkmcnt(0)
	s_setprio 1
	s_waitcnt lgkmcnt(0)
	v_mfma_f32_16x16x32_bf16 v[126:129], v[134:137], v[150:153], v[126:129]
	v_mfma_f32_16x16x32_bf16 v[122:125], v[142:145], v[150:153], v[122:125]
	v_mfma_f32_16x16x32_bf16 v[110:113], v[134:137], v[168:171], v[110:113]
	v_mfma_f32_16x16x32_bf16 v[106:109], v[142:145], v[168:171], v[106:109]
	v_mfma_f32_16x16x32_bf16 v[94:97], v[134:137], v[176:179], v[94:97]
	v_mfma_f32_16x16x32_bf16 v[90:93], v[142:145], v[176:179], v[90:93]
	v_mfma_f32_16x16x32_bf16 v[78:81], v[134:137], v[190:193], v[78:81]
	v_mfma_f32_16x16x32_bf16 v[74:77], v[142:145], v[190:193], v[74:77]
	v_mfma_f32_16x16x32_bf16 v[126:129], v[138:141], v[154:157], v[126:129]
	v_mfma_f32_16x16x32_bf16 v[122:125], v[146:149], v[154:157], v[122:125]
	v_mfma_f32_16x16x32_bf16 v[110:113], v[138:141], v[172:175], v[110:113]
	v_mfma_f32_16x16x32_bf16 v[106:109], v[146:149], v[172:175], v[106:109]
	v_mfma_f32_16x16x32_bf16 v[94:97], v[138:141], v[180:183], v[94:97]
	v_mfma_f32_16x16x32_bf16 v[90:93], v[146:149], v[180:183], v[90:93]
	v_mfma_f32_16x16x32_bf16 v[78:81], v[138:141], v[212:215], v[78:81]
	v_mfma_f32_16x16x32_bf16 v[74:77], v[146:149], v[212:215], v[74:77]
	s_setprio 0
	s_barrier
	s_add_i32 s9, 0, 0x1c000
	s_add_i32 s8, s8, s3
	v_add_u32_e32 v195, s9, v188
	s_add_i32 m0, s8, 0xffffff80
	ds_read_b128 v[216:219], v195
	ds_read_b128 v[220:223], v195 offset:1024
	ds_read_b128 v[224:227], v195 offset:2048
	ds_read_b128 v[228:231], v195 offset:3072
	global_load_lds_dwordx4 v0, s[18:19] offset:128
	s_add_i32 m0, s8, 0x1f80
	s_nop 0
	global_load_lds_dwordx4 v162, s[18:19] offset:128
	s_barrier
	s_waitcnt lgkmcnt(0)
	s_setprio 1
	s_waitcnt lgkmcnt(0)
	v_mfma_f32_16x16x32_bf16 v[118:121], v[216:219], v[150:153], v[118:121]
	v_mfma_f32_16x16x32_bf16 v[114:117], v[224:227], v[150:153], v[114:117]
	v_mfma_f32_16x16x32_bf16 v[102:105], v[216:219], v[168:171], v[102:105]
	v_mfma_f32_16x16x32_bf16 v[98:101], v[224:227], v[168:171], v[98:101]
	v_mfma_f32_16x16x32_bf16 v[86:89], v[216:219], v[176:179], v[86:89]
	v_mfma_f32_16x16x32_bf16 v[82:85], v[224:227], v[176:179], v[82:85]
	v_mfma_f32_16x16x32_bf16 v[70:73], v[216:219], v[190:193], v[70:73]
	v_mfma_f32_16x16x32_bf16 v[66:69], v[224:227], v[190:193], v[66:69]
	v_mfma_f32_16x16x32_bf16 v[118:121], v[220:223], v[154:157], v[118:121]
	v_mfma_f32_16x16x32_bf16 v[114:117], v[228:231], v[154:157], v[114:117]
	v_mfma_f32_16x16x32_bf16 v[102:105], v[220:223], v[172:175], v[102:105]
	v_mfma_f32_16x16x32_bf16 v[98:101], v[228:231], v[172:175], v[98:101]
	v_mfma_f32_16x16x32_bf16 v[86:89], v[220:223], v[180:183], v[86:89]
	v_mfma_f32_16x16x32_bf16 v[82:85], v[228:231], v[180:183], v[82:85]
	v_mfma_f32_16x16x32_bf16 v[70:73], v[220:223], v[212:215], v[70:73]
	v_mfma_f32_16x16x32_bf16 v[66:69], v[228:231], v[212:215], v[66:69]
	s_setprio 0
	s_mov_b32 m0, s47
	s_barrier
	ds_read_b128 v[150:153], v189 offset:49152
	ds_read_b128 v[154:157], v189 offset:50176
	ds_read_b128 v[168:171], v189 offset:51200
	ds_read_b128 v[172:175], v189 offset:52224
	ds_read_b128 v[176:179], v189 offset:53248
	ds_read_b128 v[180:183], v189 offset:54272
	ds_read_b128 v[190:193], v189 offset:55296
	ds_read_b128 v[212:215], v189 offset:56320
	global_load_lds_dwordx4 v158, s[22:23]
	s_mov_b32 m0, s48
	s_nop 0
	global_load_lds_dwordx4 v160, s[22:23]
	s_barrier
; #define PG8_STAGE(bufoff, gbase, voff) do { _Pragma("unroll") for (int _i = 0; _i < 2; ++_i) \
;     __builtin_amdgcn_global_load_lds((const unsigned*)((const char*)(gbase) + (voff)[_i]), (LAS unsigned*)(lds + (bufoff) + ldsw + _i * 8192), 16, 0, 0); } while (0)
; #define PG8_LDA(dst, b, h) do { _Pragma("unroll") for (int m = 0; m < 4; ++m) _Pragma("unroll") for (int k = 0; k < 2; ++k) dst[m][k] = *(const LAS bf16x8*)(lds + PG8_SA(b, h) + aoff + m * 2048 + k * 1024); } while (0)
; #define PG8_MMA(ai, bj, At, Bt) do { __builtin_amdgcn_s_setprio(1); _Pragma("unroll") for (int m = 0; m < 4; ++m) _Pragma("unroll") for (int n = 0; n < 2; ++n) _Pragma("unroll") for (int k = 0; k < 2; ++k) \
;     acc[ai][bj][m][n] = __builtin_amdgcn_mfma_f32_16x16x32_bf16(Bt[n][k], At[m][k], acc[ai][bj][m][n], 0, 0, 0); __builtin_amdgcn_s_setprio(0); } while (0)
; #define PG8_WAIT_V(n) asm volatile("s_waitcnt vmcnt(" #n ")" ::: "memory")
; #define PG8_WAIT_L(n) asm volatile("s_waitcnt lgkmcnt(" #n ")" ::: "memory")
; #define PG8_BAR __builtin_amdgcn_s_barrier()
; #define PG8_SCHED __builtin_amdgcn_sched_barrier(0)
; template <class Epi, bool SPLITA = false>
; __device__ __forceinline__ void gemm_phase(const int tid, LAS unsigned char* lds, const Gemm g, const Order& S, const Epi& E) {
;     ...
;       PG8_BAR; PG8_WAIT_L(0); PG8_MMA(0, 1, At, B1); PG8_BAR;
;       PG8_LDA(At, 1, 1); PG8_STAGE(PG8_SA(1, 0), a3, voffA);
;       PG8_BAR; PG8_WAIT_L(0); PG8_MMA(1, 0, At, B0); PG8_BAR; PG8_SCHED;
;       PG8_STAGE(PG8_SB(1, 1), b3 + hstepB, voffB);
;       PG8_WAIT_V(6); PG8_BAR; PG8_MMA(1, 1, At, B1); PG8_BAR;
;     }
	s_waitcnt lgkmcnt(0)
	s_setprio 1
	s_waitcnt lgkmcnt(0)
	v_mfma_f32_16x16x32_bf16 v[62:65], v[134:137], v[150:153], v[62:65]
	v_mfma_f32_16x16x32_bf16 v[58:61], v[142:145], v[150:153], v[58:61]
	v_mfma_f32_16x16x32_bf16 v[46:49], v[134:137], v[168:171], v[46:49]
	v_mfma_f32_16x16x32_bf16 v[42:45], v[142:145], v[168:171], v[42:45]
	v_mfma_f32_16x16x32_bf16 v[30:33], v[134:137], v[176:179], v[30:33]
	v_mfma_f32_16x16x32_bf16 v[26:29], v[142:145], v[176:179], v[26:29]
	v_mfma_f32_16x16x32_bf16 v[14:17], v[134:137], v[190:193], v[14:17]
	v_mfma_f32_16x16x32_bf16 v[10:13], v[142:145], v[190:193], v[10:13]
	v_mfma_f32_16x16x32_bf16 v[62:65], v[138:141], v[154:157], v[62:65]
	v_mfma_f32_16x16x32_bf16 v[58:61], v[146:149], v[154:157], v[58:61]
	v_mfma_f32_16x16x32_bf16 v[46:49], v[138:141], v[172:175], v[46:49]
	v_mfma_f32_16x16x32_bf16 v[42:45], v[146:149], v[172:175], v[42:45]
	v_mfma_f32_16x16x32_bf16 v[30:33], v[138:141], v[180:183], v[30:33]
	v_mfma_f32_16x16x32_bf16 v[26:29], v[146:149], v[180:183], v[26:29]
	v_mfma_f32_16x16x32_bf16 v[14:17], v[138:141], v[212:215], v[14:17]
	v_mfma_f32_16x16x32_bf16 v[10:13], v[146:149], v[212:215], v[10:13]
	s_setprio 0
	s_barrier
	s_add_u32 s18, s18, 0x160080
	s_addc_u32 s19, s19, 0
	s_add_i32 s8, s9, s3
	s_mov_b32 m0, s8
	s_nop 0
	global_load_lds_dwordx4 v0, s[18:19]
	s_add_i32 m0, s8, 0x2000
	s_nop 0
	global_load_lds_dwordx4 v162, s[18:19]
	s_waitcnt vmcnt(6)
	s_barrier
	s_setprio 1
	v_mfma_f32_16x16x32_bf16 v[54:57], v[216:219], v[150:153], v[54:57]
	v_mfma_f32_16x16x32_bf16 v[50:53], v[224:227], v[150:153], v[50:53]
	v_mfma_f32_16x16x32_bf16 v[38:41], v[216:219], v[168:171], v[38:41]
	v_mfma_f32_16x16x32_bf16 v[34:37], v[224:227], v[168:171], v[34:37]
	v_mfma_f32_16x16x32_bf16 v[22:25], v[216:219], v[176:179], v[22:25]
	v_mfma_f32_16x16x32_bf16 v[18:21], v[224:227], v[176:179], v[18:21]
	v_mfma_f32_16x16x32_bf16 v[6:9], v[216:219], v[190:193], v[6:9]
	v_mfma_f32_16x16x32_bf16 v[2:5], v[224:227], v[190:193], v[2:5]
	v_mfma_f32_16x16x32_bf16 v[54:57], v[220:223], v[154:157], v[54:57]
	v_mfma_f32_16x16x32_bf16 v[50:53], v[228:231], v[154:157], v[50:53]
	v_mfma_f32_16x16x32_bf16 v[38:41], v[220:223], v[172:175], v[38:41]
	v_mfma_f32_16x16x32_bf16 v[34:37], v[228:231], v[172:175], v[34:37]
	v_mfma_f32_16x16x32_bf16 v[22:25], v[220:223], v[180:183], v[22:25]
	v_mfma_f32_16x16x32_bf16 v[18:21], v[228:231], v[180:183], v[18:21]
	v_mfma_f32_16x16x32_bf16 v[6:9], v[220:223], v[212:215], v[6:9]
	v_mfma_f32_16x16x32_bf16 v[2:5], v[228:231], v[212:215], v[2:5]
	s_setprio 0
	s_add_i32 s29, s29, 2
	s_add_u32 s16, s16, 0x100
	s_addc_u32 s17, s17, 0
	s_cmpk_gt_u32 s29, 0x55
	s_barrier
	s_cbranch_scc0 .LBB0_87
; __device__ __forceinline__ float bflo(unsigned w) { return __uint_as_float(w << 16); }
; __device__ __forceinline__ float bfhi(unsigned w) { return __uint_as_float(w & 0xffff0000u); }
; __device__ __forceinline__ float lane_read(float v, int src) { return __int_as_float(__builtin_amdgcn_ds_bpermute(src << 2, __float_as_int(v))); }
; __device__ __forceinline__ u32x4 pack8(const f32x4 v0, const f32x4 v1) { u32x4 w; w.x = cvtpk(v0[0], v0[1]); w.y = cvtpk(v0[2], v0[3]); w.z = cvtpk(v1[0], v1[1]); w.w = cvtpk(v1[2], v1[3]); return w; }
;   __device__ __forceinline__ void operator()(const Acc& acc, const Unit& u, int wr, int wc, int fr_, int fq_) const {
;     int fr = fr_, fq = fq_; asm volatile("" : "+v"(fr), "+v"(fq));
;     const int lane = fq * 16 + fr;
;     const int row0 = u.pm * BM + wr * 64 + fr, col0 = u.pn * BM + wc * 32 + 8 * fq;
; #pragma unroll
;     for (int ai = 0; ai < 2; ++ai) {
;       u32x4 hv[4][2];
; #pragma unroll
;       for (int m = 0; m < 4; ++m)
; #pragma unroll
;         for (int bj = 0; bj < 2; ++bj) hv[m][bj] = *(const u32x4*)(rin + (size_t)(row0 + ai * HALF + m * 16) * DM + col0 + bj * HALF);
; #pragma unroll
;       for (int m = 0; m < 4; ++m) { const size_t ro = (size_t)(row0 + ai * HALF + m * 16) * DM + col0; float ss = 0.f;
; #pragma unroll
;         for (int bj = 0; bj < 2; ++bj) { const u32x4 h = hv[m][bj];
;           f32x4 v0 = acc[ai][bj][m][0], v1 = acc[ai][bj][m][1];
;           v0[0] += bflo(h.x); v0[1] += bfhi(h.x); v0[2] += bflo(h.y); v0[3] += bfhi(h.y);
;           v1[0] += bflo(h.z); v1[1] += bfhi(h.z); v1[2] += bflo(h.w); v1[3] += bfhi(h.w);
;           if (FINAL) { *(f32x4*)(outf + ro + bj * HALF) = v0; *(f32x4*)(outf + ro + bj * HALF + 4) = v1; }
;           else { ss += v0[0] * v0[0] + v0[1] * v0[1] + v0[2] * v0[2] + v0[3] * v0[3] + v1[0] * v1[0] + v1[1] * v1[1] + v1[2] * v1[2] + v1[3] * v1[3];
;             *(u32x4*)(outb + ro + bj * HALF) = pack8(v0, v1); } }
;         if (!FINAL) { ss += lane_read(ss, lane ^ 16); ss += lane_read(ss, lane ^ 32);
;           if (fq == 0) rss[(size_t)(row0 + ai * HALF + m * 16) * 32 + u.pn * 4 + wc] = ss; } }
	s_lshl_b32 s6, s53, 8
	v_mov_b32_e32 v130, v187
	v_mov_b32_e32 v131, v186
	s_add_i32 s6, s6, s45
	s_lshl_b32 s12, s4, 2
	v_add_u32_e32 v170, s6, v130
	s_lshl_b32 s6, s4, 8
	s_or_b32 s6, s6, s46
	v_lshl_add_u32 v168, v131, 3, s6
	v_ashrrev_i32_e32 v169, 31, v168
	v_lshlrev_b32_e32 v130, 2, v130
	v_lshlrev_b64 v[192:193], 1, v[168:169]
	v_ashrrev_i32_e32 v171, 31, v170
	v_lshl_add_u32 v130, v131, 6, v130
	v_lshl_add_u64 v[172:173], s[86:87], 0, v[192:193]
	v_lshlrev_b64 v[198:199], 12, v[170:171]
	v_xor_b32_e32 v191, 64, v130
	v_xor_b32_e32 v190, 0x80, v130
	v_cmp_eq_u32_e32 vcc, 0, v131
	v_lshl_add_u64 v[130:131], v[172:173], 0, v[198:199]
	global_load_dwordx4 v[212:215], v[130:131], off
	global_load_dwordx4 v[154:157], v[130:131], off offset:256
	v_add_u32_e32 v182, 16, v170
	v_ashrrev_i32_e32 v183, 31, v182
	v_add_u32_e32 v178, 32, v170
	v_lshlrev_b64 v[184:185], 12, v[182:183]
	v_ashrrev_i32_e32 v179, 31, v178
	v_add_u32_e32 v174, 48, v170
	v_lshl_add_u64 v[130:131], v[172:173], 0, v[184:185]
	v_lshlrev_b64 v[180:181], 12, v[178:179]
	v_ashrrev_i32_e32 v175, 31, v174
	global_load_dwordx4 v[150:153], v[130:131], off
	global_load_dwordx4 v[146:149], v[130:131], off offset:256
	v_lshl_add_u64 v[130:131], v[172:173], 0, v[180:181]
	v_lshlrev_b64 v[176:177], 12, v[174:175]
	global_load_dwordx4 v[142:145], v[130:131], off
	global_load_dwordx4 v[138:141], v[130:131], off offset:256
	v_lshl_add_u64 v[130:131], v[172:173], 0, v[176:177]
	global_load_dwordx4 v[134:137], v[130:131], off
	s_nop 0
	global_load_dwordx4 v[130:133], v[130:131], off offset:256
	s_ashr_i32 s13, s12, 31
	s_waitcnt vmcnt(0)
	v_lshlrev_b32_e32 v200, 16, v212
	v_and_b32_e32 v201, 0xffff0000, v212
	v_pk_add_f32 v[126:127], v[126:127], v[200:201]
	v_lshlrev_b32_e32 v200, 16, v213
	v_and_b32_e32 v201, 0xffff0000, v213
	v_pk_add_f32 v[128:129], v[128:129], v[200:201]
	v_lshlrev_b32_e32 v200, 16, v214
	v_and_b32_e32 v201, 0xffff0000, v214
	v_pk_add_f32 v[200:201], v[122:123], v[200:201]
	v_lshlrev_b32_e32 v122, 16, v215
	v_and_b32_e32 v123, 0xffff0000, v215
	v_pk_add_f32 v[202:203], v[124:125], v[122:123]
	v_pk_mul_f32 v[204:205], v[126:127], v[126:127]
	v_cvt_pk_bf16_f32 v122, v126, v127
	v_lshl_add_u64 v[126:127], s[86:87], 0, v[198:199]
	v_cvt_pk_bf16_f32 v123, v128, v129
	v_cvt_pk_bf16_f32 v124, v200, v201
	v_cvt_pk_bf16_f32 v125, v202, v203
	v_lshl_add_u64 v[126:127], v[126:127], 0, v[192:193]
	global_store_dwordx4 v[126:127], v[122:125], off
	v_pk_mul_f32 v[206:207], v[128:129], v[128:129]
	v_pk_mul_f32 v[212:213], v[200:201], v[200:201]
	v_lshlrev_b32_e32 v122, 16, v154
	v_and_b32_e32 v123, 0xffff0000, v154
	v_pk_add_f32 v[118:119], v[118:119], v[122:123]
	v_lshlrev_b32_e32 v122, 16, v155
	v_and_b32_e32 v123, 0xffff0000, v155
	v_pk_add_f32 v[120:121], v[120:121], v[122:123]
	v_lshlrev_b32_e32 v122, 16, v156
	v_and_b32_e32 v123, 0xffff0000, v156
	v_pk_add_f32 v[122:123], v[114:115], v[122:123]
	v_lshlrev_b32_e32 v114, 16, v157
	v_and_b32_e32 v115, 0xffff0000, v157
	v_pk_add_f32 v[124:125], v[116:117], v[114:115]
	v_pk_mul_f32 v[114:115], v[118:119], v[118:119]
	v_pk_mul_f32 v[116:117], v[120:121], v[120:121]
	v_add_f32_e32 v114, v114, v115
	v_add_f32_e32 v115, v204, v205
	v_add_f32_e32 v114, v116, v114
	v_add_f32_e32 v115, v206, v115
	v_pk_mul_f32 v[128:129], v[122:123], v[122:123]
	v_add_f32_e32 v114, v117, v114
	v_add_f32_e32 v115, v207, v115
	v_add_f32_e32 v114, v128, v114
	v_add_f32_e32 v115, v212, v115
	v_pk_mul_f32 v[214:215], v[202:203], v[202:203]
	v_pk_mul_f32 v[154:155], v[124:125], v[124:125]
	v_add_f32_e32 v114, v129, v114
	v_add_f32_e32 v115, v213, v115
	v_add_f32_e32 v114, v154, v114
	v_add_f32_e32 v115, v214, v115
	v_add_f32_e32 v114, v155, v114
	v_add_f32_e32 v115, v215, v115
	v_add_f32_e32 v128, v115, v114
	v_cvt_pk_bf16_f32 v114, v118, v119
	v_cvt_pk_bf16_f32 v115, v120, v121
	v_cvt_pk_bf16_f32 v116, v122, v123
	v_cvt_pk_bf16_f32 v117, v124, v125
	global_store_dwordx4 v[126:127], v[114:117], off offset:256
	ds_bpermute_b32 v114, v191, v128
	s_waitcnt lgkmcnt(0)
	v_add_f32_e32 v114, v128, v114
	ds_bpermute_b32 v115, v190, v114
	s_and_saveexec_b64 s[6:7], vcc
	s_cbranch_execz .LBB0_90
	v_readlane_b32 s8, v255, 1
	v_lshlrev_b64 v[116:117], 7, v[170:171]
	v_readlane_b32 s9, v255, 2
	s_lshl_b32 s4, s44, 2
	s_waitcnt lgkmcnt(0)
	v_add_f32_e32 v114, v114, v115
	v_lshl_add_u64 v[116:117], s[8:9], 0, v[116:117]
	v_lshl_add_u64 v[116:117], s[12:13], 2, v[116:117]
	v_lshl_add_u64 v[116:117], v[116:117], 0, s[4:5]
	global_store_dword v[116:117], v114, off

; #define PG8_STAGE(bufoff, gbase, voff) do { _Pragma("unroll") for (int _i = 0; _i < 2; ++_i) \
;     __builtin_amdgcn_global_load_lds((const unsigned*)((const char*)(gbase) + (voff)[_i]), (LAS unsigned*)(lds + (bufoff) + ldsw + _i * 8192), 16, 0, 0); } while (0)
; #define PG8_LDA(dst, b, h) do { _Pragma("unroll") for (int m = 0; m < 4; ++m) _Pragma("unroll") for (int k = 0; k < 2; ++k) dst[m][k] = *(const LAS bf16x8*)(lds + PG8_SA(b, h) + aoff + m * 2048 + k * 1024); } while (0)
; #define PG8_LDB(dst, b, h) do { _Pragma("unroll") for (int n = 0; n < 2; ++n) _Pragma("unroll") for (int k = 0; k < 2; ++k) dst[n][k] = *(const LAS bf16x8*)(lds + PG8_SB(b, h) + boff + n * 2048 + k * 1024); } while (0)
; #define PG8_WAIT_L(n) asm volatile("s_waitcnt lgkmcnt(" #n ")" ::: "memory")
; #define PG8_BAR __builtin_amdgcn_s_barrier()
; #define PG8_SCHED __builtin_amdgcn_sched_barrier(0)
; template <class Epi, bool SPLITA = false>
; __device__ __forceinline__ void gemm_phase(const int tid, LAS unsigned char* lds, const Gemm g, const Order& S, const Epi& E) {
;     ...
;     const bool has_next = S.next(ui + 1, nxt);
;     const char* nA = has_next ? (const char*)g.A + (size_t)nxt.pm * tstepA + (size_t)nxt.pn * apn : cA; const char* nA2 = (SPLITA && has_next) ? (const char*)g.A2 + (size_t)nxt.pm * tstepA : cA2; const char* nB = has_next ? (const char*)g.Bt + (size_t)nxt.pn * tstepB : cB;
;     for (int t = 0; t < nt; t += 2) {
;       const bool last = (t == nt - 2);
;       if constexpr (SPLITA) { if (t == nt1) E.mid(acc, cur, wr, wc, fr, fq); }
;       const char* a1 = PG8_TA(t + 1);
;       const char* a2 = last ? nA : PG8_TA(t + 2); const char* b2 = last ? nB : cB + (size_t)(t + 2) * kstep;
;       const char* a3 = last ? nA + kstep : PG8_TA(t + 3); const char* b3 = b2 + kstep;
;       PG8_LDB(B0, 0, 0); PG8_SCHED; PG8_LDA(At, 0, 0); PG8_STAGE(PG8_SA(1, 1), a1 + hstepA, voffA);
;       PG8_WAIT_L(8); PG8_BAR; PG8_WAIT_L(0); PG8_MMA(0, 0, At, B0); PG8_BAR; PG8_SCHED;
;       PG8_LDB(B1, 0, 1); PG8_STAGE(PG8_SB(0, 0), b2, voffB);
;       PG8_BAR; PG8_WAIT_L(0); PG8_MMA(0, 1, At, B1); PG8_BAR;
;       PG8_LDA(At, 0, 1); PG8_STAGE(PG8_SA(0, 0), a2, voffA);
;       PG8_BAR; PG8_WAIT_L(0); PG8_MMA(1, 0, At, B0); PG8_BAR; PG8_SCHED;
.LBB0_144:
	s_add_u32 s8, s40, s42
	s_addc_u32 s9, s41, s43
	s_add_u32 s20, s8, 0x100
	s_addc_u32 s21, s9, 0
	s_add_u32 s44, s30, s42
	s_addc_u32 s45, s14, s43
	s_add_u32 s8, s8, 0x180
	s_addc_u32 s9, s9, 0
	s_add_i32 s94, 0, 0x10000
	v_add_u32_e32 v90, s94, v183
	ds_read_b128 v[78:81], v90
	ds_read_b128 v[82:85], v90 offset:1024
	ds_read_b128 v[86:89], v90 offset:2048
	ds_read_b128 v[90:93], v90 offset:3072
	s_cmpk_eq_i32 s42, 0xf00
	s_cselect_b32 s47, s3, s9
	s_cselect_b32 s46, s91, s8
	s_cselect_b32 s45, s23, s45
	s_cselect_b32 s44, s28, s44
	s_cselect_b32 vcc_hi, s7, s21
	s_cselect_b32 vcc_lo, s19, s20
	v_lshl_add_u64 v[180:181], v[74:75], 0, s[42:43]
	s_add_i32 m0, s31, 0xc000
	ds_read_b128 v[94:97], v195
	ds_read_b128 v[98:101], v195 offset:1024
	ds_read_b128 v[102:105], v195 offset:2048
	ds_read_b128 v[172:175], v195 offset:3072
	ds_read_b128 v[184:187], v195 offset:4096
	ds_read_b128 v[188:191], v195 offset:5120
	ds_read_b128 v[212:215], v195 offset:6144
	ds_read_b128 v[216:219], v195 offset:7168
	global_load_lds_dwordx4 v[180:181], off
	v_lshl_add_u64 v[180:181], v[76:77], 0, s[42:43]
	s_add_i32 m0, s31, 0xe000
	s_nop 0
	global_load_lds_dwordx4 v[180:181], off
	s_waitcnt lgkmcnt(8)
	s_barrier
	s_waitcnt lgkmcnt(0)
	s_setprio 1
	s_waitcnt lgkmcnt(0)
	v_mfma_f32_16x16x32_bf16 v[30:33], v[78:81], v[94:97], v[30:33]
	v_mfma_f32_16x16x32_bf16 v[26:29], v[86:89], v[94:97], v[26:29]
	v_mfma_f32_16x16x32_bf16 v[14:17], v[78:81], v[102:105], v[14:17]
	v_mfma_f32_16x16x32_bf16 v[10:13], v[86:89], v[102:105], v[10:13]
	v_mfma_f32_16x16x32_bf16 v[158:161], v[78:81], v[184:187], v[158:161]
	v_mfma_f32_16x16x32_bf16 v[154:157], v[86:89], v[184:187], v[154:157]
	v_mfma_f32_16x16x32_bf16 v[150:153], v[78:81], v[212:215], v[150:153]
	v_mfma_f32_16x16x32_bf16 v[146:149], v[86:89], v[212:215], v[146:149]
	v_mfma_f32_16x16x32_bf16 v[30:33], v[82:85], v[98:101], v[30:33]
	v_mfma_f32_16x16x32_bf16 v[26:29], v[90:93], v[98:101], v[26:29]
	v_mfma_f32_16x16x32_bf16 v[14:17], v[82:85], v[172:175], v[14:17]
	v_mfma_f32_16x16x32_bf16 v[10:13], v[90:93], v[172:175], v[10:13]
	v_mfma_f32_16x16x32_bf16 v[158:161], v[82:85], v[188:191], v[158:161]
	v_mfma_f32_16x16x32_bf16 v[154:157], v[90:93], v[188:191], v[154:157]
	v_mfma_f32_16x16x32_bf16 v[150:153], v[82:85], v[216:219], v[150:153]
	v_mfma_f32_16x16x32_bf16 v[146:149], v[90:93], v[216:219], v[146:149]
	s_setprio 0
	s_barrier
	s_add_i32 s8, 0, 0x14000
	s_add_i32 s9, s94, s2
	v_add_u32_e32 v176, s8, v183
	s_mov_b32 m0, s9
	ds_read_b128 v[220:223], v176
	ds_read_b128 v[224:227], v176 offset:1024
	ds_read_b128 v[228:231], v176 offset:2048
	ds_read_b128 v[232:235], v176 offset:3072
	global_load_lds_dwordx4 v0, s[44:45]
	s_add_i32 m0, s9, 0x2000
	s_nop 0
	global_load_lds_dwordx4 v162, s[44:45]
	s_barrier
	s_waitcnt lgkmcnt(0)
	s_setprio 1
	s_waitcnt lgkmcnt(0)
	v_mfma_f32_16x16x32_bf16 v[22:25], v[220:223], v[94:97], v[22:25]
	v_mfma_f32_16x16x32_bf16 v[18:21], v[228:231], v[94:97], v[18:21]
	v_mfma_f32_16x16x32_bf16 v[6:9], v[220:223], v[102:105], v[6:9]
	v_mfma_f32_16x16x32_bf16 v[2:5], v[228:231], v[102:105], v[2:5]
	v_mfma_f32_16x16x32_bf16 v[130:133], v[228:231], v[212:215], v[130:133]
	v_mfma_f32_16x16x32_bf16 v[22:25], v[224:227], v[98:101], v[22:25]
	v_mfma_f32_16x16x32_bf16 v[18:21], v[232:235], v[98:101], v[18:21]
	v_mfma_f32_16x16x32_bf16 v[6:9], v[224:227], v[172:175], v[6:9]
	v_mfma_f32_16x16x32_bf16 v[2:5], v[232:235], v[172:175], v[2:5]
	v_mfma_f32_16x16x32_bf16 v[94:97], v[220:223], v[184:187], v[142:145]
	v_mfma_f32_16x16x32_bf16 v[98:101], v[228:231], v[184:187], v[138:141]
	v_mfma_f32_16x16x32_bf16 v[102:105], v[220:223], v[212:215], v[134:137]
	v_mfma_f32_16x16x32_bf16 v[130:133], v[232:235], v[216:219], v[130:133]
	v_mfma_f32_16x16x32_bf16 v[94:97], v[224:227], v[188:191], v[94:97]
	v_mfma_f32_16x16x32_bf16 v[98:101], v[232:235], v[188:191], v[98:101]
	v_mfma_f32_16x16x32_bf16 v[102:105], v[224:227], v[216:219], v[102:105]
	s_setprio 0
	s_mov_b32 m0, s31
	v_lshl_add_u64 v[198:199], vcc, 0, v[166:167]
	s_barrier
	ds_read_b128 v[134:137], v195 offset:16384
	ds_read_b128 v[138:141], v195 offset:17408
	ds_read_b128 v[142:145], v195 offset:18432
	ds_read_b128 v[172:175], v195 offset:19456
	ds_read_b128 v[184:187], v195 offset:20480
	ds_read_b128 v[188:191], v195 offset:21504
	ds_read_b128 v[212:215], v195 offset:22528
	ds_read_b128 v[216:219], v195 offset:23552
	global_load_lds_dwordx4 v[198:199], off
	v_lshl_add_u64 v[198:199], vcc, 0, v[164:165]
	s_mov_b32 m0, s51
	s_nop 0
	global_load_lds_dwordx4 v[198:199], off
	s_barrier
	s_waitcnt lgkmcnt(0)
	s_setprio 1
	s_waitcnt lgkmcnt(0)
	v_mfma_f32_16x16x32_bf16 v[126:129], v[78:81], v[134:137], v[126:129]
	v_mfma_f32_16x16x32_bf16 v[122:125], v[86:89], v[134:137], v[122:125]
	v_mfma_f32_16x16x32_bf16 v[118:121], v[78:81], v[142:145], v[118:121]
	v_mfma_f32_16x16x32_bf16 v[114:117], v[86:89], v[142:145], v[114:117]
	v_mfma_f32_16x16x32_bf16 v[70:73], v[78:81], v[184:187], v[70:73]
	v_mfma_f32_16x16x32_bf16 v[66:69], v[86:89], v[184:187], v[66:69]
	v_mfma_f32_16x16x32_bf16 v[54:57], v[78:81], v[212:215], v[54:57]
	v_mfma_f32_16x16x32_bf16 v[50:53], v[86:89], v[212:215], v[50:53]
	v_mfma_f32_16x16x32_bf16 v[126:129], v[82:85], v[138:141], v[126:129]
	v_mfma_f32_16x16x32_bf16 v[122:125], v[90:93], v[138:141], v[122:125]
	v_mfma_f32_16x16x32_bf16 v[118:121], v[82:85], v[172:175], v[118:121]
	v_mfma_f32_16x16x32_bf16 v[114:117], v[90:93], v[172:175], v[114:117]
	v_mfma_f32_16x16x32_bf16 v[70:73], v[82:85], v[188:191], v[70:73]
	v_mfma_f32_16x16x32_bf16 v[66:69], v[90:93], v[188:191], v[66:69]
	v_mfma_f32_16x16x32_bf16 v[54:57], v[82:85], v[216:219], v[54:57]
	v_mfma_f32_16x16x32_bf16 v[50:53], v[90:93], v[216:219], v[50:53]
	s_setprio 0
	s_barrier
; #define PG8_STAGE(bufoff, gbase, voff) do { _Pragma("unroll") for (int _i = 0; _i < 2; ++_i) \
;     __builtin_amdgcn_global_load_lds((const unsigned*)((const char*)(gbase) + (voff)[_i]), (LAS unsigned*)(lds + (bufoff) + ldsw + _i * 8192), 16, 0, 0); } while (0)
; #define PG8_LDA(dst, b, h) do { _Pragma("unroll") for (int m = 0; m < 4; ++m) _Pragma("unroll") for (int k = 0; k < 2; ++k) dst[m][k] = *(const LAS bf16x8*)(lds + PG8_SA(b, h) + aoff + m * 2048 + k * 1024); } while (0)
; #define PG8_LDB(dst, b, h) do { _Pragma("unroll") for (int n = 0; n < 2; ++n) _Pragma("unroll") for (int k = 0; k < 2; ++k) dst[n][k] = *(const LAS bf16x8*)(lds + PG8_SB(b, h) + boff + n * 2048 + k * 1024); } while (0)
; #define PG8_MMA(ai, bj, At, Bt) do { __builtin_amdgcn_s_setprio(1); _Pragma("unroll") for (int m = 0; m < 4; ++m) _Pragma("unroll") for (int n = 0; n < 2; ++n) _Pragma("unroll") for (int k = 0; k < 2; ++k) \
;     acc[ai][bj][m][n] = __builtin_amdgcn_mfma_f32_16x16x32_bf16(Bt[n][k], At[m][k], acc[ai][bj][m][n], 0, 0, 0); __builtin_amdgcn_s_setprio(0); } while (0)
; #define PG8_WAIT_V(n) asm volatile("s_waitcnt vmcnt(" #n ")" ::: "memory")
; #define PG8_WAIT_L(n) asm volatile("s_waitcnt lgkmcnt(" #n ")" ::: "memory")
; #define PG8_BAR __builtin_amdgcn_s_barrier()
; #define PG8_SCHED __builtin_amdgcn_sched_barrier(0)
; template <class Epi, bool SPLITA = false>
; __device__ __forceinline__ void gemm_phase(const int tid, LAS unsigned char* lds, const Gemm g, const Order& S, const Epi& E) {
;     ...
;       PG8_STAGE(PG8_SB(0, 1), b2 + hstepB, voffB);
;       PG8_WAIT_V(6); PG8_BAR; PG8_MMA(1, 1, At, B1); PG8_BAR;
;       PG8_LDB(B0, 1, 0); PG8_SCHED; PG8_LDA(At, 1, 0); PG8_STAGE(PG8_SA(0, 1), a2 + hstepA, voffA);
;       PG8_WAIT_L(8); PG8_BAR; PG8_WAIT_L(0); PG8_MMA(0, 0, At, B0); PG8_BAR; PG8_SCHED;
;       PG8_LDB(B1, 1, 1); PG8_STAGE(PG8_SB(1, 0), b3, voffB);
;       PG8_BAR; PG8_WAIT_L(0); PG8_MMA(0, 1, At, B1); PG8_BAR;
;       PG8_LDA(At, 1, 1); PG8_STAGE(PG8_SA(1, 0), a3, voffA);
	s_add_u32 s20, s44, 0x80000
	s_addc_u32 s21, s45, 0
	s_add_i32 s8, s8, s2
	s_mov_b32 m0, s8
	s_nop 0
	global_load_lds_dwordx4 v0, s[20:21]
	s_add_i32 m0, s8, 0x2000
	s_nop 0
	global_load_lds_dwordx4 v162, s[20:21]
	s_waitcnt vmcnt(6)
	s_barrier
	s_setprio 1
	v_mfma_f32_16x16x32_bf16 v[62:65], v[220:223], v[142:145], v[62:65]
	v_mfma_f32_16x16x32_bf16 v[58:61], v[228:231], v[142:145], v[58:61]
	v_mfma_f32_16x16x32_bf16 v[46:49], v[220:223], v[184:187], v[46:49]
	v_mfma_f32_16x16x32_bf16 v[42:45], v[228:231], v[184:187], v[42:45]
	v_mfma_f32_16x16x32_bf16 v[38:41], v[220:223], v[212:215], v[38:41]
	v_mfma_f32_16x16x32_bf16 v[34:37], v[228:231], v[212:215], v[34:37]
	v_mfma_f32_16x16x32_bf16 v[78:81], v[220:223], v[134:137], v[110:113]
	v_mfma_f32_16x16x32_bf16 v[82:85], v[228:231], v[134:137], v[106:109]
	v_mfma_f32_16x16x32_bf16 v[62:65], v[224:227], v[172:175], v[62:65]
	v_mfma_f32_16x16x32_bf16 v[58:61], v[232:235], v[172:175], v[58:61]
	v_mfma_f32_16x16x32_bf16 v[46:49], v[224:227], v[188:191], v[46:49]
	v_mfma_f32_16x16x32_bf16 v[42:45], v[232:235], v[188:191], v[42:45]
	v_mfma_f32_16x16x32_bf16 v[38:41], v[224:227], v[216:219], v[38:41]
	v_mfma_f32_16x16x32_bf16 v[34:37], v[232:235], v[216:219], v[34:37]
	v_mfma_f32_16x16x32_bf16 v[78:81], v[224:227], v[138:141], v[78:81]
	v_mfma_f32_16x16x32_bf16 v[82:85], v[232:235], v[138:141], v[82:85]
	s_setprio 0
	s_add_i32 s8, 0, 0x18000
	v_add_u32_e32 v110, s8, v183
	s_barrier
	ds_read_b128 v[86:89], v110
	ds_read_b128 v[90:93], v110 offset:1024
	ds_read_b128 v[106:109], v110 offset:2048
	ds_read_b128 v[110:113], v110 offset:3072
	s_add_u32 s20, vcc_lo, 0x80000
	s_addc_u32 s21, vcc_hi, 0
	s_mov_b32 m0, s52
	ds_read_b128 v[134:137], v195 offset:32768
	ds_read_b128 v[138:141], v195 offset:33792
	ds_read_b128 v[142:145], v195 offset:34816
	ds_read_b128 v[172:175], v195 offset:35840
	ds_read_b128 v[184:187], v195 offset:36864
	ds_read_b128 v[188:191], v195 offset:37888
	ds_read_b128 v[212:215], v195 offset:38912
	ds_read_b128 v[216:219], v195 offset:39936
	global_load_lds_dwordx4 v166, s[20:21]
	s_mov_b32 m0, s53
	s_nop 0
	global_load_lds_dwordx4 v164, s[20:21]
	s_waitcnt lgkmcnt(8)
	s_barrier
	s_waitcnt lgkmcnt(0)
	s_setprio 1
	s_waitcnt lgkmcnt(0)
	v_mfma_f32_16x16x32_bf16 v[30:33], v[86:89], v[134:137], v[30:33]
	v_mfma_f32_16x16x32_bf16 v[26:29], v[106:109], v[134:137], v[26:29]
	v_mfma_f32_16x16x32_bf16 v[14:17], v[86:89], v[142:145], v[14:17]
	v_mfma_f32_16x16x32_bf16 v[10:13], v[106:109], v[142:145], v[10:13]
	v_mfma_f32_16x16x32_bf16 v[158:161], v[86:89], v[184:187], v[158:161]
	v_mfma_f32_16x16x32_bf16 v[154:157], v[106:109], v[184:187], v[154:157]
	v_mfma_f32_16x16x32_bf16 v[150:153], v[86:89], v[212:215], v[150:153]
	v_mfma_f32_16x16x32_bf16 v[146:149], v[106:109], v[212:215], v[146:149]
	v_mfma_f32_16x16x32_bf16 v[30:33], v[90:93], v[138:141], v[30:33]
	v_mfma_f32_16x16x32_bf16 v[26:29], v[110:113], v[138:141], v[26:29]
	v_mfma_f32_16x16x32_bf16 v[14:17], v[90:93], v[172:175], v[14:17]
	v_mfma_f32_16x16x32_bf16 v[10:13], v[110:113], v[172:175], v[10:13]
	v_mfma_f32_16x16x32_bf16 v[158:161], v[90:93], v[188:191], v[158:161]
	v_mfma_f32_16x16x32_bf16 v[154:157], v[110:113], v[188:191], v[154:157]
	v_mfma_f32_16x16x32_bf16 v[150:153], v[90:93], v[216:219], v[150:153]
	v_mfma_f32_16x16x32_bf16 v[146:149], v[110:113], v[216:219], v[146:149]
	s_setprio 0
	s_barrier
	s_add_i32 s9, 0, 0x1c000
	s_add_i32 s8, s8, s2
	v_add_u32_e32 v176, s9, v183
	s_add_i32 m0, s8, 0xffffff80
	ds_read_b128 v[220:223], v176
	ds_read_b128 v[224:227], v176 offset:1024
	ds_read_b128 v[228:231], v176 offset:2048
	ds_read_b128 v[232:235], v176 offset:3072
	global_load_lds_dwordx4 v0, s[44:45] offset:128
	s_add_i32 m0, s8, 0x1f80
	s_nop 0
	global_load_lds_dwordx4 v162, s[44:45] offset:128
	s_barrier
	s_waitcnt lgkmcnt(0)
	s_setprio 1
	s_waitcnt lgkmcnt(0)
	v_mfma_f32_16x16x32_bf16 v[94:97], v[220:223], v[184:187], v[94:97]
	v_mfma_f32_16x16x32_bf16 v[22:25], v[220:223], v[134:137], v[22:25]
	v_mfma_f32_16x16x32_bf16 v[18:21], v[228:231], v[134:137], v[18:21]
	v_mfma_f32_16x16x32_bf16 v[6:9], v[220:223], v[142:145], v[6:9]
	v_mfma_f32_16x16x32_bf16 v[2:5], v[228:231], v[142:145], v[2:5]
	v_mfma_f32_16x16x32_bf16 v[142:145], v[224:227], v[188:191], v[94:97]
	v_mfma_f32_16x16x32_bf16 v[94:97], v[228:231], v[184:187], v[98:101]
	v_mfma_f32_16x16x32_bf16 v[22:25], v[224:227], v[138:141], v[22:25]
	v_mfma_f32_16x16x32_bf16 v[18:21], v[232:235], v[138:141], v[18:21]
	v_mfma_f32_16x16x32_bf16 v[138:141], v[232:235], v[188:191], v[94:97]
	v_mfma_f32_16x16x32_bf16 v[94:97], v[220:223], v[212:215], v[102:105]
	v_mfma_f32_16x16x32_bf16 v[134:137], v[224:227], v[216:219], v[94:97]
	v_mfma_f32_16x16x32_bf16 v[94:97], v[228:231], v[212:215], v[130:133]
	v_mfma_f32_16x16x32_bf16 v[6:9], v[224:227], v[172:175], v[6:9]
	v_mfma_f32_16x16x32_bf16 v[2:5], v[232:235], v[172:175], v[2:5]
	v_mfma_f32_16x16x32_bf16 v[130:133], v[232:235], v[216:219], v[94:97]
	s_setprio 0
	s_mov_b32 m0, s55
	s_barrier
	s_nop 0
	ds_read_b128 v[94:97], v195 offset:49152
	ds_read_b128 v[98:101], v195 offset:50176
	ds_read_b128 v[102:105], v195 offset:51200
	ds_read_b128 v[172:175], v195 offset:52224
	ds_read_b128 v[184:187], v195 offset:53248
	ds_read_b128 v[188:191], v195 offset:54272
	ds_read_b128 v[212:215], v195 offset:55296
	ds_read_b128 v[216:219], v195 offset:56320
	global_load_lds_dwordx4 v166, s[46:47]
	s_mov_b32 m0, s93
	s_nop 0
	global_load_lds_dwordx4 v164, s[46:47]
	s_barrier
; #define PG8_STAGE(bufoff, gbase, voff) do { _Pragma("unroll") for (int _i = 0; _i < 2; ++_i) \
;     __builtin_amdgcn_global_load_lds((const unsigned*)((const char*)(gbase) + (voff)[_i]), (LAS unsigned*)(lds + (bufoff) + ldsw + _i * 8192), 16, 0, 0); } while (0)
; #define PG8_LDA(dst, b, h) do { _Pragma("unroll") for (int m = 0; m < 4; ++m) _Pragma("unroll") for (int k = 0; k < 2; ++k) dst[m][k] = *(const LAS bf16x8*)(lds + PG8_SA(b, h) + aoff + m * 2048 + k * 1024); } while (0)
; #define PG8_WAIT_V(n) asm volatile("s_waitcnt vmcnt(" #n ")" ::: "memory")
; #define PG8_WAIT_L(n) asm volatile("s_waitcnt lgkmcnt(" #n ")" ::: "memory")
; #define PG8_BAR __builtin_amdgcn_s_barrier()
; #define PG8_SCHED __builtin_amdgcn_sched_barrier(0)
; template <class Epi, bool SPLITA = false>
; __device__ __forceinline__ void gemm_phase(const int tid, LAS unsigned char* lds, const Gemm g, const Order& S, const Epi& E) {
;     ...
;       PG8_BAR; PG8_WAIT_L(0); PG8_MMA(0, 1, At, B1); PG8_BAR;
;       PG8_LDA(At, 1, 1); PG8_STAGE(PG8_SA(1, 0), a3, voffA);
;       PG8_BAR; PG8_WAIT_L(0); PG8_MMA(1, 0, At, B0); PG8_BAR; PG8_SCHED;
;       PG8_STAGE(PG8_SB(1, 1), b3 + hstepB, voffB);
;       PG8_WAIT_V(6); PG8_BAR; PG8_MMA(1, 1, At, B1); PG8_BAR;
;     }
;   __device__ __forceinline__ void operator()(Acc& acc, const Unit& u, int wr, int wc, int fr_, int fq_) const {
;     ...
;     const int ch0 = u.pn * 128 + wc * 32 + 8 * fq;
;     f32x4 w0[2], w1[2], w2[2], bb[2];
; #pragma unroll
;     for (int n = 0; n < 2; ++n) { w0[n] = *(const f32x4*)(wconv + ch0 + 4 * n); w1[n] = *(const f32x4*)(wconv + DFF + ch0 + 4 * n);
;       w2[n] = *(const f32x4*)(wconv + 2 * DFF + ch0 + 4 * n); bb[n] = *(const f32x4*)(bconv + ch0 + 4 * n); }
;     if (u.pm == 128) {
;       if (wr == 0) {
; #pragma unroll
;         for (int m = 0; m < 2; ++m) { const int rec = 1024 + m * 16 + fr; bf16_t* rp = EDGE + (size_t)rec * 3 * DFF + ch0;
;           f32x4 p0 = w1[0] * acc[0][0][m][0] + bb[0], p1 = w1[1] * acc[0][0][m][1] + bb[1];
;           *(u32x4*)(rp) = pack8(p0, p1); *(u32x4*)(rp + DFF) = pack8(acc[0][0][m][0], acc[0][0][m][1]); *(u32x4*)(rp + 2 * DFF) = pack8(acc[0][1][m][0], acc[0][1][m][1]); }
;       }
;       return;
;     }
; #pragma unroll
;     for (int ai = 0; ai < 2; ++ai)
; #pragma unroll
;       for (int m = 0; m < 4; ++m) { const float rstd = rss[u.pm * BM + ai * HALF + wr * 64 + m * 16 + fr];
	s_waitcnt lgkmcnt(0)
	s_setprio 1
	s_waitcnt lgkmcnt(0)
	v_mfma_f32_16x16x32_bf16 v[126:129], v[86:89], v[94:97], v[126:129]
	v_mfma_f32_16x16x32_bf16 v[122:125], v[106:109], v[94:97], v[122:125]
	v_mfma_f32_16x16x32_bf16 v[118:121], v[86:89], v[102:105], v[118:121]
	v_mfma_f32_16x16x32_bf16 v[114:117], v[106:109], v[102:105], v[114:117]
	v_mfma_f32_16x16x32_bf16 v[70:73], v[86:89], v[184:187], v[70:73]
	v_mfma_f32_16x16x32_bf16 v[66:69], v[106:109], v[184:187], v[66:69]
	v_mfma_f32_16x16x32_bf16 v[54:57], v[86:89], v[212:215], v[54:57]
	v_mfma_f32_16x16x32_bf16 v[50:53], v[106:109], v[212:215], v[50:53]
	v_mfma_f32_16x16x32_bf16 v[126:129], v[90:93], v[98:101], v[126:129]
	v_mfma_f32_16x16x32_bf16 v[122:125], v[110:113], v[98:101], v[122:125]
	v_mfma_f32_16x16x32_bf16 v[118:121], v[90:93], v[172:175], v[118:121]
	v_mfma_f32_16x16x32_bf16 v[114:117], v[110:113], v[172:175], v[114:117]
	v_mfma_f32_16x16x32_bf16 v[70:73], v[90:93], v[188:191], v[70:73]
	v_mfma_f32_16x16x32_bf16 v[66:69], v[110:113], v[188:191], v[66:69]
	v_mfma_f32_16x16x32_bf16 v[54:57], v[90:93], v[216:219], v[54:57]
	v_mfma_f32_16x16x32_bf16 v[50:53], v[110:113], v[216:219], v[50:53]
	s_setprio 0
	s_barrier
	s_add_u32 s20, s44, 0x80080
	s_addc_u32 s21, s45, 0
	s_add_i32 s8, s9, s2
	s_mov_b32 m0, s8
	s_nop 0
	global_load_lds_dwordx4 v0, s[20:21]
	s_add_i32 m0, s8, 0x2000
	s_nop 0
	global_load_lds_dwordx4 v162, s[20:21]
	s_waitcnt vmcnt(6)
	s_barrier
	s_setprio 1
	v_mfma_f32_16x16x32_bf16 v[78:81], v[220:223], v[94:97], v[78:81]
	v_mfma_f32_16x16x32_bf16 v[110:113], v[224:227], v[98:101], v[78:81]
	v_mfma_f32_16x16x32_bf16 v[78:81], v[228:231], v[94:97], v[82:85]
	v_mfma_f32_16x16x32_bf16 v[62:65], v[220:223], v[102:105], v[62:65]
	v_mfma_f32_16x16x32_bf16 v[58:61], v[228:231], v[102:105], v[58:61]
	v_mfma_f32_16x16x32_bf16 v[46:49], v[220:223], v[184:187], v[46:49]
	v_mfma_f32_16x16x32_bf16 v[42:45], v[228:231], v[184:187], v[42:45]
	v_mfma_f32_16x16x32_bf16 v[38:41], v[220:223], v[212:215], v[38:41]
	v_mfma_f32_16x16x32_bf16 v[34:37], v[228:231], v[212:215], v[34:37]
	v_mfma_f32_16x16x32_bf16 v[106:109], v[232:235], v[98:101], v[78:81]
	v_mfma_f32_16x16x32_bf16 v[62:65], v[224:227], v[172:175], v[62:65]
	v_mfma_f32_16x16x32_bf16 v[58:61], v[232:235], v[172:175], v[58:61]
	v_mfma_f32_16x16x32_bf16 v[46:49], v[224:227], v[188:191], v[46:49]
	v_mfma_f32_16x16x32_bf16 v[42:45], v[232:235], v[188:191], v[42:45]
	v_mfma_f32_16x16x32_bf16 v[38:41], v[224:227], v[216:219], v[38:41]
	v_mfma_f32_16x16x32_bf16 v[34:37], v[232:235], v[216:219], v[34:37]
	s_setprio 0
	s_add_i32 s29, s29, 2
	s_add_u32 s42, s42, 0x100
	s_addc_u32 s43, s43, 0
	s_cmp_gt_u32 s29, 29
	s_barrier
	s_cbranch_scc0 .LBB0_144
	s_lshl_b32 s3, s6, 7
	v_mov_b32_e32 v172, v179
	v_mov_b32_e32 v74, v177
	s_or_b32 s3, s3, s54
	s_cmpk_eq_i32 s90, 0x80
	v_lshl_add_u32 v174, v74, 3, s3
	v_ashrrev_i32_e32 v175, 31, v174
	v_lshlrev_b64 v[90:91], 2, v[174:175]
	v_lshl_add_u64 v[78:79], s[48:49], 0, v[90:91]
	v_lshl_add_u64 v[86:87], s[16:17], 0, v[90:91]
	global_load_dwordx4 v[74:77], v[78:79], off offset:16
	s_nop 0
	global_load_dwordx4 v[78:81], v[78:79], off
	s_nop 0
	global_load_dwordx4 v[82:85], v[86:87], off offset:16
	s_nop 0
	global_load_dwordx4 v[86:89], v[86:87], off
	s_mov_b64 s[6:7], -1
	s_movk_i32 s94, 0x1000
	v_mov_b32_e32 v219, v178
	s_cbranch_scc1 .LBB0_163
	v_readlane_b32 s6, v255, 40
	v_readlane_b32 s7, v255, 41
	s_lshl_b32 s3, s90, 8
	s_add_i32 s3, s3, s4
	v_lshl_add_u64 v[92:93], s[6:7], 0, v[90:91]
	v_readlane_b32 s6, v255, 45
	v_readlane_b32 s7, v255, 46
	v_add_u32_e32 v180, s3, v172
	v_ashrrev_i32_e32 v181, 31, v180
	v_lshl_add_u64 v[98:99], s[6:7], 0, v[90:91]
	v_readlane_b32 s6, v255, 36
	v_readlane_b32 s7, v255, 37
	global_load_dwordx4 v[94:97], v[92:93], off offset:16
	global_load_dwordx4 v[102:105], v[92:93], off
	s_nop 0
	global_load_dwordx4 v[90:93], v[98:99], off offset:16
	s_nop 0
	global_load_dwordx4 v[98:101], v[98:99], off
	v_lshl_add_u64 v[198:199], v[180:181], 2, s[6:7]
	global_load_dword v176, v[198:199], off
	global_load_dword v220, v[198:199], off offset:64
	s_ashr_i32 s91, s90, 31
	s_lshl_b64 s[6:7], s[90:91], 8
	s_add_u32 s6, s6, s4
	v_readlane_b32 s3, v255, 33
	s_addc_u32 s7, s7, s3
	v_ashrrev_i32_e32 v173, 31, v172
	v_lshl_add_u64 v[228:229], s[6:7], 0, v[172:173]
	v_mov_b32_e32 v173, v1
	v_cmp_eq_u32_e64 s[42:43], 0, v172
	v_mov_b32_e32 v181, v1
	v_cmp_eq_u32_e64 s[44:45], 15, v172
	v_cmp_ne_u32_e64 s[46:47], 0, v172
	v_cmp_ne_u32_e64 s[40:41], 15, v172
	s_waitcnt vmcnt(0)
; __device__ __forceinline__ float sigmoidf_(float v) { return __builtin_amdgcn_rcpf(1.f + __builtin_amdgcn_exp2f(v * -1.4426950408889634f)); }
; __device__ __forceinline__ float dpp_ror1(float v) { return __int_as_float(__builtin_amdgcn_update_dpp(0, __float_as_int(v), 0x121, 0xf, 0xf, false)); }
;   __device__ __forceinline__ void operator()(Acc& acc, const Unit& u, int wr, int wc, int fr_, int fq_) const {
;     ...
;     for (int ai = 0; ai < 2; ++ai)
; #pragma unroll
;       for (int m = 0; m < 4; ++m) { const float rstd = rss[u.pm * BM + ai * HALF + wr * 64 + m * 16 + fr];
; #pragma unroll
;         for (int bj = 0; bj < 2; ++bj)
; #pragma unroll
;           for (int n = 0; n < 2; ++n) acc[ai][bj][m][n] *= rstd; }
; #pragma unroll
;     for (int ai = 0; ai < 2; ++ai) {
;       const int strip = u.pm * 4 + ai * 2 + wr;
; #pragma unroll
;       for (int m = 0; m < 4; ++m) {
;         f32x4 uv[2];
; #pragma unroll
;         for (int n = 0; n < 2; ++n) {
;           const f32x4 cur = acc[ai][0][m][n]; f32x4 prev, next;
; #pragma unroll
;           for (int e = 0; e < 4; ++e) {
;             const float x = dpp_ror1(cur[e]), y = m > 0 ? dpp_ror1(acc[ai][0][m > 0 ? m - 1 : 0][n][e]) : 0.f;
;             prev[e] = fr == 0 ? y : x;
;             const float x2 = dpp_ror15(cur[e]), y2 = m < 3 ? dpp_ror15(acc[ai][0][m < 3 ? m + 1 : 3][n][e]) : 0.f;
;             next[e] = fr == 15 ? y2 : x2;
;           }
;           uv[n] = w0[n] * prev + w1[n] * cur + w2[n] * next + bb[n];
;         }
;         const bool first = (m == 0 && fr == 0), lastr = (m == 3 && fr == 15);
;         if (first || lastr) {
;           const int rec = strip * 2 + (lastr ? 1 : 0); bf16_t* rp = EDGE + (size_t)rec * 3 * DFF + ch0;
;           *(u32x4*)(rp) = pack8(uv[0], uv[1]); *(u32x4*)(rp + DFF) = pack8(acc[ai][0][m][0], acc[ai][0][m][1]); *(u32x4*)(rp + 2 * DFF) = pack8(acc[ai][1][m][0], acc[ai][1][m][1]);
;         } else {
;           f32x4 o0, o1;
; #pragma unroll
;           for (int e = 0; e < 4; ++e) { o0[e] = uv[0][e] * sigmoidf_(uv[0][e]) * acc[ai][1][m][0][e]; o1[e] = uv[1][e] * sigmoidf_(uv[1][e]) * acc[ai][1][m][1][e]; }
;           const size_t row = (size_t)u.pm * BM + ai * HALF + wr * 64 + m * 16 + fr;
;           *(u32x4*)(ACT + row * DFF + ch0) = pack8(o0, o1);
	v_pk_mul_f32 v[192:193], v[32:33], v[176:177] op_sel_hi:[1,0]
	v_pk_mul_f32 v[212:213], v[30:31], v[176:177] op_sel_hi:[1,0]
	v_pk_mul_f32 v[184:185], v[28:29], v[176:177] op_sel_hi:[1,0]
	v_pk_mul_f32 v[186:187], v[26:27], v[176:177] op_sel_hi:[1,0]
	v_pk_mul_f32 v[224:225], v[24:25], v[176:177] op_sel_hi:[1,0]
	v_pk_mul_f32 v[230:231], v[22:23], v[176:177] op_sel_hi:[1,0]
	v_pk_mul_f32 v[222:223], v[20:21], v[176:177] op_sel_hi:[1,0]
	v_pk_mul_f32 v[226:227], v[18:19], v[176:177] op_sel_hi:[1,0]
	global_load_dword v218, v[198:199], off offset:128
	global_load_dword v196, v[198:199], off offset:192
	global_load_dword v182, v[198:199], off offset:512
	global_load_dword v180, v[198:199], off offset:576
	global_load_dword v178, v[198:199], off offset:640
	global_load_dword v176, v[198:199], off offset:704
	v_mov_b32_dpp v173, v212 row_ror:1 row_mask:0xf bank_mask:0xf
	v_pk_mul_f32 v[216:217], v[14:15], v[220:221] op_sel_hi:[1,0]
	v_cndmask_b32_e64 v198, v173, 0, s[42:43]
	v_mov_b32_e32 v173, v1
	v_mov_b32_dpp v181, v216 row_ror:15 row_mask:0xf bank_mask:0xf
	v_pk_mul_f32 v[214:215], v[16:17], v[220:221] op_sel_hi:[1,0]
	v_mov_b32_dpp v173, v212 row_ror:15 row_mask:0xf bank_mask:0xf
	v_cndmask_b32_e64 v200, v173, v181, s[44:45]
	v_mov_b32_e32 v173, v1
	v_mov_b32_e32 v181, v1
	v_pk_mul_f32 v[190:191], v[10:11], v[220:221] op_sel_hi:[1,0]
	v_mov_b32_dpp v173, v213 row_ror:1 row_mask:0xf bank_mask:0xf
	v_cndmask_b32_e64 v199, v173, 0, s[42:43]
	v_mov_b32_e32 v173, v1
	v_mov_b32_dpp v181, v217 row_ror:15 row_mask:0xf bank_mask:0xf
	v_pk_mul_f32 v[198:199], v[102:103], v[198:199]
	v_mov_b32_dpp v173, v213 row_ror:15 row_mask:0xf bank_mask:0xf
	v_cndmask_b32_e64 v201, v173, v181, s[44:45]
	v_mov_b32_e32 v173, v1
	v_mov_b32_e32 v181, v1
	v_pk_fma_f32 v[198:199], v[78:79], v[212:213], v[198:199]
	v_mov_b32_dpp v173, v192 row_ror:1 row_mask:0xf bank_mask:0xf
	v_cndmask_b32_e64 v202, v173, 0, s[42:43]
	v_mov_b32_e32 v173, v1
	v_mov_b32_dpp v181, v214 row_ror:15 row_mask:0xf bank_mask:0xf
	v_pk_fma_f32 v[198:199], v[98:99], v[200:201], v[198:199]
	v_mov_b32_dpp v173, v192 row_ror:15 row_mask:0xf bank_mask:0xf
	v_cndmask_b32_e64 v204, v173, v181, s[44:45]
	v_mov_b32_e32 v173, v1
	v_mov_b32_e32 v181, v1
	v_pk_mul_f32 v[188:189], v[12:13], v[220:221] op_sel_hi:[1,0]
	v_mov_b32_dpp v173, v193 row_ror:1 row_mask:0xf bank_mask:0xf
	v_cndmask_b32_e64 v203, v173, 0, s[42:43]
	v_mov_b32_e32 v173, v1
	v_mov_b32_dpp v181, v215 row_ror:15 row_mask:0xf bank_mask:0xf
	v_pk_mul_f32 v[202:203], v[104:105], v[202:203]
	v_mov_b32_dpp v173, v193 row_ror:15 row_mask:0xf bank_mask:0xf
	v_cndmask_b32_e64 v205, v173, v181, s[44:45]
	v_mov_b32_e32 v173, v1
	v_mov_b32_e32 v181, v1
	v_pk_fma_f32 v[202:203], v[80:81], v[192:193], v[202:203]
	v_mov_b32_dpp v173, v186 row_ror:1 row_mask:0xf bank_mask:0xf
	v_cndmask_b32_e64 v236, v173, 0, s[42:43]
	v_mov_b32_e32 v173, v1
	v_mov_b32_dpp v181, v190 row_ror:15 row_mask:0xf bank_mask:0xf
	v_pk_add_f32 v[234:235], v[86:87], v[198:199]
	v_mov_b32_dpp v173, v186 row_ror:15 row_mask:0xf bank_mask:0xf
	v_cndmask_b32_e64 v238, v173, v181, s[44:45]
	v_mov_b32_e32 v173, v1
	v_mov_b32_e32 v181, v1
	v_pk_fma_f32 v[200:201], v[100:101], v[204:205], v[202:203]
	v_mov_b32_dpp v173, v187 row_ror:1 row_mask:0xf bank_mask:0xf
	v_cndmask_b32_e64 v237, v173, 0, s[42:43]
	v_mov_b32_e32 v173, v1
	v_mov_b32_dpp v181, v191 row_ror:15 row_mask:0xf bank_mask:0xf
	v_pk_add_f32 v[232:233], v[88:89], v[200:201]
	v_mov_b32_dpp v173, v187 row_ror:15 row_mask:0xf bank_mask:0xf
	v_cndmask_b32_e64 v239, v173, v181, s[44:45]
	v_mov_b32_e32 v173, v1
	v_mov_b32_e32 v181, v1
	v_pk_mul_f32 v[202:203], v[94:95], v[236:237]
	v_mov_b32_dpp v173, v184 row_ror:1 row_mask:0xf bank_mask:0xf
	v_cndmask_b32_e64 v198, v173, 0, s[42:43]
	v_mov_b32_e32 v173, v1
	v_mov_b32_dpp v181, v188 row_ror:15 row_mask:0xf bank_mask:0xf
	v_pk_fma_f32 v[202:203], v[74:75], v[186:187], v[202:203]
	v_mov_b32_dpp v173, v184 row_ror:15 row_mask:0xf bank_mask:0xf
	v_cndmask_b32_e64 v200, v173, v181, s[44:45]
	v_mov_b32_e32 v173, v1
	v_mov_b32_e32 v181, v1
	v_pk_fma_f32 v[202:203], v[90:91], v[238:239], v[202:203]
	v_mov_b32_dpp v173, v185 row_ror:1 row_mask:0xf bank_mask:0xf
	v_cndmask_b32_e64 v199, v173, 0, s[42:43]
	v_mov_b32_e32 v173, v1
	v_mov_b32_dpp v181, v189 row_ror:15 row_mask:0xf bank_mask:0xf
	v_pk_mul_f32 v[198:199], v[96:97], v[198:199]
	v_mov_b32_dpp v173, v185 row_ror:15 row_mask:0xf bank_mask:0xf
	v_cndmask_b32_e64 v201, v173, v181, s[44:45]
	v_pk_fma_f32 v[198:199], v[76:77], v[184:185], v[198:199]
	v_pk_add_f32 v[240:241], v[82:83], v[202:203]
	v_pk_fma_f32 v[198:199], v[92:93], v[200:201], v[198:199]
	s_nop 0
	v_pk_add_f32 v[238:239], v[84:85], v[198:199]
	s_and_saveexec_b64 s[6:7], s[46:47]
	s_xor_b64 vcc, exec, s[6:7]
	s_cbranch_execz .LBB0_148
	v_mul_f32_e32 v173, 0xbfb8aa3b, v234
	v_exp_f32_e32 v173, v173
	v_mad_u64_u32 v[236:237], s[6:7], v228, s24, 0
	v_mad_i32_i24 v237, v229, s24, v237
	v_add_f32_e32 v173, 1.0, v173
	v_rcp_f32_e32 v198, v173
	v_mul_f32_e32 v173, 0xbfb8aa3b, v240
	v_exp_f32_e32 v173, v173
	s_nop 0
	v_add_f32_e32 v173, 1.0, v173
	v_rcp_f32_e32 v200, v173
	v_mul_f32_e32 v173, 0xbfb8aa3b, v235
	v_exp_f32_e32 v173, v173
	s_nop 0
	v_add_f32_e32 v173, 1.0, v173
	v_rcp_f32_e32 v199, v173
	v_mul_f32_e32 v173, 0xbfb8aa3b, v241
	v_exp_f32_e32 v173, v173
	v_pk_mul_f32 v[198:199], v[234:235], v[198:199]
	s_nop 0
	v_pk_mul_f32 v[198:199], v[230:231], v[198:199]
	v_add_f32_e32 v173, 1.0, v173
	v_rcp_f32_e32 v201, v173
	v_mul_f32_e32 v173, 0xbfb8aa3b, v232
	v_exp_f32_e32 v173, v173
	v_pk_mul_f32 v[200:201], v[240:241], v[200:201]
	s_nop 0
	v_pk_mul_f32 v[200:201], v[226:227], v[200:201]
	v_add_f32_e32 v173, 1.0, v173
	v_rcp_f32_e32 v202, v173
	v_mul_f32_e32 v173, 0xbfb8aa3b, v238
	v_exp_f32_e32 v173, v173
	s_nop 0
	v_add_f32_e32 v173, 1.0, v173
	v_rcp_f32_e32 v204, v173
	v_mul_f32_e32 v173, 0xbfb8aa3b, v233
	v_exp_f32_e32 v173, v173
	s_nop 0
	v_add_f32_e32 v173, 1.0, v173
	v_rcp_f32_e32 v203, v173
	v_mul_f32_e32 v173, 0xbfb8aa3b, v239
	v_exp_f32_e32 v173, v173
	v_pk_mul_f32 v[202:203], v[232:233], v[202:203]
	s_nop 0
	v_pk_mul_f32 v[202:203], v[224:225], v[202:203]
	v_add_f32_e32 v173, 1.0, v173
	v_rcp_f32_e32 v205, v173
	v_cvt_pk_bf16_f32 v224, v200, v201
	v_pk_mul_f32 v[204:205], v[238:239], v[204:205]
	s_nop 0
	v_pk_mul_f32 v[204:205], v[222:223], v[204:205]
	v_cvt_pk_bf16_f32 v222, v198, v199
	v_mov_b64_e32 v[198:199], s[34:35]
	v_mad_u64_u32 v[198:199], s[6:7], v228, s24, v[198:199]
	v_mad_i32_i24 v199, v229, s24, v199
	v_cvt_pk_bf16_f32 v223, v202, v203
	v_cvt_pk_bf16_f32 v225, v204, v205
	v_lshl_add_u64 v[198:199], v[174:175], 1, v[198:199]
	global_store_dwordx4 v[198:199], v[222:225], off

; #define PG8_STAGE(bufoff, gbase, voff) do { _Pragma("unroll") for (int _i = 0; _i < 2; ++_i) \
;     __builtin_amdgcn_global_load_lds((const unsigned*)((const char*)(gbase) + (voff)[_i]), (LAS unsigned*)(lds + (bufoff) + ldsw + _i * 8192), 16, 0, 0); } while (0)
; #define PG8_WAIT_V(n) asm volatile("s_waitcnt vmcnt(" #n ")" ::: "memory")
; #define PG8_BAR __builtin_amdgcn_s_barrier()
; template <class Epi, bool SPLITA = false>
; __device__ __forceinline__ void gemm_phase(const int tid, LAS unsigned char* lds, const Gemm g, const Order& S, const Epi& E) {
;     ...
;   PG8_STAGE(PG8_SB(0, 0), cB, voffB); PG8_STAGE(PG8_SA(0, 0), cA, voffA); PG8_STAGE(PG8_SB(0, 1), cB + hstepB, voffB); PG8_STAGE(PG8_SA(0, 1), cA + hstepA, voffA);
;   if (wr == 1) PG8_BAR;
;   PG8_WAIT_V(4); PG8_BAR;
;   PG8_STAGE(PG8_SB(1, 0), cB + kstep, voffB); PG8_STAGE(PG8_SA(1, 0), cA + kstep, voffA); PG8_STAGE(PG8_SB(1, 1), cB + hstepB + kstep, voffB);
;   PG8_WAIT_V(6); PG8_BAR;
.LBB0_183:
	v_bfe_u32 v186, v210, 4, 2
	v_lshl_add_u64 v[8:9], s[42:43], 0, v[0:1]
	v_mov_b32_e32 v163, v1
	v_and_b32_e32 v187, 15, v210
	v_lshlrev_b32_e32 v16, 4, v186
	v_lshlrev_b32_e32 v17, 2, v210
	v_mov_b32_e32 v159, v1
	s_and_b32 s54, s2, 3
	v_lshl_or_b32 v16, v187, 6, v16
	s_lshl_b32 s2, s4, 13
	v_and_b32_e32 v17, 32, v17
	s_add_i32 m0, s23, 0x18000
	v_lshl_add_u64 v[8:9], v[8:9], 0, s[96:97]
	v_mov_b32_e32 v161, v1
	s_lshl_b32 s55, s4, 6
	v_bitop3_b32 v18, v16, s2, v17 bitop3:0xde
	s_lshl_b32 s90, s54, 5
	s_lshl_b32 s2, s54, 12
	s_waitcnt vmcnt(4)
	s_barrier
	global_load_lds_dwordx4 v[8:9], off
	s_add_i32 m0, s23, 0x19f80
	s_add_i32 s91, s23, 0x8000
	s_add_i32 s93, s23, 0xa000
	global_load_lds_dwordx4 v162, s[42:43] offset:128
	s_add_i32 m0, s91, 0xffffff80
	s_add_u32 s6, s42, 0x80080
	global_load_lds_dwordx4 v158, s[40:41] offset:128
	s_add_i32 m0, s93, 0xffffff80
	s_addc_u32 s7, s43, 0
	global_load_lds_dwordx4 v160, s[40:41] offset:128
	s_add_i32 m0, s23, 0x1c000
	s_nop 0
	global_load_lds_dwordx4 v0, s[6:7]
	v_lshl_add_u64 v[8:9], s[6:7], 0, v[162:163]
	s_add_i32 m0, s23, 0x1e000
	v_bitop3_b32 v188, v16, s2, v17 bitop3:0xde
	global_load_lds_dwordx4 v162, s[6:7]
	v_lshlrev_b32_e32 v8, 15, v2
	v_and_b32_e32 v8, 0xffff0000, v8
	v_lshl_add_u32 v3, v3, 12, v8
	v_and_b32_e32 v2, 1, v2
	v_lshl_or_b32 v2, v2, 6, v3
	v_lshl_add_u32 v164, v4, 1, v2
	v_lshlrev_b32_e32 v2, 15, v5
	v_and_b32_e32 v2, 0xffff0000, v2
	s_waitcnt vmcnt(6)
	v_lshl_add_u32 v2, v6, 12, v2
	v_and_b32_e32 v3, 1, v5
	v_lshl_or_b32 v2, v3, 6, v2
	s_ashr_i32 s2, s92, 31
	v_mov_b32_e32 v165, v1
	v_lshl_add_u32 v166, v7, 1, v2
	v_mov_b32_e32 v167, v1
	s_mov_b32 s28, 0
	v_add_u32_e32 v189, 0, v18
	s_barrier
	s_branch .LBB0_185

; #define PG8_STAGE(bufoff, gbase, voff) do { _Pragma("unroll") for (int _i = 0; _i < 2; ++_i) \
;     __builtin_amdgcn_global_load_lds((const unsigned*)((const char*)(gbase) + (voff)[_i]), (LAS unsigned*)(lds + (bufoff) + ldsw + _i * 8192), 16, 0, 0); } while (0)
; #define PG8_LDA(dst, b, h) do { _Pragma("unroll") for (int m = 0; m < 4; ++m) _Pragma("unroll") for (int k = 0; k < 2; ++k) dst[m][k] = *(const LAS bf16x8*)(lds + PG8_SA(b, h) + aoff + m * 2048 + k * 1024); } while (0)
; #define PG8_LDB(dst, b, h) do { _Pragma("unroll") for (int n = 0; n < 2; ++n) _Pragma("unroll") for (int k = 0; k < 2; ++k) dst[n][k] = *(const LAS bf16x8*)(lds + PG8_SB(b, h) + boff + n * 2048 + k * 1024); } while (0)
; #define PG8_WAIT_L(n) asm volatile("s_waitcnt lgkmcnt(" #n ")" ::: "memory")
; #define PG8_BAR __builtin_amdgcn_s_barrier()
; #define PG8_SCHED __builtin_amdgcn_sched_barrier(0)
; template <class Epi, bool SPLITA = false>
; __device__ __forceinline__ void gemm_phase(const int tid, LAS unsigned char* lds, const Gemm g, const Order& S, const Epi& E) {
;     ...
;     const bool has_next = S.next(ui + 1, nxt);
;     const char* nA = has_next ? (const char*)g.A + (size_t)nxt.pm * tstepA + (size_t)nxt.pn * apn : cA; const char* nA2 = (SPLITA && has_next) ? (const char*)g.A2 + (size_t)nxt.pm * tstepA : cA2; const char* nB = has_next ? (const char*)g.Bt + (size_t)nxt.pn * tstepB : cB;
;     for (int t = 0; t < nt; t += 2) {
;       const bool last = (t == nt - 2);
;       if constexpr (SPLITA) { if (t == nt1) E.mid(acc, cur, wr, wc, fr, fq); }
;       const char* a1 = PG8_TA(t + 1);
;       const char* a2 = last ? nA : PG8_TA(t + 2); const char* b2 = last ? nB : cB + (size_t)(t + 2) * kstep;
;       const char* a3 = last ? nA + kstep : PG8_TA(t + 3); const char* b3 = b2 + kstep;
;       PG8_LDB(B0, 0, 0); PG8_SCHED; PG8_LDA(At, 0, 0); PG8_STAGE(PG8_SA(1, 1), a1 + hstepA, voffA);
;       PG8_WAIT_L(8); PG8_BAR; PG8_WAIT_L(0); PG8_MMA(0, 0, At, B0); PG8_BAR; PG8_SCHED;
;       PG8_LDB(B1, 0, 1); PG8_STAGE(PG8_SB(0, 0), b2, voffB);
;       PG8_BAR; PG8_WAIT_L(0); PG8_MMA(0, 1, At, B1); PG8_BAR;
;       PG8_LDA(At, 0, 1); PG8_STAGE(PG8_SA(0, 0), a2, voffA);
;       PG8_BAR; PG8_WAIT_L(0); PG8_MMA(1, 0, At, B0); PG8_BAR; PG8_SCHED;
.LBB0_192:
	s_add_u32 s20, s40, s42
	s_addc_u32 s21, s41, s43
	s_add_u32 s48, s20, 0x100
	s_addc_u32 s49, s21, 0
	s_add_u32 s44, vcc_lo, s42
	s_addc_u32 s45, vcc_hi, s43
	s_add_u32 s20, s20, 0x180
	s_addc_u32 s21, s21, 0
	s_add_i32 s94, 0, 0x10000
	v_add_u32_e32 v146, s94, v188
	ds_read_b128 v[134:137], v146
	ds_read_b128 v[138:141], v146 offset:1024
	ds_read_b128 v[142:145], v146 offset:2048
	ds_read_b128 v[146:149], v146 offset:3072
	s_cmpk_eq_i32 s42, 0xf00
	s_cselect_b32 s47, s19, s21
	s_cselect_b32 s46, s13, s20
	s_cselect_b32 s45, s7, s45
	s_cselect_b32 s44, s11, s44
	s_cselect_b32 s49, s4, s49
	s_cselect_b32 s48, s6, s48
	v_lshl_add_u64 v[184:185], v[130:131], 0, s[42:43]
	s_add_i32 m0, s23, 0xc000
	ds_read_b128 v[150:153], v189
	ds_read_b128 v[154:157], v189 offset:1024
	ds_read_b128 v[168:171], v189 offset:2048
	ds_read_b128 v[172:175], v189 offset:3072
	ds_read_b128 v[176:179], v189 offset:4096
	ds_read_b128 v[180:183], v189 offset:5120
	ds_read_b128 v[190:193], v189 offset:6144
	ds_read_b128 v[212:215], v189 offset:7168
	global_load_lds_dwordx4 v[184:185], off
	v_lshl_add_u64 v[184:185], v[132:133], 0, s[42:43]
	s_add_i32 m0, s23, 0xe000
	s_nop 0
	global_load_lds_dwordx4 v[184:185], off
	s_waitcnt lgkmcnt(8)
	s_barrier
	s_waitcnt lgkmcnt(0)
	s_setprio 1
	s_waitcnt lgkmcnt(0)
	v_mfma_f32_16x16x32_bf16 v[126:129], v[134:137], v[150:153], v[126:129]
	v_mfma_f32_16x16x32_bf16 v[122:125], v[142:145], v[150:153], v[122:125]
	v_mfma_f32_16x16x32_bf16 v[110:113], v[134:137], v[168:171], v[110:113]
	v_mfma_f32_16x16x32_bf16 v[106:109], v[142:145], v[168:171], v[106:109]
	v_mfma_f32_16x16x32_bf16 v[94:97], v[134:137], v[176:179], v[94:97]
	v_mfma_f32_16x16x32_bf16 v[90:93], v[142:145], v[176:179], v[90:93]
	v_mfma_f32_16x16x32_bf16 v[78:81], v[134:137], v[190:193], v[78:81]
	v_mfma_f32_16x16x32_bf16 v[74:77], v[142:145], v[190:193], v[74:77]
	v_mfma_f32_16x16x32_bf16 v[126:129], v[138:141], v[154:157], v[126:129]
	v_mfma_f32_16x16x32_bf16 v[122:125], v[146:149], v[154:157], v[122:125]
	v_mfma_f32_16x16x32_bf16 v[110:113], v[138:141], v[172:175], v[110:113]
	v_mfma_f32_16x16x32_bf16 v[106:109], v[146:149], v[172:175], v[106:109]
	v_mfma_f32_16x16x32_bf16 v[94:97], v[138:141], v[180:183], v[94:97]
	v_mfma_f32_16x16x32_bf16 v[90:93], v[146:149], v[180:183], v[90:93]
	v_mfma_f32_16x16x32_bf16 v[78:81], v[138:141], v[212:215], v[78:81]
	v_mfma_f32_16x16x32_bf16 v[74:77], v[146:149], v[212:215], v[74:77]
	s_setprio 0
	s_barrier
	s_add_i32 s8, 0, 0x14000
	v_add_u32_e32 v184, s8, v188
	s_add_i32 s9, s94, s3
	ds_read_b128 v[216:219], v184
	ds_read_b128 v[220:223], v184 offset:1024
	ds_read_b128 v[224:227], v184 offset:2048
	ds_read_b128 v[228:231], v184 offset:3072
	s_mov_b32 m0, s9
	s_nop 0
	global_load_lds_dwordx4 v0, s[44:45]
	s_add_i32 m0, s9, 0x2000
	s_nop 0
	global_load_lds_dwordx4 v162, s[44:45]
	s_barrier
	s_waitcnt lgkmcnt(0)
	s_setprio 1
	s_waitcnt lgkmcnt(0)
	v_mfma_f32_16x16x32_bf16 v[118:121], v[216:219], v[150:153], v[118:121]
	v_mfma_f32_16x16x32_bf16 v[114:117], v[224:227], v[150:153], v[114:117]
	v_mfma_f32_16x16x32_bf16 v[102:105], v[216:219], v[168:171], v[102:105]
	v_mfma_f32_16x16x32_bf16 v[98:101], v[224:227], v[168:171], v[98:101]
	v_mfma_f32_16x16x32_bf16 v[86:89], v[216:219], v[176:179], v[86:89]
	v_mfma_f32_16x16x32_bf16 v[82:85], v[224:227], v[176:179], v[82:85]
	v_mfma_f32_16x16x32_bf16 v[70:73], v[216:219], v[190:193], v[70:73]
	v_mfma_f32_16x16x32_bf16 v[66:69], v[224:227], v[190:193], v[66:69]
	v_mfma_f32_16x16x32_bf16 v[118:121], v[220:223], v[154:157], v[118:121]
	v_mfma_f32_16x16x32_bf16 v[114:117], v[228:231], v[154:157], v[114:117]
	v_mfma_f32_16x16x32_bf16 v[102:105], v[220:223], v[172:175], v[102:105]
	v_mfma_f32_16x16x32_bf16 v[98:101], v[228:231], v[172:175], v[98:101]
	v_mfma_f32_16x16x32_bf16 v[86:89], v[220:223], v[180:183], v[86:89]
	v_mfma_f32_16x16x32_bf16 v[82:85], v[228:231], v[180:183], v[82:85]
	v_mfma_f32_16x16x32_bf16 v[70:73], v[220:223], v[212:215], v[70:73]
	v_mfma_f32_16x16x32_bf16 v[66:69], v[228:231], v[212:215], v[66:69]
	s_setprio 0
	s_mov_b32 m0, s23
	s_barrier
	ds_read_b128 v[150:153], v189 offset:16384
	ds_read_b128 v[154:157], v189 offset:17408
	ds_read_b128 v[168:171], v189 offset:18432
	ds_read_b128 v[172:175], v189 offset:19456
	ds_read_b128 v[176:179], v189 offset:20480
	ds_read_b128 v[180:183], v189 offset:21504
	ds_read_b128 v[190:193], v189 offset:22528
	ds_read_b128 v[212:215], v189 offset:23552
	global_load_lds_dwordx4 v158, s[48:49]
	s_mov_b32 m0, s51
	s_nop 0
	global_load_lds_dwordx4 v160, s[48:49]
	s_barrier
	s_waitcnt lgkmcnt(0)
	s_setprio 1
	s_waitcnt lgkmcnt(0)
	v_mfma_f32_16x16x32_bf16 v[62:65], v[134:137], v[150:153], v[62:65]
	v_mfma_f32_16x16x32_bf16 v[58:61], v[142:145], v[150:153], v[58:61]
	v_mfma_f32_16x16x32_bf16 v[46:49], v[134:137], v[168:171], v[46:49]
	v_mfma_f32_16x16x32_bf16 v[42:45], v[142:145], v[168:171], v[42:45]
	v_mfma_f32_16x16x32_bf16 v[30:33], v[134:137], v[176:179], v[30:33]
	v_mfma_f32_16x16x32_bf16 v[26:29], v[142:145], v[176:179], v[26:29]
	v_mfma_f32_16x16x32_bf16 v[14:17], v[134:137], v[190:193], v[14:17]
	v_mfma_f32_16x16x32_bf16 v[10:13], v[142:145], v[190:193], v[10:13]
	v_mfma_f32_16x16x32_bf16 v[62:65], v[138:141], v[154:157], v[62:65]
	v_mfma_f32_16x16x32_bf16 v[58:61], v[146:149], v[154:157], v[58:61]
	v_mfma_f32_16x16x32_bf16 v[46:49], v[138:141], v[172:175], v[46:49]
	v_mfma_f32_16x16x32_bf16 v[42:45], v[146:149], v[172:175], v[42:45]
	v_mfma_f32_16x16x32_bf16 v[30:33], v[138:141], v[180:183], v[30:33]
	v_mfma_f32_16x16x32_bf16 v[26:29], v[146:149], v[180:183], v[26:29]
	v_mfma_f32_16x16x32_bf16 v[14:17], v[138:141], v[212:215], v[14:17]
	v_mfma_f32_16x16x32_bf16 v[10:13], v[146:149], v[212:215], v[10:13]
	s_setprio 0
	s_barrier
; #define PG8_STAGE(bufoff, gbase, voff) do { _Pragma("unroll") for (int _i = 0; _i < 2; ++_i) \
;     __builtin_amdgcn_global_load_lds((const unsigned*)((const char*)(gbase) + (voff)[_i]), (LAS unsigned*)(lds + (bufoff) + ldsw + _i * 8192), 16, 0, 0); } while (0)
; #define PG8_LDA(dst, b, h) do { _Pragma("unroll") for (int m = 0; m < 4; ++m) _Pragma("unroll") for (int k = 0; k < 2; ++k) dst[m][k] = *(const LAS bf16x8*)(lds + PG8_SA(b, h) + aoff + m * 2048 + k * 1024); } while (0)
; #define PG8_LDB(dst, b, h) do { _Pragma("unroll") for (int n = 0; n < 2; ++n) _Pragma("unroll") for (int k = 0; k < 2; ++k) dst[n][k] = *(const LAS bf16x8*)(lds + PG8_SB(b, h) + boff + n * 2048 + k * 1024); } while (0)
; #define PG8_MMA(ai, bj, At, Bt) do { __builtin_amdgcn_s_setprio(1); _Pragma("unroll") for (int m = 0; m < 4; ++m) _Pragma("unroll") for (int n = 0; n < 2; ++n) _Pragma("unroll") for (int k = 0; k < 2; ++k) \
;     acc[ai][bj][m][n] = __builtin_amdgcn_mfma_f32_16x16x32_bf16(Bt[n][k], At[m][k], acc[ai][bj][m][n], 0, 0, 0); __builtin_amdgcn_s_setprio(0); } while (0)
; #define PG8_WAIT_V(n) asm volatile("s_waitcnt vmcnt(" #n ")" ::: "memory")
; #define PG8_WAIT_L(n) asm volatile("s_waitcnt lgkmcnt(" #n ")" ::: "memory")
; #define PG8_BAR __builtin_amdgcn_s_barrier()
; #define PG8_SCHED __builtin_amdgcn_sched_barrier(0)
; template <class Epi, bool SPLITA = false>
; __device__ __forceinline__ void gemm_phase(const int tid, LAS unsigned char* lds, const Gemm g, const Order& S, const Epi& E) {
;     ...
;       PG8_STAGE(PG8_SB(0, 1), b2 + hstepB, voffB);
;       PG8_WAIT_V(6); PG8_BAR; PG8_MMA(1, 1, At, B1); PG8_BAR;
;       PG8_LDB(B0, 1, 0); PG8_SCHED; PG8_LDA(At, 1, 0); PG8_STAGE(PG8_SA(0, 1), a2 + hstepA, voffA);
;       PG8_WAIT_L(8); PG8_BAR; PG8_WAIT_L(0); PG8_MMA(0, 0, At, B0); PG8_BAR; PG8_SCHED;
;       PG8_LDB(B1, 1, 1); PG8_STAGE(PG8_SB(1, 0), b3, voffB);
;       PG8_BAR; PG8_WAIT_L(0); PG8_MMA(0, 1, At, B1); PG8_BAR;
;       PG8_LDA(At, 1, 1); PG8_STAGE(PG8_SA(1, 0), a3, voffA);
	s_add_u32 s20, s44, 0x80000
	s_addc_u32 s21, s45, 0
	s_add_i32 s8, s8, s3
	s_mov_b32 m0, s8
	s_nop 0
	global_load_lds_dwordx4 v0, s[20:21]
	s_add_i32 m0, s8, 0x2000
	s_nop 0
	global_load_lds_dwordx4 v162, s[20:21]
	s_waitcnt vmcnt(6)
	s_barrier
	s_setprio 1
	v_mfma_f32_16x16x32_bf16 v[54:57], v[216:219], v[150:153], v[54:57]
	v_mfma_f32_16x16x32_bf16 v[50:53], v[224:227], v[150:153], v[50:53]
	v_mfma_f32_16x16x32_bf16 v[38:41], v[216:219], v[168:171], v[38:41]
	v_mfma_f32_16x16x32_bf16 v[34:37], v[224:227], v[168:171], v[34:37]
	v_mfma_f32_16x16x32_bf16 v[22:25], v[216:219], v[176:179], v[22:25]
	v_mfma_f32_16x16x32_bf16 v[18:21], v[224:227], v[176:179], v[18:21]
	v_mfma_f32_16x16x32_bf16 v[6:9], v[216:219], v[190:193], v[6:9]
	v_mfma_f32_16x16x32_bf16 v[2:5], v[224:227], v[190:193], v[2:5]
	v_mfma_f32_16x16x32_bf16 v[54:57], v[220:223], v[154:157], v[54:57]
	v_mfma_f32_16x16x32_bf16 v[50:53], v[228:231], v[154:157], v[50:53]
	v_mfma_f32_16x16x32_bf16 v[38:41], v[220:223], v[172:175], v[38:41]
	v_mfma_f32_16x16x32_bf16 v[34:37], v[228:231], v[172:175], v[34:37]
	v_mfma_f32_16x16x32_bf16 v[22:25], v[220:223], v[180:183], v[22:25]
	v_mfma_f32_16x16x32_bf16 v[18:21], v[228:231], v[180:183], v[18:21]
	v_mfma_f32_16x16x32_bf16 v[6:9], v[220:223], v[212:215], v[6:9]
	v_mfma_f32_16x16x32_bf16 v[2:5], v[228:231], v[212:215], v[2:5]
	s_setprio 0
	s_add_i32 s8, 0, 0x18000
	v_add_u32_e32 v146, s8, v188
	s_barrier
	ds_read_b128 v[134:137], v146
	ds_read_b128 v[138:141], v146 offset:1024
	ds_read_b128 v[142:145], v146 offset:2048
	ds_read_b128 v[146:149], v146 offset:3072
	s_add_u32 s20, s48, 0x80000
	s_addc_u32 s21, s49, 0
	s_mov_b32 m0, s52
	ds_read_b128 v[150:153], v189 offset:32768
	ds_read_b128 v[154:157], v189 offset:33792
	ds_read_b128 v[168:171], v189 offset:34816
	ds_read_b128 v[172:175], v189 offset:35840
	ds_read_b128 v[176:179], v189 offset:36864
	ds_read_b128 v[180:183], v189 offset:37888
	ds_read_b128 v[190:193], v189 offset:38912
	ds_read_b128 v[212:215], v189 offset:39936
	global_load_lds_dwordx4 v158, s[20:21]
	s_mov_b32 m0, s53
	s_nop 0
	global_load_lds_dwordx4 v160, s[20:21]
	s_waitcnt lgkmcnt(8)
	s_barrier
	s_waitcnt lgkmcnt(0)
	s_setprio 1
	s_waitcnt lgkmcnt(0)
	v_mfma_f32_16x16x32_bf16 v[126:129], v[134:137], v[150:153], v[126:129]
	v_mfma_f32_16x16x32_bf16 v[122:125], v[142:145], v[150:153], v[122:125]
	v_mfma_f32_16x16x32_bf16 v[110:113], v[134:137], v[168:171], v[110:113]
	v_mfma_f32_16x16x32_bf16 v[106:109], v[142:145], v[168:171], v[106:109]
	v_mfma_f32_16x16x32_bf16 v[94:97], v[134:137], v[176:179], v[94:97]
	v_mfma_f32_16x16x32_bf16 v[90:93], v[142:145], v[176:179], v[90:93]
	v_mfma_f32_16x16x32_bf16 v[78:81], v[134:137], v[190:193], v[78:81]
	v_mfma_f32_16x16x32_bf16 v[74:77], v[142:145], v[190:193], v[74:77]
	v_mfma_f32_16x16x32_bf16 v[126:129], v[138:141], v[154:157], v[126:129]
	v_mfma_f32_16x16x32_bf16 v[122:125], v[146:149], v[154:157], v[122:125]
	v_mfma_f32_16x16x32_bf16 v[110:113], v[138:141], v[172:175], v[110:113]
	v_mfma_f32_16x16x32_bf16 v[106:109], v[146:149], v[172:175], v[106:109]
	v_mfma_f32_16x16x32_bf16 v[94:97], v[138:141], v[180:183], v[94:97]
	v_mfma_f32_16x16x32_bf16 v[90:93], v[146:149], v[180:183], v[90:93]
	v_mfma_f32_16x16x32_bf16 v[78:81], v[138:141], v[212:215], v[78:81]
	v_mfma_f32_16x16x32_bf16 v[74:77], v[146:149], v[212:215], v[74:77]
	s_setprio 0
	s_barrier
	s_add_i32 s9, 0, 0x1c000
	s_add_i32 s8, s8, s3
	v_add_u32_e32 v195, s9, v188
	s_add_i32 m0, s8, 0xffffff80
	ds_read_b128 v[216:219], v195
	ds_read_b128 v[220:223], v195 offset:1024
	ds_read_b128 v[224:227], v195 offset:2048
	ds_read_b128 v[228:231], v195 offset:3072
	global_load_lds_dwordx4 v0, s[44:45] offset:128
	s_add_i32 m0, s8, 0x1f80
	s_nop 0
	global_load_lds_dwordx4 v162, s[44:45] offset:128
	s_barrier
	s_waitcnt lgkmcnt(0)
	s_setprio 1
	s_waitcnt lgkmcnt(0)
	v_mfma_f32_16x16x32_bf16 v[118:121], v[216:219], v[150:153], v[118:121]
	v_mfma_f32_16x16x32_bf16 v[114:117], v[224:227], v[150:153], v[114:117]
	v_mfma_f32_16x16x32_bf16 v[102:105], v[216:219], v[168:171], v[102:105]
	v_mfma_f32_16x16x32_bf16 v[98:101], v[224:227], v[168:171], v[98:101]
	v_mfma_f32_16x16x32_bf16 v[86:89], v[216:219], v[176:179], v[86:89]
	v_mfma_f32_16x16x32_bf16 v[82:85], v[224:227], v[176:179], v[82:85]
	v_mfma_f32_16x16x32_bf16 v[70:73], v[216:219], v[190:193], v[70:73]
	v_mfma_f32_16x16x32_bf16 v[66:69], v[224:227], v[190:193], v[66:69]
	v_mfma_f32_16x16x32_bf16 v[118:121], v[220:223], v[154:157], v[118:121]
	v_mfma_f32_16x16x32_bf16 v[114:117], v[228:231], v[154:157], v[114:117]
	v_mfma_f32_16x16x32_bf16 v[102:105], v[220:223], v[172:175], v[102:105]
	v_mfma_f32_16x16x32_bf16 v[98:101], v[228:231], v[172:175], v[98:101]
	v_mfma_f32_16x16x32_bf16 v[86:89], v[220:223], v[180:183], v[86:89]
	v_mfma_f32_16x16x32_bf16 v[82:85], v[228:231], v[180:183], v[82:85]
	v_mfma_f32_16x16x32_bf16 v[70:73], v[220:223], v[212:215], v[70:73]
	v_mfma_f32_16x16x32_bf16 v[66:69], v[228:231], v[212:215], v[66:69]
	s_setprio 0
	s_mov_b32 m0, s91
	s_barrier
	ds_read_b128 v[150:153], v189 offset:49152
	ds_read_b128 v[154:157], v189 offset:50176
	ds_read_b128 v[168:171], v189 offset:51200
	ds_read_b128 v[172:175], v189 offset:52224
	ds_read_b128 v[176:179], v189 offset:53248
	ds_read_b128 v[180:183], v189 offset:54272
	ds_read_b128 v[190:193], v189 offset:55296
	ds_read_b128 v[212:215], v189 offset:56320
	global_load_lds_dwordx4 v158, s[46:47]
	s_mov_b32 m0, s93
	s_nop 0
	global_load_lds_dwordx4 v160, s[46:47]
	s_barrier
; #define PG8_STAGE(bufoff, gbase, voff) do { _Pragma("unroll") for (int _i = 0; _i < 2; ++_i) \
;     __builtin_amdgcn_global_load_lds((const unsigned*)((const char*)(gbase) + (voff)[_i]), (LAS unsigned*)(lds + (bufoff) + ldsw + _i * 8192), 16, 0, 0); } while (0)
; #define PG8_LDA(dst, b, h) do { _Pragma("unroll") for (int m = 0; m < 4; ++m) _Pragma("unroll") for (int k = 0; k < 2; ++k) dst[m][k] = *(const LAS bf16x8*)(lds + PG8_SA(b, h) + aoff + m * 2048 + k * 1024); } while (0)
; #define PG8_MMA(ai, bj, At, Bt) do { __builtin_amdgcn_s_setprio(1); _Pragma("unroll") for (int m = 0; m < 4; ++m) _Pragma("unroll") for (int n = 0; n < 2; ++n) _Pragma("unroll") for (int k = 0; k < 2; ++k) \
;     acc[ai][bj][m][n] = __builtin_amdgcn_mfma_f32_16x16x32_bf16(Bt[n][k], At[m][k], acc[ai][bj][m][n], 0, 0, 0); __builtin_amdgcn_s_setprio(0); } while (0)
; #define PG8_WAIT_V(n) asm volatile("s_waitcnt vmcnt(" #n ")" ::: "memory")
; #define PG8_WAIT_L(n) asm volatile("s_waitcnt lgkmcnt(" #n ")" ::: "memory")
; #define PG8_BAR __builtin_amdgcn_s_barrier()
; #define PG8_SCHED __builtin_amdgcn_sched_barrier(0)
; template <class Epi, bool SPLITA = false>
; __device__ __forceinline__ void gemm_phase(const int tid, LAS unsigned char* lds, const Gemm g, const Order& S, const Epi& E) {
;     ...
;       PG8_BAR; PG8_WAIT_L(0); PG8_MMA(0, 1, At, B1); PG8_BAR;
;       PG8_LDA(At, 1, 1); PG8_STAGE(PG8_SA(1, 0), a3, voffA);
;       PG8_BAR; PG8_WAIT_L(0); PG8_MMA(1, 0, At, B0); PG8_BAR; PG8_SCHED;
;       PG8_STAGE(PG8_SB(1, 1), b3 + hstepB, voffB);
;       PG8_WAIT_V(6); PG8_BAR; PG8_MMA(1, 1, At, B1); PG8_BAR;
;     }
	s_waitcnt lgkmcnt(0)
	s_setprio 1
	s_waitcnt lgkmcnt(0)
	v_mfma_f32_16x16x32_bf16 v[62:65], v[134:137], v[150:153], v[62:65]
	v_mfma_f32_16x16x32_bf16 v[58:61], v[142:145], v[150:153], v[58:61]
	v_mfma_f32_16x16x32_bf16 v[46:49], v[134:137], v[168:171], v[46:49]
	v_mfma_f32_16x16x32_bf16 v[42:45], v[142:145], v[168:171], v[42:45]
	v_mfma_f32_16x16x32_bf16 v[30:33], v[134:137], v[176:179], v[30:33]
	v_mfma_f32_16x16x32_bf16 v[26:29], v[142:145], v[176:179], v[26:29]
	v_mfma_f32_16x16x32_bf16 v[14:17], v[134:137], v[190:193], v[14:17]
	v_mfma_f32_16x16x32_bf16 v[10:13], v[142:145], v[190:193], v[10:13]
	v_mfma_f32_16x16x32_bf16 v[62:65], v[138:141], v[154:157], v[62:65]
	v_mfma_f32_16x16x32_bf16 v[58:61], v[146:149], v[154:157], v[58:61]
	v_mfma_f32_16x16x32_bf16 v[46:49], v[138:141], v[172:175], v[46:49]
	v_mfma_f32_16x16x32_bf16 v[42:45], v[146:149], v[172:175], v[42:45]
	v_mfma_f32_16x16x32_bf16 v[30:33], v[138:141], v[180:183], v[30:33]
	v_mfma_f32_16x16x32_bf16 v[26:29], v[146:149], v[180:183], v[26:29]
	v_mfma_f32_16x16x32_bf16 v[14:17], v[138:141], v[212:215], v[14:17]
	v_mfma_f32_16x16x32_bf16 v[10:13], v[146:149], v[212:215], v[10:13]
	s_setprio 0
	s_barrier
	s_add_u32 s20, s44, 0x80080
	s_addc_u32 s21, s45, 0
	s_add_i32 s8, s9, s3
	s_mov_b32 m0, s8
	s_nop 0
	global_load_lds_dwordx4 v0, s[20:21]
	s_add_i32 m0, s8, 0x2000
	s_nop 0
	global_load_lds_dwordx4 v162, s[20:21]
	s_waitcnt vmcnt(6)
	s_barrier
	s_setprio 1
	v_mfma_f32_16x16x32_bf16 v[54:57], v[216:219], v[150:153], v[54:57]
	v_mfma_f32_16x16x32_bf16 v[50:53], v[224:227], v[150:153], v[50:53]
	v_mfma_f32_16x16x32_bf16 v[38:41], v[216:219], v[168:171], v[38:41]
	v_mfma_f32_16x16x32_bf16 v[34:37], v[224:227], v[168:171], v[34:37]
	v_mfma_f32_16x16x32_bf16 v[22:25], v[216:219], v[176:179], v[22:25]
	v_mfma_f32_16x16x32_bf16 v[18:21], v[224:227], v[176:179], v[18:21]
	v_mfma_f32_16x16x32_bf16 v[6:9], v[216:219], v[190:193], v[6:9]
	v_mfma_f32_16x16x32_bf16 v[2:5], v[224:227], v[190:193], v[2:5]
	v_mfma_f32_16x16x32_bf16 v[54:57], v[220:223], v[154:157], v[54:57]
	v_mfma_f32_16x16x32_bf16 v[50:53], v[228:231], v[154:157], v[50:53]
	v_mfma_f32_16x16x32_bf16 v[38:41], v[220:223], v[172:175], v[38:41]
	v_mfma_f32_16x16x32_bf16 v[34:37], v[228:231], v[172:175], v[34:37]
	v_mfma_f32_16x16x32_bf16 v[22:25], v[220:223], v[180:183], v[22:25]
	v_mfma_f32_16x16x32_bf16 v[18:21], v[228:231], v[180:183], v[18:21]
	v_mfma_f32_16x16x32_bf16 v[6:9], v[220:223], v[212:215], v[6:9]
	v_mfma_f32_16x16x32_bf16 v[2:5], v[228:231], v[212:215], v[2:5]
	s_setprio 0
	s_add_i32 s29, s29, 2
	s_add_u32 s42, s42, 0x100
	s_addc_u32 s43, s43, 0
	s_cmp_gt_u32 s29, 29
	s_barrier
	s_cbranch_scc0 .LBB0_192
; __device__ __forceinline__ float bflo(unsigned w) { return __uint_as_float(w << 16); }
; __device__ __forceinline__ float bfhi(unsigned w) { return __uint_as_float(w & 0xffff0000u); }
; __device__ __forceinline__ float lane_read(float v, int src) { return __int_as_float(__builtin_amdgcn_ds_bpermute(src << 2, __float_as_int(v))); }
; __device__ __forceinline__ u32x4 pack8(const f32x4 v0, const f32x4 v1) { u32x4 w; w.x = cvtpk(v0[0], v0[1]); w.y = cvtpk(v0[2], v0[3]); w.z = cvtpk(v1[0], v1[1]); w.w = cvtpk(v1[2], v1[3]); return w; }
;   __device__ __forceinline__ void operator()(const Acc& acc, const Unit& u, int wr, int wc, int fr_, int fq_) const {
;     int fr = fr_, fq = fq_; asm volatile("" : "+v"(fr), "+v"(fq));
;     const int lane = fq * 16 + fr;
;     const int row0 = u.pm * BM + wr * 64 + fr, col0 = u.pn * BM + wc * 32 + 8 * fq;
; #pragma unroll
;     for (int ai = 0; ai < 2; ++ai) {
;       u32x4 hv[4][2];
; #pragma unroll
;       for (int m = 0; m < 4; ++m)
; #pragma unroll
;         for (int bj = 0; bj < 2; ++bj) hv[m][bj] = *(const u32x4*)(rin + (size_t)(row0 + ai * HALF + m * 16) * DM + col0 + bj * HALF);
; #pragma unroll
;       for (int m = 0; m < 4; ++m) { const size_t ro = (size_t)(row0 + ai * HALF + m * 16) * DM + col0; float ss = 0.f;
; #pragma unroll
;         for (int bj = 0; bj < 2; ++bj) { const u32x4 h = hv[m][bj];
;           f32x4 v0 = acc[ai][bj][m][0], v1 = acc[ai][bj][m][1];
;           v0[0] += bflo(h.x); v0[1] += bfhi(h.x); v0[2] += bflo(h.y); v0[3] += bfhi(h.y);
;           v1[0] += bflo(h.z); v1[1] += bfhi(h.z); v1[2] += bflo(h.w); v1[3] += bfhi(h.w);
;           if (FINAL) { *(f32x4*)(outf + ro + bj * HALF) = v0; *(f32x4*)(outf + ro + bj * HALF + 4) = v1; }
;           else { ss += v0[0] * v0[0] + v0[1] * v0[1] + v0[2] * v0[2] + v0[3] * v0[3] + v1[0] * v1[0] + v1[1] * v1[1] + v1[2] * v1[2] + v1[3] * v1[3];
;             *(u32x4*)(outb + ro + bj * HALF) = pack8(v0, v1); } }
;         if (!FINAL) { ss += lane_read(ss, lane ^ 16); ss += lane_read(ss, lane ^ 32);
;           if (fq == 0) rss[(size_t)(row0 + ai * HALF + m * 16) * 32 + u.pn * 4 + wc] = ss; } }
	s_lshl_b32 s4, s22, 8
	v_mov_b32_e32 v130, v187
	v_mov_b32_e32 v131, v186
	s_add_i32 s4, s4, s55
	s_nop 0
	v_add_u32_e32 v170, s4, v130
	s_lshl_b32 s4, s18, 8
	s_or_b32 s4, s4, s90
	v_lshl_add_u32 v168, v131, 3, s4
	v_ashrrev_i32_e32 v169, 31, v168
	v_lshlrev_b32_e32 v130, 2, v130
	v_lshlrev_b64 v[192:193], 1, v[168:169]
	v_ashrrev_i32_e32 v171, 31, v170
	v_lshl_add_u32 v130, v131, 6, v130
	v_lshl_add_u64 v[172:173], s[86:87], 0, v[192:193]
	v_lshlrev_b64 v[198:199], 12, v[170:171]
	v_xor_b32_e32 v191, 64, v130
	v_xor_b32_e32 v190, 0x80, v130
	v_cmp_eq_u32_e32 vcc, 0, v131
	v_lshl_add_u64 v[130:131], v[172:173], 0, v[198:199]
	global_load_dwordx4 v[212:215], v[130:131], off
	global_load_dwordx4 v[154:157], v[130:131], off offset:256
	v_add_u32_e32 v182, 16, v170
	v_ashrrev_i32_e32 v183, 31, v182
	v_add_u32_e32 v178, 32, v170
	v_lshlrev_b64 v[184:185], 12, v[182:183]
	v_ashrrev_i32_e32 v179, 31, v178
	v_add_u32_e32 v174, 48, v170
	v_lshl_add_u64 v[130:131], v[172:173], 0, v[184:185]
	v_lshlrev_b64 v[180:181], 12, v[178:179]
	v_ashrrev_i32_e32 v175, 31, v174
	global_load_dwordx4 v[150:153], v[130:131], off
	global_load_dwordx4 v[146:149], v[130:131], off offset:256
	v_lshl_add_u64 v[130:131], v[172:173], 0, v[180:181]
	v_lshlrev_b64 v[176:177], 12, v[174:175]
	global_load_dwordx4 v[142:145], v[130:131], off
	global_load_dwordx4 v[138:141], v[130:131], off offset:256
	v_lshl_add_u64 v[130:131], v[172:173], 0, v[176:177]
	global_load_dwordx4 v[134:137], v[130:131], off
	s_nop 0
	global_load_dwordx4 v[130:133], v[130:131], off offset:256
	s_lshl_b32 s18, s18, 2
	s_ashr_i32 s19, s18, 31
	s_waitcnt vmcnt(0)
	v_lshlrev_b32_e32 v200, 16, v212
	v_and_b32_e32 v201, 0xffff0000, v212
	v_pk_add_f32 v[126:127], v[126:127], v[200:201]
	v_lshlrev_b32_e32 v200, 16, v213
	v_and_b32_e32 v201, 0xffff0000, v213
	v_pk_add_f32 v[128:129], v[128:129], v[200:201]
	v_lshlrev_b32_e32 v200, 16, v214
	v_and_b32_e32 v201, 0xffff0000, v214
	v_pk_add_f32 v[200:201], v[122:123], v[200:201]
	v_lshlrev_b32_e32 v122, 16, v215
	v_and_b32_e32 v123, 0xffff0000, v215
	v_pk_add_f32 v[202:203], v[124:125], v[122:123]
	v_pk_mul_f32 v[204:205], v[126:127], v[126:127]
	v_cvt_pk_bf16_f32 v122, v126, v127
	v_lshl_add_u64 v[126:127], s[0:1], 0, v[198:199]
	v_cvt_pk_bf16_f32 v123, v128, v129
	v_cvt_pk_bf16_f32 v124, v200, v201
	v_cvt_pk_bf16_f32 v125, v202, v203
	v_lshl_add_u64 v[126:127], v[126:127], 0, v[192:193]
	global_store_dwordx4 v[126:127], v[122:125], off
	v_pk_mul_f32 v[206:207], v[128:129], v[128:129]
	v_pk_mul_f32 v[212:213], v[200:201], v[200:201]
	v_lshlrev_b32_e32 v122, 16, v154
	v_and_b32_e32 v123, 0xffff0000, v154
	v_pk_add_f32 v[118:119], v[118:119], v[122:123]
	v_lshlrev_b32_e32 v122, 16, v155
	v_and_b32_e32 v123, 0xffff0000, v155
	v_pk_add_f32 v[120:121], v[120:121], v[122:123]
	v_lshlrev_b32_e32 v122, 16, v156
	v_and_b32_e32 v123, 0xffff0000, v156
	v_pk_add_f32 v[122:123], v[114:115], v[122:123]
	v_lshlrev_b32_e32 v114, 16, v157
	v_and_b32_e32 v115, 0xffff0000, v157
	v_pk_add_f32 v[124:125], v[116:117], v[114:115]
	v_pk_mul_f32 v[114:115], v[118:119], v[118:119]
	v_pk_mul_f32 v[116:117], v[120:121], v[120:121]
	v_add_f32_e32 v114, v114, v115
	v_add_f32_e32 v115, v204, v205
	v_add_f32_e32 v114, v116, v114
	v_add_f32_e32 v115, v206, v115
	v_pk_mul_f32 v[128:129], v[122:123], v[122:123]
	v_add_f32_e32 v114, v117, v114
	v_add_f32_e32 v115, v207, v115
	v_add_f32_e32 v114, v128, v114
	v_add_f32_e32 v115, v212, v115
	v_pk_mul_f32 v[214:215], v[202:203], v[202:203]
	v_pk_mul_f32 v[154:155], v[124:125], v[124:125]
	v_add_f32_e32 v114, v129, v114
	v_add_f32_e32 v115, v213, v115
	v_add_f32_e32 v114, v154, v114
	v_add_f32_e32 v115, v214, v115
	v_add_f32_e32 v114, v155, v114
	v_add_f32_e32 v115, v215, v115
	v_add_f32_e32 v128, v115, v114
	v_cvt_pk_bf16_f32 v114, v118, v119
	v_cvt_pk_bf16_f32 v115, v120, v121
	v_cvt_pk_bf16_f32 v116, v122, v123
	v_cvt_pk_bf16_f32 v117, v124, v125
	global_store_dwordx4 v[126:127], v[114:117], off offset:256
	ds_bpermute_b32 v114, v191, v128
	s_waitcnt lgkmcnt(0)
	v_add_f32_e32 v114, v128, v114
	ds_bpermute_b32 v115, v190, v114
	s_and_saveexec_b64 s[6:7], vcc
	s_cbranch_execz .LBB0_195
	v_readlane_b32 s8, v255, 1
	v_lshlrev_b64 v[116:117], 7, v[170:171]
	v_readlane_b32 s9, v255, 2
	s_lshl_b32 s4, s54, 2
	s_waitcnt lgkmcnt(0)
	v_add_f32_e32 v114, v114, v115
	v_lshl_add_u64 v[116:117], s[8:9], 0, v[116:117]
	v_lshl_add_u64 v[116:117], s[18:19], 2, v[116:117]
	v_lshl_add_u64 v[116:117], v[116:117], 0, s[4:5]
	global_store_dword v[116:117], v114, off

; #define PG8_STAGE(bufoff, gbase, voff) do { _Pragma("unroll") for (int _i = 0; _i < 2; ++_i) \
;     __builtin_amdgcn_global_load_lds((const unsigned*)((const char*)(gbase) + (voff)[_i]), (LAS unsigned*)(lds + (bufoff) + ldsw + _i * 8192), 16, 0, 0); } while (0)
; #define PG8_WAIT_V(n) asm volatile("s_waitcnt vmcnt(" #n ")" ::: "memory")
; #define PG8_BAR __builtin_amdgcn_s_barrier()
; template <class Epi, bool SPLITA = false>
; __device__ __forceinline__ void gemm_phase(const int tid, LAS unsigned char* lds, const Gemm g, const Order& S, const Epi& E) {
;     ...
;   const char* cA2 = SPLITA ? (const char*)g.A2 + (size_t)cur.pm * tstepA : cA; const int nt1 = SPLITA ? g.nt1 : nt;
;     ...
;   PG8_STAGE(PG8_SB(0, 0), cB, voffB); PG8_STAGE(PG8_SA(0, 0), cA, voffA); PG8_STAGE(PG8_SB(0, 1), cB + hstepB, voffB); PG8_STAGE(PG8_SA(0, 1), cA + hstepA, voffA);
;   if (wr == 1) PG8_BAR;
;   PG8_WAIT_V(4); PG8_BAR;
;   PG8_STAGE(PG8_SB(1, 0), cB + kstep, voffB); PG8_STAGE(PG8_SA(1, 0), cA + kstep, voffA); PG8_STAGE(PG8_SB(1, 1), cB + hstepB + kstep, voffB);
;   PG8_WAIT_V(6); PG8_BAR;
.LBB0_228:
	v_lshl_add_u64 v[2:3], s[40:41], 0, v[0:1]
	v_mov_b32_e32 v213, v1
	v_bfe_u32 v195, v210, 4, 2
	s_lshl_b32 s6, s1, 6
	s_lshl_b32 s0, s0, 5
	v_mov_b32_e32 v217, v1
	v_and_b32_e32 v196, 15, v210
	v_writelane_b32 v255, s6, 36
	v_lshlrev_b32_e32 v10, 4, v195
	v_lshlrev_b32_e32 v11, 2, v210
	s_and_b32 s0, s0, 0x60
	s_add_i32 m0, s51, 0x18000
	v_lshl_add_u64 v[2:3], v[2:3], 0, s[96:97]
	v_mov_b32_e32 v215, v1
	s_and_b32 s3, 0xffff, s3
	v_lshl_or_b32 v10, v196, 6, v10
	s_lshl_b32 s1, s1, 13
	v_and_b32_e32 v11, 32, v11
	v_writelane_b32 v255, s0, 38
	s_lshl_b32 s0, s0, 7
	s_waitcnt vmcnt(4)
	s_barrier
	global_load_lds_dwordx4 v[2:3], off
	s_add_i32 m0, s51, 0x19f80
	s_add_i32 s47, s51, 0x8000
	s_add_i32 s38, s51, 0xa000
	v_bitop3_b32 v209, s0, v10, v11 bitop3:0xf6
	global_load_lds_dwordx4 v212, s[40:41] offset:128
	s_add_i32 m0, s47, 0xffffff80
	s_add_u32 s0, s40, 0x80080
	v_bitop3_b32 v12, v10, s1, v11 bitop3:0xde
	global_load_lds_dwordx4 v216, s[14:15] offset:128
	s_add_i32 m0, s38, 0xffffff80
	s_addc_u32 s1, s41, 0
	global_load_lds_dwordx4 v214, s[14:15] offset:128
	s_add_i32 m0, s51, 0x1c000
	s_nop 0
	global_load_lds_dwordx4 v0, s[0:1]
	v_lshl_add_u64 v[2:3], s[0:1], 0, v[212:213]
	s_add_i32 m0, s51, 0x1e000
	s_ashr_i32 s0, s92, 31
	global_load_lds_dwordx4 v[2:3], off
	s_waitcnt vmcnt(6)
	v_writelane_b32 v255, s0, 40
	s_mov_b32 s39, 0
	v_add_u32_e32 v211, 0, v12
	s_mov_b64 s[0:1], s[4:5]
	s_barrier
	s_branch .LBB0_230

; #define PG8_STAGE(bufoff, gbase, voff) do { _Pragma("unroll") for (int _i = 0; _i < 2; ++_i) \
;     __builtin_amdgcn_global_load_lds((const unsigned*)((const char*)(gbase) + (voff)[_i]), (LAS unsigned*)(lds + (bufoff) + ldsw + _i * 8192), 16, 0, 0); } while (0)
; #define PG8_LDA(dst, b, h) do { _Pragma("unroll") for (int m = 0; m < 4; ++m) _Pragma("unroll") for (int k = 0; k < 2; ++k) dst[m][k] = *(const LAS bf16x8*)(lds + PG8_SA(b, h) + aoff + m * 2048 + k * 1024); } while (0)
; #define PG8_LDB(dst, b, h) do { _Pragma("unroll") for (int n = 0; n < 2; ++n) _Pragma("unroll") for (int k = 0; k < 2; ++k) dst[n][k] = *(const LAS bf16x8*)(lds + PG8_SB(b, h) + boff + n * 2048 + k * 1024); } while (0)
; #define PG8_WAIT_L(n) asm volatile("s_waitcnt lgkmcnt(" #n ")" ::: "memory")
; #define PG8_BAR __builtin_amdgcn_s_barrier()
; #define PG8_SCHED __builtin_amdgcn_sched_barrier(0)
; template <class Epi, bool SPLITA = false>
; __device__ __forceinline__ void gemm_phase(const int tid, LAS unsigned char* lds, const Gemm g, const Order& S, const Epi& E) {
;     ...
;     const bool has_next = S.next(ui + 1, nxt);
;     const char* nA = has_next ? (const char*)g.A + (size_t)nxt.pm * tstepA + (size_t)nxt.pn * apn : cA; const char* nA2 = (SPLITA && has_next) ? (const char*)g.A2 + (size_t)nxt.pm * tstepA : cA2; const char* nB = has_next ? (const char*)g.Bt + (size_t)nxt.pn * tstepB : cB;
;     for (int t = 0; t < nt; t += 2) {
;       const bool last = (t == nt - 2);
;       if constexpr (SPLITA) { if (t == nt1) E.mid(acc, cur, wr, wc, fr, fq); }
;       const char* a1 = PG8_TA(t + 1);
;       const char* a2 = last ? nA : PG8_TA(t + 2); const char* b2 = last ? nB : cB + (size_t)(t + 2) * kstep;
;       const char* a3 = last ? nA + kstep : PG8_TA(t + 3); const char* b3 = b2 + kstep;
;       PG8_LDB(B0, 0, 0); PG8_SCHED; PG8_LDA(At, 0, 0); PG8_STAGE(PG8_SA(1, 1), a1 + hstepA, voffA);
;       PG8_WAIT_L(8); PG8_BAR; PG8_WAIT_L(0); PG8_MMA(0, 0, At, B0); PG8_BAR; PG8_SCHED;
;       PG8_LDB(B1, 0, 1); PG8_STAGE(PG8_SB(0, 0), b2, voffB);
;       PG8_BAR; PG8_WAIT_L(0); PG8_MMA(0, 1, At, B1); PG8_BAR;
;       PG8_LDA(At, 0, 1); PG8_STAGE(PG8_SA(0, 0), a2, voffA);
;       PG8_BAR; PG8_WAIT_L(0); PG8_MMA(1, 0, At, B0); PG8_BAR; PG8_SCHED;
.LBB0_237:
	s_add_u32 s3, s52, s40
	s_addc_u32 s4, s53, s41
	s_and_b64 s[22:23], exec, s[48:49]
	s_cselect_b32 s49, s30, s4
	s_cselect_b32 s48, s31, s3
	s_cmp_lt_u32 s2, 16
	s_cselect_b64 s[22:23], -1, 0
	s_and_b64 s[28:29], s[22:23], exec
	s_cselect_b32 s3, 0, -16
	s_add_i32 s3, s3, s2
	s_add_i32 s4, s3, 1
	s_and_b64 s[22:23], s[22:23], exec
	s_cselect_b32 s3, s15, s55
	s_cselect_b32 s20, s14, s54
	s_lshl_b64 s[22:23], s[4:5], 7
	s_add_u32 s4, s20, s22
	s_addc_u32 s20, s3, s23
	s_add_i32 s21, 0, 0x10000
	v_add_u32_e32 v142, s21, v209
	ds_read_b128 v[130:133], v142
	ds_read_b128 v[134:137], v142 offset:1024
	ds_read_b128 v[138:141], v142 offset:2048
	ds_read_b128 v[142:145], v142 offset:3072
	s_add_i32 s3, s2, 2
	s_add_u32 s22, s4, 0x40000
	s_addc_u32 s23, s20, 0
	s_add_i32 m0, s51, 0xc000
	ds_read_b128 v[146:149], v211
	ds_read_b128 v[150:153], v211 offset:1024
	ds_read_b128 v[154:157], v211 offset:2048
	ds_read_b128 v[158:161], v211 offset:3072
	ds_read_b128 v[162:165], v211 offset:4096
	ds_read_b128 v[166:169], v211 offset:5120
	ds_read_b128 v[170:173], v211 offset:6144
	ds_read_b128 v[174:177], v211 offset:7168
	global_load_lds_dwordx4 v216, s[22:23]
	s_add_i32 m0, s51, 0xe000
	s_nop 0
	global_load_lds_dwordx4 v214, s[22:23]
	s_waitcnt lgkmcnt(8)
	s_barrier
	s_waitcnt lgkmcnt(0)
	s_setprio 1
	s_waitcnt lgkmcnt(0)
	v_mfma_f32_16x16x32_bf16 v[126:129], v[130:133], v[146:149], v[126:129]
	v_mfma_f32_16x16x32_bf16 v[122:125], v[138:141], v[146:149], v[122:125]
	v_mfma_f32_16x16x32_bf16 v[110:113], v[130:133], v[154:157], v[110:113]
	v_mfma_f32_16x16x32_bf16 v[106:109], v[138:141], v[154:157], v[106:109]
	v_mfma_f32_16x16x32_bf16 v[94:97], v[130:133], v[162:165], v[94:97]
	v_mfma_f32_16x16x32_bf16 v[90:93], v[138:141], v[162:165], v[90:93]
	v_mfma_f32_16x16x32_bf16 v[78:81], v[130:133], v[170:173], v[78:81]
	v_mfma_f32_16x16x32_bf16 v[74:77], v[138:141], v[170:173], v[74:77]
	v_mfma_f32_16x16x32_bf16 v[126:129], v[134:137], v[150:153], v[126:129]
	v_mfma_f32_16x16x32_bf16 v[122:125], v[142:145], v[150:153], v[122:125]
	v_mfma_f32_16x16x32_bf16 v[110:113], v[134:137], v[158:161], v[110:113]
	v_mfma_f32_16x16x32_bf16 v[106:109], v[142:145], v[158:161], v[106:109]
	v_mfma_f32_16x16x32_bf16 v[94:97], v[134:137], v[166:169], v[94:97]
	v_mfma_f32_16x16x32_bf16 v[90:93], v[142:145], v[166:169], v[90:93]
	v_mfma_f32_16x16x32_bf16 v[78:81], v[134:137], v[174:177], v[78:81]
	v_mfma_f32_16x16x32_bf16 v[74:77], v[142:145], v[174:177], v[74:77]
	s_setprio 0
	s_barrier
	s_add_i32 s4, 0, 0x14000
	s_add_i32 s20, s21, s93
	v_add_u32_e32 v190, s4, v209
	s_mov_b32 m0, s20
	ds_read_b128 v[178:181], v190
	ds_read_b128 v[182:185], v190 offset:1024
	ds_read_b128 v[186:189], v190 offset:2048
	ds_read_b128 v[190:193], v190 offset:3072
	global_load_lds_dwordx4 v0, s[48:49]
	s_add_i32 m0, s20, 0x2000
	s_nop 0
	global_load_lds_dwordx4 v212, s[48:49]
	s_barrier
	s_waitcnt lgkmcnt(0)
	s_setprio 1
	s_waitcnt lgkmcnt(0)
	v_mfma_f32_16x16x32_bf16 v[118:121], v[178:181], v[146:149], v[118:121]
	v_mfma_f32_16x16x32_bf16 v[114:117], v[186:189], v[146:149], v[114:117]
	v_mfma_f32_16x16x32_bf16 v[102:105], v[178:181], v[154:157], v[102:105]
	v_mfma_f32_16x16x32_bf16 v[98:101], v[186:189], v[154:157], v[98:101]
	v_mfma_f32_16x16x32_bf16 v[86:89], v[178:181], v[162:165], v[86:89]
	v_mfma_f32_16x16x32_bf16 v[82:85], v[186:189], v[162:165], v[82:85]
	v_mfma_f32_16x16x32_bf16 v[70:73], v[178:181], v[170:173], v[70:73]
	v_mfma_f32_16x16x32_bf16 v[66:69], v[186:189], v[170:173], v[66:69]
	v_mfma_f32_16x16x32_bf16 v[118:121], v[182:185], v[150:153], v[118:121]
	v_mfma_f32_16x16x32_bf16 v[114:117], v[190:193], v[150:153], v[114:117]
	v_mfma_f32_16x16x32_bf16 v[102:105], v[182:185], v[158:161], v[102:105]
	v_mfma_f32_16x16x32_bf16 v[98:101], v[190:193], v[158:161], v[98:101]
	v_mfma_f32_16x16x32_bf16 v[86:89], v[182:185], v[166:169], v[86:89]
	v_mfma_f32_16x16x32_bf16 v[82:85], v[190:193], v[166:169], v[82:85]
	v_mfma_f32_16x16x32_bf16 v[70:73], v[182:185], v[174:177], v[70:73]
	v_mfma_f32_16x16x32_bf16 v[66:69], v[190:193], v[174:177], v[66:69]
	s_setprio 0
	s_mov_b32 m0, s51
	s_barrier
	ds_read_b128 v[146:149], v211 offset:16384
	ds_read_b128 v[150:153], v211 offset:17408
	ds_read_b128 v[154:157], v211 offset:18432
	ds_read_b128 v[158:161], v211 offset:19456
	ds_read_b128 v[162:165], v211 offset:20480
	ds_read_b128 v[166:169], v211 offset:21504
	ds_read_b128 v[170:173], v211 offset:22528
	ds_read_b128 v[174:177], v211 offset:23552
	global_load_lds_dwordx4 v216, s[90:91]
	s_mov_b32 m0, s44
	s_nop 0
	global_load_lds_dwordx4 v214, s[90:91]
	s_barrier
	s_waitcnt lgkmcnt(0)
	s_setprio 1
	s_waitcnt lgkmcnt(0)
	v_mfma_f32_16x16x32_bf16 v[62:65], v[130:133], v[146:149], v[62:65]
	v_mfma_f32_16x16x32_bf16 v[58:61], v[138:141], v[146:149], v[58:61]
	v_mfma_f32_16x16x32_bf16 v[46:49], v[130:133], v[154:157], v[46:49]
	v_mfma_f32_16x16x32_bf16 v[42:45], v[138:141], v[154:157], v[42:45]
	v_mfma_f32_16x16x32_bf16 v[30:33], v[130:133], v[162:165], v[30:33]
	v_mfma_f32_16x16x32_bf16 v[26:29], v[138:141], v[162:165], v[26:29]
	v_mfma_f32_16x16x32_bf16 v[14:17], v[130:133], v[170:173], v[14:17]
	v_mfma_f32_16x16x32_bf16 v[10:13], v[138:141], v[170:173], v[10:13]
	v_mfma_f32_16x16x32_bf16 v[62:65], v[134:137], v[150:153], v[62:65]
	v_mfma_f32_16x16x32_bf16 v[58:61], v[142:145], v[150:153], v[58:61]
	v_mfma_f32_16x16x32_bf16 v[46:49], v[134:137], v[158:161], v[46:49]
	v_mfma_f32_16x16x32_bf16 v[42:45], v[142:145], v[158:161], v[42:45]
	v_mfma_f32_16x16x32_bf16 v[30:33], v[134:137], v[166:169], v[30:33]
	v_mfma_f32_16x16x32_bf16 v[26:29], v[142:145], v[166:169], v[26:29]
	v_mfma_f32_16x16x32_bf16 v[14:17], v[134:137], v[174:177], v[14:17]
	v_mfma_f32_16x16x32_bf16 v[10:13], v[142:145], v[174:177], v[10:13]
	s_setprio 0
	s_barrier
; #define PG8_STAGE(bufoff, gbase, voff) do { _Pragma("unroll") for (int _i = 0; _i < 2; ++_i) \
;     __builtin_amdgcn_global_load_lds((const unsigned*)((const char*)(gbase) + (voff)[_i]), (LAS unsigned*)(lds + (bufoff) + ldsw + _i * 8192), 16, 0, 0); } while (0)
; #define PG8_LDA(dst, b, h) do { _Pragma("unroll") for (int m = 0; m < 4; ++m) _Pragma("unroll") for (int k = 0; k < 2; ++k) dst[m][k] = *(const LAS bf16x8*)(lds + PG8_SA(b, h) + aoff + m * 2048 + k * 1024); } while (0)
; #define PG8_LDB(dst, b, h) do { _Pragma("unroll") for (int n = 0; n < 2; ++n) _Pragma("unroll") for (int k = 0; k < 2; ++k) dst[n][k] = *(const LAS bf16x8*)(lds + PG8_SB(b, h) + boff + n * 2048 + k * 1024); } while (0)
; #define PG8_MMA(ai, bj, At, Bt) do { __builtin_amdgcn_s_setprio(1); _Pragma("unroll") for (int m = 0; m < 4; ++m) _Pragma("unroll") for (int n = 0; n < 2; ++n) _Pragma("unroll") for (int k = 0; k < 2; ++k) \
;     acc[ai][bj][m][n] = __builtin_amdgcn_mfma_f32_16x16x32_bf16(Bt[n][k], At[m][k], acc[ai][bj][m][n], 0, 0, 0); __builtin_amdgcn_s_setprio(0); } while (0)
; #define PG8_WAIT_V(n) asm volatile("s_waitcnt vmcnt(" #n ")" ::: "memory")
; #define PG8_WAIT_L(n) asm volatile("s_waitcnt lgkmcnt(" #n ")" ::: "memory")
; #define PG8_BAR __builtin_amdgcn_s_barrier()
; #define PG8_SCHED __builtin_amdgcn_sched_barrier(0)
; template <class Epi, bool SPLITA = false>
; __device__ __forceinline__ void gemm_phase(const int tid, LAS unsigned char* lds, const Gemm g, const Order& S, const Epi& E) {
;     ...
;       PG8_STAGE(PG8_SB(0, 1), b2 + hstepB, voffB);
;       PG8_WAIT_V(6); PG8_BAR; PG8_MMA(1, 1, At, B1); PG8_BAR;
;       PG8_LDB(B0, 1, 0); PG8_SCHED; PG8_LDA(At, 1, 0); PG8_STAGE(PG8_SA(0, 1), a2 + hstepA, voffA);
;       PG8_WAIT_L(8); PG8_BAR; PG8_WAIT_L(0); PG8_MMA(0, 0, At, B0); PG8_BAR; PG8_SCHED;
;       PG8_LDB(B1, 1, 1); PG8_STAGE(PG8_SB(1, 0), b3, voffB);
;       PG8_BAR; PG8_WAIT_L(0); PG8_MMA(0, 1, At, B1); PG8_BAR;
;       PG8_LDA(At, 1, 1); PG8_STAGE(PG8_SA(1, 0), a3, voffA);
	s_add_u32 s22, s48, 0x80000
	s_addc_u32 s23, s49, 0
	s_add_i32 s4, s4, s93
	s_mov_b32 m0, s4
	s_nop 0
	global_load_lds_dwordx4 v0, s[22:23]
	s_add_i32 m0, s4, 0x2000
	s_nop 0
	global_load_lds_dwordx4 v212, s[22:23]
	s_waitcnt vmcnt(6)
	s_barrier
	s_setprio 1
	v_mfma_f32_16x16x32_bf16 v[54:57], v[178:181], v[146:149], v[54:57]
	v_mfma_f32_16x16x32_bf16 v[50:53], v[186:189], v[146:149], v[50:53]
	v_mfma_f32_16x16x32_bf16 v[38:41], v[178:181], v[154:157], v[38:41]
	v_mfma_f32_16x16x32_bf16 v[34:37], v[186:189], v[154:157], v[34:37]
	v_mfma_f32_16x16x32_bf16 v[22:25], v[178:181], v[162:165], v[22:25]
	v_mfma_f32_16x16x32_bf16 v[18:21], v[186:189], v[162:165], v[18:21]
	v_mfma_f32_16x16x32_bf16 v[6:9], v[178:181], v[170:173], v[6:9]
	v_mfma_f32_16x16x32_bf16 v[2:5], v[186:189], v[170:173], v[2:5]
	v_mfma_f32_16x16x32_bf16 v[54:57], v[182:185], v[150:153], v[54:57]
	v_mfma_f32_16x16x32_bf16 v[50:53], v[190:193], v[150:153], v[50:53]
	v_mfma_f32_16x16x32_bf16 v[38:41], v[182:185], v[158:161], v[38:41]
	v_mfma_f32_16x16x32_bf16 v[34:37], v[190:193], v[158:161], v[34:37]
	v_mfma_f32_16x16x32_bf16 v[22:25], v[182:185], v[166:169], v[22:25]
	v_mfma_f32_16x16x32_bf16 v[18:21], v[190:193], v[166:169], v[18:21]
	v_mfma_f32_16x16x32_bf16 v[6:9], v[182:185], v[174:177], v[6:9]
	v_mfma_f32_16x16x32_bf16 v[2:5], v[190:193], v[174:177], v[2:5]
	s_setprio 0
	s_add_i32 s4, 0, 0x18000
	v_add_u32_e32 v142, s4, v209
	s_barrier
	ds_read_b128 v[130:133], v142
	ds_read_b128 v[134:137], v142 offset:1024
	ds_read_b128 v[138:141], v142 offset:2048
	ds_read_b128 v[142:145], v142 offset:3072
	s_add_u32 s22, s90, 0x40000
	s_addc_u32 s23, s91, 0
	s_mov_b32 m0, s45
	ds_read_b128 v[146:149], v211 offset:32768
	ds_read_b128 v[150:153], v211 offset:33792
	ds_read_b128 v[154:157], v211 offset:34816
	ds_read_b128 v[158:161], v211 offset:35840
	ds_read_b128 v[162:165], v211 offset:36864
	ds_read_b128 v[166:169], v211 offset:37888
	ds_read_b128 v[170:173], v211 offset:38912
	ds_read_b128 v[174:177], v211 offset:39936
	global_load_lds_dwordx4 v216, s[22:23]
	s_mov_b32 m0, s46
	s_nop 0
	global_load_lds_dwordx4 v214, s[22:23]
	s_waitcnt lgkmcnt(8)
	s_barrier
	s_waitcnt lgkmcnt(0)
	s_setprio 1
	s_waitcnt lgkmcnt(0)
	v_mfma_f32_16x16x32_bf16 v[126:129], v[130:133], v[146:149], v[126:129]
	v_mfma_f32_16x16x32_bf16 v[122:125], v[138:141], v[146:149], v[122:125]
	v_mfma_f32_16x16x32_bf16 v[110:113], v[130:133], v[154:157], v[110:113]
	v_mfma_f32_16x16x32_bf16 v[106:109], v[138:141], v[154:157], v[106:109]
	v_mfma_f32_16x16x32_bf16 v[94:97], v[130:133], v[162:165], v[94:97]
	v_mfma_f32_16x16x32_bf16 v[90:93], v[138:141], v[162:165], v[90:93]
	v_mfma_f32_16x16x32_bf16 v[78:81], v[130:133], v[170:173], v[78:81]
	v_mfma_f32_16x16x32_bf16 v[74:77], v[138:141], v[170:173], v[74:77]
	v_mfma_f32_16x16x32_bf16 v[126:129], v[134:137], v[150:153], v[126:129]
	v_mfma_f32_16x16x32_bf16 v[122:125], v[142:145], v[150:153], v[122:125]
	v_mfma_f32_16x16x32_bf16 v[110:113], v[134:137], v[158:161], v[110:113]
	v_mfma_f32_16x16x32_bf16 v[106:109], v[142:145], v[158:161], v[106:109]
	v_mfma_f32_16x16x32_bf16 v[94:97], v[134:137], v[166:169], v[94:97]
	v_mfma_f32_16x16x32_bf16 v[90:93], v[142:145], v[166:169], v[90:93]
	v_mfma_f32_16x16x32_bf16 v[78:81], v[134:137], v[174:177], v[78:81]
	v_mfma_f32_16x16x32_bf16 v[74:77], v[142:145], v[174:177], v[74:77]
	s_setprio 0
	s_barrier
	s_add_i32 s20, 0, 0x1c000
	s_add_i32 s4, s4, s93
	v_add_u32_e32 v190, s20, v209
	s_add_i32 m0, s4, 0xffffff80
	ds_read_b128 v[178:181], v190
	ds_read_b128 v[182:185], v190 offset:1024
	ds_read_b128 v[186:189], v190 offset:2048
	ds_read_b128 v[190:193], v190 offset:3072
	global_load_lds_dwordx4 v0, s[48:49] offset:128
	s_add_i32 m0, s4, 0x1f80
	s_nop 0
	global_load_lds_dwordx4 v212, s[48:49] offset:128
	s_barrier
; #define PG8_STAGE(bufoff, gbase, voff) do { _Pragma("unroll") for (int _i = 0; _i < 2; ++_i) \
;     __builtin_amdgcn_global_load_lds((const unsigned*)((const char*)(gbase) + (voff)[_i]), (LAS unsigned*)(lds + (bufoff) + ldsw + _i * 8192), 16, 0, 0); } while (0)
; #define PG8_LDA(dst, b, h) do { _Pragma("unroll") for (int m = 0; m < 4; ++m) _Pragma("unroll") for (int k = 0; k < 2; ++k) dst[m][k] = *(const LAS bf16x8*)(lds + PG8_SA(b, h) + aoff + m * 2048 + k * 1024); } while (0)
; #define PG8_MMA(ai, bj, At, Bt) do { __builtin_amdgcn_s_setprio(1); _Pragma("unroll") for (int m = 0; m < 4; ++m) _Pragma("unroll") for (int n = 0; n < 2; ++n) _Pragma("unroll") for (int k = 0; k < 2; ++k) \
;     acc[ai][bj][m][n] = __builtin_amdgcn_mfma_f32_16x16x32_bf16(Bt[n][k], At[m][k], acc[ai][bj][m][n], 0, 0, 0); __builtin_amdgcn_s_setprio(0); } while (0)
; #define PG8_WAIT_V(n) asm volatile("s_waitcnt vmcnt(" #n ")" ::: "memory")
; #define PG8_WAIT_L(n) asm volatile("s_waitcnt lgkmcnt(" #n ")" ::: "memory")
; #define PG8_BAR __builtin_amdgcn_s_barrier()
; #define PG8_SCHED __builtin_amdgcn_sched_barrier(0)
; template <class Epi, bool SPLITA = false>
; __device__ __forceinline__ void gemm_phase(const int tid, LAS unsigned char* lds, const Gemm g, const Order& S, const Epi& E) {
;     ...
;       PG8_BAR; PG8_WAIT_L(0); PG8_MMA(0, 1, At, B1); PG8_BAR;
;       PG8_LDA(At, 1, 1); PG8_STAGE(PG8_SA(1, 0), a3, voffA);
;       PG8_BAR; PG8_WAIT_L(0); PG8_MMA(1, 0, At, B0); PG8_BAR; PG8_SCHED;
;       PG8_STAGE(PG8_SB(1, 1), b3 + hstepB, voffB);
;       PG8_WAIT_V(6); PG8_BAR; PG8_MMA(1, 1, At, B1); PG8_BAR;
;     }
	s_waitcnt lgkmcnt(0)
	s_setprio 1
	s_waitcnt lgkmcnt(0)
	v_mfma_f32_16x16x32_bf16 v[118:121], v[178:181], v[146:149], v[118:121]
	v_mfma_f32_16x16x32_bf16 v[114:117], v[186:189], v[146:149], v[114:117]
	v_mfma_f32_16x16x32_bf16 v[102:105], v[178:181], v[154:157], v[102:105]
	v_mfma_f32_16x16x32_bf16 v[98:101], v[186:189], v[154:157], v[98:101]
	v_mfma_f32_16x16x32_bf16 v[86:89], v[178:181], v[162:165], v[86:89]
	v_mfma_f32_16x16x32_bf16 v[82:85], v[186:189], v[162:165], v[82:85]
	v_mfma_f32_16x16x32_bf16 v[70:73], v[178:181], v[170:173], v[70:73]
	v_mfma_f32_16x16x32_bf16 v[66:69], v[186:189], v[170:173], v[66:69]
	v_mfma_f32_16x16x32_bf16 v[118:121], v[182:185], v[150:153], v[118:121]
	v_mfma_f32_16x16x32_bf16 v[114:117], v[190:193], v[150:153], v[114:117]
	v_mfma_f32_16x16x32_bf16 v[102:105], v[182:185], v[158:161], v[102:105]
	v_mfma_f32_16x16x32_bf16 v[98:101], v[190:193], v[158:161], v[98:101]
	v_mfma_f32_16x16x32_bf16 v[86:89], v[182:185], v[166:169], v[86:89]
	v_mfma_f32_16x16x32_bf16 v[82:85], v[190:193], v[166:169], v[82:85]
	v_mfma_f32_16x16x32_bf16 v[70:73], v[182:185], v[174:177], v[70:73]
	v_mfma_f32_16x16x32_bf16 v[66:69], v[190:193], v[174:177], v[66:69]
	s_setprio 0
	s_mov_b32 m0, s47
	s_barrier
	ds_read_b128 v[146:149], v211 offset:49152
	ds_read_b128 v[150:153], v211 offset:50176
	ds_read_b128 v[154:157], v211 offset:51200
	ds_read_b128 v[158:161], v211 offset:52224
	ds_read_b128 v[162:165], v211 offset:53248
	ds_read_b128 v[166:169], v211 offset:54272
	ds_read_b128 v[170:173], v211 offset:55296
	ds_read_b128 v[174:177], v211 offset:56320
	global_load_lds_dwordx4 v216, s[42:43]
	s_mov_b32 m0, s38
	s_nop 0
	global_load_lds_dwordx4 v214, s[42:43]
	s_barrier
	s_waitcnt lgkmcnt(0)
	s_setprio 1
	s_waitcnt lgkmcnt(0)
	v_mfma_f32_16x16x32_bf16 v[62:65], v[130:133], v[146:149], v[62:65]
	v_mfma_f32_16x16x32_bf16 v[58:61], v[138:141], v[146:149], v[58:61]
	v_mfma_f32_16x16x32_bf16 v[46:49], v[130:133], v[154:157], v[46:49]
	v_mfma_f32_16x16x32_bf16 v[42:45], v[138:141], v[154:157], v[42:45]
	v_mfma_f32_16x16x32_bf16 v[30:33], v[130:133], v[162:165], v[30:33]
	v_mfma_f32_16x16x32_bf16 v[26:29], v[138:141], v[162:165], v[26:29]
	v_mfma_f32_16x16x32_bf16 v[14:17], v[130:133], v[170:173], v[14:17]
	v_mfma_f32_16x16x32_bf16 v[10:13], v[138:141], v[170:173], v[10:13]
	v_mfma_f32_16x16x32_bf16 v[62:65], v[134:137], v[150:153], v[62:65]
	v_mfma_f32_16x16x32_bf16 v[58:61], v[142:145], v[150:153], v[58:61]
	v_mfma_f32_16x16x32_bf16 v[46:49], v[134:137], v[158:161], v[46:49]
	v_mfma_f32_16x16x32_bf16 v[42:45], v[142:145], v[158:161], v[42:45]
	v_mfma_f32_16x16x32_bf16 v[30:33], v[134:137], v[166:169], v[30:33]
	v_mfma_f32_16x16x32_bf16 v[26:29], v[142:145], v[166:169], v[26:29]
	v_mfma_f32_16x16x32_bf16 v[14:17], v[134:137], v[174:177], v[14:17]
	v_mfma_f32_16x16x32_bf16 v[10:13], v[142:145], v[174:177], v[10:13]
	s_setprio 0
	s_barrier
	s_add_u32 s22, s48, 0x80080
	s_addc_u32 s23, s49, 0
	s_add_i32 s4, s20, s93
	s_mov_b32 m0, s4
	s_nop 0
	global_load_lds_dwordx4 v0, s[22:23]
	s_add_i32 m0, s4, 0x2000
	s_nop 0
	global_load_lds_dwordx4 v212, s[22:23]
	s_waitcnt vmcnt(6)
	s_barrier
	s_setprio 1
	v_mfma_f32_16x16x32_bf16 v[54:57], v[178:181], v[146:149], v[54:57]
	v_mfma_f32_16x16x32_bf16 v[50:53], v[186:189], v[146:149], v[50:53]
	v_mfma_f32_16x16x32_bf16 v[38:41], v[178:181], v[154:157], v[38:41]
	v_mfma_f32_16x16x32_bf16 v[34:37], v[186:189], v[154:157], v[34:37]
	v_mfma_f32_16x16x32_bf16 v[22:25], v[178:181], v[162:165], v[22:25]
	v_mfma_f32_16x16x32_bf16 v[18:21], v[186:189], v[162:165], v[18:21]
	v_mfma_f32_16x16x32_bf16 v[6:9], v[178:181], v[170:173], v[6:9]
	v_mfma_f32_16x16x32_bf16 v[2:5], v[186:189], v[170:173], v[2:5]
	v_mfma_f32_16x16x32_bf16 v[54:57], v[182:185], v[150:153], v[54:57]
	v_mfma_f32_16x16x32_bf16 v[50:53], v[190:193], v[150:153], v[50:53]
	v_mfma_f32_16x16x32_bf16 v[38:41], v[182:185], v[158:161], v[38:41]
	v_mfma_f32_16x16x32_bf16 v[34:37], v[190:193], v[158:161], v[34:37]
	v_mfma_f32_16x16x32_bf16 v[22:25], v[182:185], v[166:169], v[22:25]
	v_mfma_f32_16x16x32_bf16 v[18:21], v[190:193], v[166:169], v[18:21]
	v_mfma_f32_16x16x32_bf16 v[6:9], v[182:185], v[174:177], v[6:9]
	v_mfma_f32_16x16x32_bf16 v[2:5], v[190:193], v[174:177], v[2:5]
	s_setprio 0
	s_add_u32 s40, s40, 0x100
	s_addc_u32 s41, s41, 0
	v_readlane_b32 s90, v255, 31
	s_cmp_gt_u32 s2, 29
	s_mov_b32 s2, s3
	v_readlane_b32 s91, v255, 32
	s_barrier
	s_cbranch_scc1 .LBB0_229

; #define PG8_STAGE(bufoff, gbase, voff) do { _Pragma("unroll") for (int _i = 0; _i < 2; ++_i) \
;     __builtin_amdgcn_global_load_lds((const unsigned*)((const char*)(gbase) + (voff)[_i]), (LAS unsigned*)(lds + (bufoff) + ldsw + _i * 8192), 16, 0, 0); } while (0)
; #define PG8_LDA(dst, b, h) do { _Pragma("unroll") for (int m = 0; m < 4; ++m) _Pragma("unroll") for (int k = 0; k < 2; ++k) dst[m][k] = *(const LAS bf16x8*)(lds + PG8_SA(b, h) + aoff + m * 2048 + k * 1024); } while (0)
; #define PG8_LDB(dst, b, h) do { _Pragma("unroll") for (int n = 0; n < 2; ++n) _Pragma("unroll") for (int k = 0; k < 2; ++k) dst[n][k] = *(const LAS bf16x8*)(lds + PG8_SB(b, h) + boff + n * 2048 + k * 1024); } while (0)
; #define PG8_MMA(ai, bj, At, Bt) do { __builtin_amdgcn_s_setprio(1); _Pragma("unroll") for (int m = 0; m < 4; ++m) _Pragma("unroll") for (int n = 0; n < 2; ++n) _Pragma("unroll") for (int k = 0; k < 2; ++k) \
;     acc[ai][bj][m][n] = __builtin_amdgcn_mfma_f32_16x16x32_bf16(Bt[n][k], At[m][k], acc[ai][bj][m][n], 0, 0, 0); __builtin_amdgcn_s_setprio(0); } while (0)
; #define PG8_WAIT_L(n) asm volatile("s_waitcnt lgkmcnt(" #n ")" ::: "memory")
; #define PG8_BAR __builtin_amdgcn_s_barrier()
; #define PG8_SCHED __builtin_amdgcn_sched_barrier(0)
; template <class Epi, bool SPLITA = false>
; __device__ __forceinline__ void gemm_phase(const int tid, LAS unsigned char* lds, const Gemm g, const Order& S, const Epi& E) {
;     ...
;       const char* a1 = PG8_TA(t + 1);
;       const char* a2 = last ? nA : PG8_TA(t + 2); const char* b2 = last ? nB : cB + (size_t)(t + 2) * kstep;
;       const char* a3 = last ? nA + kstep : PG8_TA(t + 3); const char* b3 = b2 + kstep;
;       PG8_LDB(B0, 0, 0); PG8_SCHED; PG8_LDA(At, 0, 0); PG8_STAGE(PG8_SA(1, 1), a1 + hstepA, voffA);
;       PG8_WAIT_L(8); PG8_BAR; PG8_WAIT_L(0); PG8_MMA(0, 0, At, B0); PG8_BAR; PG8_SCHED;
;       PG8_LDB(B1, 0, 1); PG8_STAGE(PG8_SB(0, 0), b2, voffB);
;       PG8_BAR; PG8_WAIT_L(0); PG8_MMA(0, 1, At, B1); PG8_BAR;
;       PG8_LDA(At, 0, 1); PG8_STAGE(PG8_SA(0, 0), a2, voffA);
;       PG8_BAR; PG8_WAIT_L(0); PG8_MMA(1, 0, At, B0); PG8_BAR; PG8_SCHED;
.LBB0_328:
	s_add_u32 s12, s8, s10
	s_addc_u32 s13, s9, s11
	s_add_u32 s16, s12, 0x100
	s_addc_u32 s17, s13, 0
	s_add_u32 s20, s55, s10
	s_addc_u32 s21, s90, s11
	s_add_u32 s12, s12, 0x180
	s_addc_u32 s13, s13, 0
	s_add_i32 s22, 0, 0x10000
	v_add_u32_e32 v160, s22, v146
	ds_read_b128 v[148:151], v160
	ds_read_b128 v[152:155], v160 offset:1024
	ds_read_b128 v[156:159], v160 offset:2048
	ds_read_b128 v[160:163], v160 offset:3072
	s_cmpk_eq_i32 s10, 0x1000
	s_cselect_b32 s15, s41, s13
	s_cselect_b32 s14, s40, s12
	s_cselect_b32 s13, s7, s21
	s_cselect_b32 s12, s6, s20
	s_cselect_b32 s17, s1, s17
	s_cselect_b32 s16, s0, s16
	v_lshl_add_u64 v[192:193], v[140:141], 0, s[10:11]
	s_add_i32 m0, s30, 0xc000
	ds_read_b128 v[164:167], v147
	ds_read_b128 v[168:171], v147 offset:1024
	ds_read_b128 v[172:175], v147 offset:2048
	ds_read_b128 v[176:179], v147 offset:3072
	ds_read_b128 v[180:183], v147 offset:4096
	ds_read_b128 v[184:187], v147 offset:5120
	ds_read_b128 v[188:191], v147 offset:6144
	ds_read_b128 v[212:215], v147 offset:7168
	global_load_lds_dwordx4 v[192:193], off
	v_lshl_add_u64 v[192:193], v[142:143], 0, s[10:11]
	s_add_i32 m0, s30, 0xe000
	s_nop 0
	global_load_lds_dwordx4 v[192:193], off
	s_waitcnt lgkmcnt(8)
	s_barrier
	s_waitcnt lgkmcnt(0)
	s_setprio 1
	s_waitcnt lgkmcnt(0)
	v_mfma_f32_16x16x32_bf16 v[126:129], v[148:151], v[164:167], v[126:129]
	v_mfma_f32_16x16x32_bf16 v[122:125], v[156:159], v[164:167], v[122:125]
	v_mfma_f32_16x16x32_bf16 v[110:113], v[148:151], v[172:175], v[110:113]
	v_mfma_f32_16x16x32_bf16 v[106:109], v[156:159], v[172:175], v[106:109]
	v_mfma_f32_16x16x32_bf16 v[94:97], v[148:151], v[180:183], v[94:97]
	v_mfma_f32_16x16x32_bf16 v[90:93], v[156:159], v[180:183], v[90:93]
	v_mfma_f32_16x16x32_bf16 v[78:81], v[148:151], v[188:191], v[78:81]
	v_mfma_f32_16x16x32_bf16 v[74:77], v[156:159], v[188:191], v[74:77]
	v_mfma_f32_16x16x32_bf16 v[126:129], v[152:155], v[168:171], v[126:129]
	v_mfma_f32_16x16x32_bf16 v[122:125], v[160:163], v[168:171], v[122:125]
	v_mfma_f32_16x16x32_bf16 v[110:113], v[152:155], v[176:179], v[110:113]
	v_mfma_f32_16x16x32_bf16 v[106:109], v[160:163], v[176:179], v[106:109]
	v_mfma_f32_16x16x32_bf16 v[94:97], v[152:155], v[184:187], v[94:97]
	v_mfma_f32_16x16x32_bf16 v[90:93], v[160:163], v[184:187], v[90:93]
	v_mfma_f32_16x16x32_bf16 v[78:81], v[152:155], v[212:215], v[78:81]
	v_mfma_f32_16x16x32_bf16 v[74:77], v[160:163], v[212:215], v[74:77]
	s_setprio 0
	s_barrier
	s_add_i32 s20, 0, 0x14000
	v_add_u32_e32 v192, s20, v146
	s_add_i32 s21, s22, s18
	ds_read_b128 v[216:219], v192
	ds_read_b128 v[220:223], v192 offset:1024
	ds_read_b128 v[224:227], v192 offset:2048
	ds_read_b128 v[228:231], v192 offset:3072
	s_mov_b32 m0, s21
	s_nop 0
	global_load_lds_dwordx4 v0, s[12:13]
	s_add_i32 m0, s21, 0x2000
	s_nop 0
	global_load_lds_dwordx4 v134, s[12:13]
	s_barrier
	s_waitcnt lgkmcnt(0)
	s_setprio 1
	s_waitcnt lgkmcnt(0)
	v_mfma_f32_16x16x32_bf16 v[118:121], v[216:219], v[164:167], v[118:121]
	v_mfma_f32_16x16x32_bf16 v[114:117], v[224:227], v[164:167], v[114:117]
	v_mfma_f32_16x16x32_bf16 v[102:105], v[216:219], v[172:175], v[102:105]
	v_mfma_f32_16x16x32_bf16 v[98:101], v[224:227], v[172:175], v[98:101]
	v_mfma_f32_16x16x32_bf16 v[86:89], v[216:219], v[180:183], v[86:89]
	v_mfma_f32_16x16x32_bf16 v[82:85], v[224:227], v[180:183], v[82:85]
	v_mfma_f32_16x16x32_bf16 v[70:73], v[216:219], v[188:191], v[70:73]
	v_mfma_f32_16x16x32_bf16 v[66:69], v[224:227], v[188:191], v[66:69]
	v_mfma_f32_16x16x32_bf16 v[118:121], v[220:223], v[168:171], v[118:121]
	v_mfma_f32_16x16x32_bf16 v[114:117], v[228:231], v[168:171], v[114:117]
	v_mfma_f32_16x16x32_bf16 v[102:105], v[220:223], v[176:179], v[102:105]
	v_mfma_f32_16x16x32_bf16 v[98:101], v[228:231], v[176:179], v[98:101]
	v_mfma_f32_16x16x32_bf16 v[86:89], v[220:223], v[184:187], v[86:89]
	v_mfma_f32_16x16x32_bf16 v[82:85], v[228:231], v[184:187], v[82:85]
	v_mfma_f32_16x16x32_bf16 v[70:73], v[220:223], v[212:215], v[70:73]
	v_mfma_f32_16x16x32_bf16 v[66:69], v[228:231], v[212:215], v[66:69]
	s_setprio 0
	s_mov_b32 m0, s30
	s_barrier
	ds_read_b128 v[164:167], v147 offset:16384
	ds_read_b128 v[168:171], v147 offset:17408
	ds_read_b128 v[172:175], v147 offset:18432
	ds_read_b128 v[176:179], v147 offset:19456
	ds_read_b128 v[180:183], v147 offset:20480
	ds_read_b128 v[184:187], v147 offset:21504
	ds_read_b128 v[188:191], v147 offset:22528
	ds_read_b128 v[212:215], v147 offset:23552
	global_load_lds_dwordx4 v130, s[16:17]
	s_mov_b32 m0, s31
	s_nop 0
	global_load_lds_dwordx4 v132, s[16:17]
	s_barrier
	s_waitcnt lgkmcnt(0)
	s_setprio 1
	s_waitcnt lgkmcnt(0)
	v_mfma_f32_16x16x32_bf16 v[62:65], v[148:151], v[164:167], v[62:65]
	v_mfma_f32_16x16x32_bf16 v[58:61], v[156:159], v[164:167], v[58:61]
	v_mfma_f32_16x16x32_bf16 v[46:49], v[148:151], v[172:175], v[46:49]
	v_mfma_f32_16x16x32_bf16 v[42:45], v[156:159], v[172:175], v[42:45]
	v_mfma_f32_16x16x32_bf16 v[30:33], v[148:151], v[180:183], v[30:33]
	v_mfma_f32_16x16x32_bf16 v[26:29], v[156:159], v[180:183], v[26:29]
	v_mfma_f32_16x16x32_bf16 v[14:17], v[148:151], v[188:191], v[14:17]
	v_mfma_f32_16x16x32_bf16 v[10:13], v[156:159], v[188:191], v[10:13]
	v_mfma_f32_16x16x32_bf16 v[62:65], v[152:155], v[168:171], v[62:65]
	v_mfma_f32_16x16x32_bf16 v[58:61], v[160:163], v[168:171], v[58:61]
	v_mfma_f32_16x16x32_bf16 v[46:49], v[152:155], v[176:179], v[46:49]
	v_mfma_f32_16x16x32_bf16 v[42:45], v[160:163], v[176:179], v[42:45]
	v_mfma_f32_16x16x32_bf16 v[30:33], v[152:155], v[184:187], v[30:33]
	v_mfma_f32_16x16x32_bf16 v[26:29], v[160:163], v[184:187], v[26:29]
	v_mfma_f32_16x16x32_bf16 v[14:17], v[152:155], v[212:215], v[14:17]
	v_mfma_f32_16x16x32_bf16 v[10:13], v[160:163], v[212:215], v[10:13]
	s_setprio 0
	s_barrier
; #define PG8_STAGE(bufoff, gbase, voff) do { _Pragma("unroll") for (int _i = 0; _i < 2; ++_i) \
;     __builtin_amdgcn_global_load_lds((const unsigned*)((const char*)(gbase) + (voff)[_i]), (LAS unsigned*)(lds + (bufoff) + ldsw + _i * 8192), 16, 0, 0); } while (0)
; #define PG8_LDA(dst, b, h) do { _Pragma("unroll") for (int m = 0; m < 4; ++m) _Pragma("unroll") for (int k = 0; k < 2; ++k) dst[m][k] = *(const LAS bf16x8*)(lds + PG8_SA(b, h) + aoff + m * 2048 + k * 1024); } while (0)
; #define PG8_LDB(dst, b, h) do { _Pragma("unroll") for (int n = 0; n < 2; ++n) _Pragma("unroll") for (int k = 0; k < 2; ++k) dst[n][k] = *(const LAS bf16x8*)(lds + PG8_SB(b, h) + boff + n * 2048 + k * 1024); } while (0)
; #define PG8_MMA(ai, bj, At, Bt) do { __builtin_amdgcn_s_setprio(1); _Pragma("unroll") for (int m = 0; m < 4; ++m) _Pragma("unroll") for (int n = 0; n < 2; ++n) _Pragma("unroll") for (int k = 0; k < 2; ++k) \
;     acc[ai][bj][m][n] = __builtin_amdgcn_mfma_f32_16x16x32_bf16(Bt[n][k], At[m][k], acc[ai][bj][m][n], 0, 0, 0); __builtin_amdgcn_s_setprio(0); } while (0)
; #define PG8_WAIT_V(n) asm volatile("s_waitcnt vmcnt(" #n ")" ::: "memory")
; #define PG8_WAIT_L(n) asm volatile("s_waitcnt lgkmcnt(" #n ")" ::: "memory")
; #define PG8_BAR __builtin_amdgcn_s_barrier()
; #define PG8_SCHED __builtin_amdgcn_sched_barrier(0)
; template <class Epi, bool SPLITA = false>
; __device__ __forceinline__ void gemm_phase(const int tid, LAS unsigned char* lds, const Gemm g, const Order& S, const Epi& E) {
;     ...
;       PG8_STAGE(PG8_SB(0, 1), b2 + hstepB, voffB);
;       PG8_WAIT_V(6); PG8_BAR; PG8_MMA(1, 1, At, B1); PG8_BAR;
;       PG8_LDB(B0, 1, 0); PG8_SCHED; PG8_LDA(At, 1, 0); PG8_STAGE(PG8_SA(0, 1), a2 + hstepA, voffA);
;       PG8_WAIT_L(8); PG8_BAR; PG8_WAIT_L(0); PG8_MMA(0, 0, At, B0); PG8_BAR; PG8_SCHED;
;       PG8_LDB(B1, 1, 1); PG8_STAGE(PG8_SB(1, 0), b3, voffB);
;       PG8_BAR; PG8_WAIT_L(0); PG8_MMA(0, 1, At, B1); PG8_BAR;
	s_add_u32 s22, s12, 0x88000
	s_addc_u32 s23, s13, 0
	s_add_i32 s20, s20, s18
	s_mov_b32 m0, s20
	s_nop 0
	global_load_lds_dwordx4 v0, s[22:23]
	s_add_i32 m0, s20, 0x2000
	s_nop 0
	global_load_lds_dwordx4 v134, s[22:23]
	s_waitcnt vmcnt(6)
	s_barrier
	s_setprio 1
	v_mfma_f32_16x16x32_bf16 v[54:57], v[216:219], v[164:167], v[54:57]
	v_mfma_f32_16x16x32_bf16 v[50:53], v[224:227], v[164:167], v[50:53]
	v_mfma_f32_16x16x32_bf16 v[38:41], v[216:219], v[172:175], v[38:41]
	v_mfma_f32_16x16x32_bf16 v[34:37], v[224:227], v[172:175], v[34:37]
	v_mfma_f32_16x16x32_bf16 v[22:25], v[216:219], v[180:183], v[22:25]
	v_mfma_f32_16x16x32_bf16 v[18:21], v[224:227], v[180:183], v[18:21]
	v_mfma_f32_16x16x32_bf16 v[6:9], v[216:219], v[188:191], v[6:9]
	v_mfma_f32_16x16x32_bf16 v[2:5], v[224:227], v[188:191], v[2:5]
	v_mfma_f32_16x16x32_bf16 v[54:57], v[220:223], v[168:171], v[54:57]
	v_mfma_f32_16x16x32_bf16 v[50:53], v[228:231], v[168:171], v[50:53]
	v_mfma_f32_16x16x32_bf16 v[38:41], v[220:223], v[176:179], v[38:41]
	v_mfma_f32_16x16x32_bf16 v[34:37], v[228:231], v[176:179], v[34:37]
	v_mfma_f32_16x16x32_bf16 v[22:25], v[220:223], v[184:187], v[22:25]
	v_mfma_f32_16x16x32_bf16 v[18:21], v[228:231], v[184:187], v[18:21]
	v_mfma_f32_16x16x32_bf16 v[6:9], v[220:223], v[212:215], v[6:9]
	v_mfma_f32_16x16x32_bf16 v[2:5], v[228:231], v[212:215], v[2:5]
	s_setprio 0
	s_add_i32 s20, 0, 0x18000
	v_add_u32_e32 v160, s20, v146
	s_barrier
	ds_read_b128 v[148:151], v160
	ds_read_b128 v[152:155], v160 offset:1024
	ds_read_b128 v[156:159], v160 offset:2048
	ds_read_b128 v[160:163], v160 offset:3072
	s_add_u32 s16, s16, 0x88000
	s_addc_u32 s17, s17, 0
	s_mov_b32 m0, s42
	ds_read_b128 v[164:167], v147 offset:32768
	ds_read_b128 v[168:171], v147 offset:33792
	ds_read_b128 v[172:175], v147 offset:34816
	ds_read_b128 v[176:179], v147 offset:35840
	ds_read_b128 v[180:183], v147 offset:36864
	ds_read_b128 v[184:187], v147 offset:37888
	ds_read_b128 v[188:191], v147 offset:38912
	ds_read_b128 v[212:215], v147 offset:39936
	global_load_lds_dwordx4 v130, s[16:17]
	s_mov_b32 m0, s43
	s_nop 0
	global_load_lds_dwordx4 v132, s[16:17]
	s_waitcnt lgkmcnt(8)
	s_barrier
	s_waitcnt lgkmcnt(0)
	s_setprio 1
	s_waitcnt lgkmcnt(0)
	v_mfma_f32_16x16x32_bf16 v[126:129], v[148:151], v[164:167], v[126:129]
	v_mfma_f32_16x16x32_bf16 v[122:125], v[156:159], v[164:167], v[122:125]
	v_mfma_f32_16x16x32_bf16 v[110:113], v[148:151], v[172:175], v[110:113]
	v_mfma_f32_16x16x32_bf16 v[106:109], v[156:159], v[172:175], v[106:109]
	v_mfma_f32_16x16x32_bf16 v[94:97], v[148:151], v[180:183], v[94:97]
	v_mfma_f32_16x16x32_bf16 v[90:93], v[156:159], v[180:183], v[90:93]
	v_mfma_f32_16x16x32_bf16 v[78:81], v[148:151], v[188:191], v[78:81]
	v_mfma_f32_16x16x32_bf16 v[74:77], v[156:159], v[188:191], v[74:77]
	v_mfma_f32_16x16x32_bf16 v[126:129], v[152:155], v[168:171], v[126:129]
	v_mfma_f32_16x16x32_bf16 v[122:125], v[160:163], v[168:171], v[122:125]
	v_mfma_f32_16x16x32_bf16 v[110:113], v[152:155], v[176:179], v[110:113]
	v_mfma_f32_16x16x32_bf16 v[106:109], v[160:163], v[176:179], v[106:109]
	v_mfma_f32_16x16x32_bf16 v[94:97], v[152:155], v[184:187], v[94:97]
	v_mfma_f32_16x16x32_bf16 v[90:93], v[160:163], v[184:187], v[90:93]
	v_mfma_f32_16x16x32_bf16 v[78:81], v[152:155], v[212:215], v[78:81]
	v_mfma_f32_16x16x32_bf16 v[74:77], v[160:163], v[212:215], v[74:77]
	s_setprio 0
	s_barrier
	s_add_i32 s16, 0, 0x1c000
	s_add_i32 s17, s20, s18
	v_add_u32_e32 v195, s16, v146
	s_add_i32 m0, s17, 0xffffff80
	ds_read_b128 v[216:219], v195
	ds_read_b128 v[220:223], v195 offset:1024
	ds_read_b128 v[224:227], v195 offset:2048
	ds_read_b128 v[228:231], v195 offset:3072
	global_load_lds_dwordx4 v0, s[12:13] offset:128
	s_add_i32 m0, s17, 0x1f80
	s_nop 0
	global_load_lds_dwordx4 v134, s[12:13] offset:128
	s_barrier
	s_waitcnt lgkmcnt(0)
	s_setprio 1
	s_waitcnt lgkmcnt(0)
	v_mfma_f32_16x16x32_bf16 v[118:121], v[216:219], v[164:167], v[118:121]
	v_mfma_f32_16x16x32_bf16 v[114:117], v[224:227], v[164:167], v[114:117]
	v_mfma_f32_16x16x32_bf16 v[102:105], v[216:219], v[172:175], v[102:105]
	v_mfma_f32_16x16x32_bf16 v[98:101], v[224:227], v[172:175], v[98:101]
	v_mfma_f32_16x16x32_bf16 v[86:89], v[216:219], v[180:183], v[86:89]
	v_mfma_f32_16x16x32_bf16 v[82:85], v[224:227], v[180:183], v[82:85]
	v_mfma_f32_16x16x32_bf16 v[70:73], v[216:219], v[188:191], v[70:73]
	v_mfma_f32_16x16x32_bf16 v[66:69], v[224:227], v[188:191], v[66:69]
	v_mfma_f32_16x16x32_bf16 v[118:121], v[220:223], v[168:171], v[118:121]
	v_mfma_f32_16x16x32_bf16 v[114:117], v[228:231], v[168:171], v[114:117]
	v_mfma_f32_16x16x32_bf16 v[102:105], v[220:223], v[176:179], v[102:105]
	v_mfma_f32_16x16x32_bf16 v[98:101], v[228:231], v[176:179], v[98:101]
	v_mfma_f32_16x16x32_bf16 v[86:89], v[220:223], v[184:187], v[86:89]
	v_mfma_f32_16x16x32_bf16 v[82:85], v[228:231], v[184:187], v[82:85]
	v_mfma_f32_16x16x32_bf16 v[70:73], v[220:223], v[212:215], v[70:73]
	v_mfma_f32_16x16x32_bf16 v[66:69], v[228:231], v[212:215], v[66:69]
	s_setprio 0
	s_mov_b32 m0, s46
	s_barrier
; #define PG8_STAGE(bufoff, gbase, voff) do { _Pragma("unroll") for (int _i = 0; _i < 2; ++_i) \
;     __builtin_amdgcn_global_load_lds((const unsigned*)((const char*)(gbase) + (voff)[_i]), (LAS unsigned*)(lds + (bufoff) + ldsw + _i * 8192), 16, 0, 0); } while (0)
; #define PG8_LDA(dst, b, h) do { _Pragma("unroll") for (int m = 0; m < 4; ++m) _Pragma("unroll") for (int k = 0; k < 2; ++k) dst[m][k] = *(const LAS bf16x8*)(lds + PG8_SA(b, h) + aoff + m * 2048 + k * 1024); } while (0)
; #define PG8_MMA(ai, bj, At, Bt) do { __builtin_amdgcn_s_setprio(1); _Pragma("unroll") for (int m = 0; m < 4; ++m) _Pragma("unroll") for (int n = 0; n < 2; ++n) _Pragma("unroll") for (int k = 0; k < 2; ++k) \
;     acc[ai][bj][m][n] = __builtin_amdgcn_mfma_f32_16x16x32_bf16(Bt[n][k], At[m][k], acc[ai][bj][m][n], 0, 0, 0); __builtin_amdgcn_s_setprio(0); } while (0)
; #define PG8_WAIT_V(n) asm volatile("s_waitcnt vmcnt(" #n ")" ::: "memory")
; #define PG8_WAIT_L(n) asm volatile("s_waitcnt lgkmcnt(" #n ")" ::: "memory")
; #define PG8_BAR __builtin_amdgcn_s_barrier()
; #define PG8_SCHED __builtin_amdgcn_sched_barrier(0)
; __device__ __forceinline__ u32x4 pack8(const f32x4 v0, const f32x4 v1) { u32x4 w; w.x = cvtpk(v0[0], v0[1]); w.y = cvtpk(v0[2], v0[3]); w.z = cvtpk(v1[0], v1[1]); w.w = cvtpk(v1[2], v1[3]); return w; }
; template <class Epi, bool SPLITA = false>
; __device__ __forceinline__ void gemm_phase(const int tid, LAS unsigned char* lds, const Gemm g, const Order& S, const Epi& E) {
;     ...
;       PG8_LDA(At, 1, 1); PG8_STAGE(PG8_SA(1, 0), a3, voffA);
;       PG8_BAR; PG8_WAIT_L(0); PG8_MMA(1, 0, At, B0); PG8_BAR; PG8_SCHED;
;       PG8_STAGE(PG8_SB(1, 1), b3 + hstepB, voffB);
;       PG8_WAIT_V(6); PG8_BAR; PG8_MMA(1, 1, At, B1); PG8_BAR;
;   __device__ __forceinline__ void operator()(const Acc& acc, const Unit& u, int wr, int wc, int fr_, int fq_) const {
;     ...
;     const int z = u.pn >> 2, b = z >> 4, k1 = z & 15, j0 = (u.pn & 3) * 256 + wc * 32 + 8 * fq;
;     const int r0 = u.pm * BM + wr * 64 + fr;
; #pragma unroll
;     for (int ai = 0; ai < 2; ++ai)
; #pragma unroll
;       for (int m = 0; m < 4; ++m) { const int k2 = r0 + ai * HALF + m * 16;
;         if (k2 < FN2) { bf16_t* rowp = F + (size_t)row_of(b, k1 + 16 * k2) * 1024 + j0;
; #pragma unroll
;           for (int bj = 0; bj < 2; ++bj) *(u32x4*)(rowp + bj * HALF) = pack8(acc[ai][bj][m][0], acc[ai][bj][m][1]); } }
	ds_read_b128 v[164:167], v147 offset:49152
	ds_read_b128 v[168:171], v147 offset:50176
	ds_read_b128 v[172:175], v147 offset:51200
	ds_read_b128 v[176:179], v147 offset:52224
	ds_read_b128 v[180:183], v147 offset:53248
	ds_read_b128 v[184:187], v147 offset:54272
	ds_read_b128 v[188:191], v147 offset:55296
	ds_read_b128 v[212:215], v147 offset:56320
	global_load_lds_dwordx4 v130, s[14:15]
	s_mov_b32 m0, s47
	s_nop 0
	global_load_lds_dwordx4 v132, s[14:15]
	s_barrier
	s_waitcnt lgkmcnt(0)
	s_setprio 1
	s_waitcnt lgkmcnt(0)
	v_mfma_f32_16x16x32_bf16 v[62:65], v[148:151], v[164:167], v[62:65]
	v_mfma_f32_16x16x32_bf16 v[58:61], v[156:159], v[164:167], v[58:61]
	v_mfma_f32_16x16x32_bf16 v[46:49], v[148:151], v[172:175], v[46:49]
	v_mfma_f32_16x16x32_bf16 v[42:45], v[156:159], v[172:175], v[42:45]
	v_mfma_f32_16x16x32_bf16 v[30:33], v[148:151], v[180:183], v[30:33]
	v_mfma_f32_16x16x32_bf16 v[26:29], v[156:159], v[180:183], v[26:29]
	v_mfma_f32_16x16x32_bf16 v[14:17], v[148:151], v[188:191], v[14:17]
	v_mfma_f32_16x16x32_bf16 v[10:13], v[156:159], v[188:191], v[10:13]
	v_mfma_f32_16x16x32_bf16 v[62:65], v[152:155], v[168:171], v[62:65]
	v_mfma_f32_16x16x32_bf16 v[58:61], v[160:163], v[168:171], v[58:61]
	v_mfma_f32_16x16x32_bf16 v[46:49], v[152:155], v[176:179], v[46:49]
	v_mfma_f32_16x16x32_bf16 v[42:45], v[160:163], v[176:179], v[42:45]
	v_mfma_f32_16x16x32_bf16 v[30:33], v[152:155], v[184:187], v[30:33]
	v_mfma_f32_16x16x32_bf16 v[26:29], v[160:163], v[184:187], v[26:29]
	v_mfma_f32_16x16x32_bf16 v[14:17], v[152:155], v[212:215], v[14:17]
	v_mfma_f32_16x16x32_bf16 v[10:13], v[160:163], v[212:215], v[10:13]
	s_setprio 0
	s_barrier
	s_add_u32 s12, s12, 0x88080
	s_addc_u32 s13, s13, 0
	s_add_i32 s14, s16, s18
	s_mov_b32 m0, s14
	s_nop 0
	global_load_lds_dwordx4 v0, s[12:13]
	s_add_i32 m0, s14, 0x2000
	s_nop 0
	global_load_lds_dwordx4 v134, s[12:13]
	s_waitcnt vmcnt(6)
	s_barrier
	s_setprio 1
	v_mfma_f32_16x16x32_bf16 v[54:57], v[216:219], v[164:167], v[54:57]
	v_mfma_f32_16x16x32_bf16 v[50:53], v[224:227], v[164:167], v[50:53]
	v_mfma_f32_16x16x32_bf16 v[38:41], v[216:219], v[172:175], v[38:41]
	v_mfma_f32_16x16x32_bf16 v[34:37], v[224:227], v[172:175], v[34:37]
	v_mfma_f32_16x16x32_bf16 v[22:25], v[216:219], v[180:183], v[22:25]
	v_mfma_f32_16x16x32_bf16 v[18:21], v[224:227], v[180:183], v[18:21]
	v_mfma_f32_16x16x32_bf16 v[6:9], v[216:219], v[188:191], v[6:9]
	v_mfma_f32_16x16x32_bf16 v[2:5], v[224:227], v[188:191], v[2:5]
	v_mfma_f32_16x16x32_bf16 v[54:57], v[220:223], v[168:171], v[54:57]
	v_mfma_f32_16x16x32_bf16 v[50:53], v[228:231], v[168:171], v[50:53]
	v_mfma_f32_16x16x32_bf16 v[38:41], v[220:223], v[176:179], v[38:41]
	v_mfma_f32_16x16x32_bf16 v[34:37], v[228:231], v[176:179], v[34:37]
	v_mfma_f32_16x16x32_bf16 v[22:25], v[220:223], v[184:187], v[22:25]
	v_mfma_f32_16x16x32_bf16 v[18:21], v[228:231], v[184:187], v[18:21]
	v_mfma_f32_16x16x32_bf16 v[6:9], v[220:223], v[212:215], v[6:9]
	v_mfma_f32_16x16x32_bf16 v[2:5], v[228:231], v[212:215], v[2:5]
	s_setprio 0
	s_add_i32 s91, s91, 2
	s_add_u32 s10, s10, 0x100
	s_addc_u32 s11, s11, 0
	s_cmp_gt_u32 s91, 31
	s_barrier
	s_cbranch_scc0 .LBB0_328
	s_lshl_b32 s10, s51, 8
	v_mov_b32_e32 v141, v145
	v_mov_b32_e32 v140, v144
	s_and_b32 s10, s10, 0x300
	s_or_b32 s10, s10, s45
	v_lshl_add_u32 v140, v140, 3, s10
	s_lshl_b32 s10, s52, 8
	s_ashr_i32 s8, s51, 6
	s_add_i32 s10, s10, s44
	s_bfe_u32 s9, s51, 0x40002
	v_add_u32_e32 v142, s10, v141
	s_lshl_b32 s10, s8, 14
	s_lshl_b32 s11, s8, 4
	s_movk_i32 s8, 0x401
	s_add_i32 s10, s10, -16
	s_add_i32 s11, s11, 0x8000
	v_ashrrev_i32_e32 v141, 31, v140
	v_cmp_gt_i32_e32 vcc, s8, v142
	v_lshl_or_b32 v143, v142, 4, s9
	s_and_saveexec_b64 s[8:9], vcc
	s_cbranch_execz .LBB0_331
	v_mov_b32_e32 v148, s10
	v_mov_b32_e32 v149, s11
	v_cmp_gt_i32_e32 vcc, 16, v143
	v_readlane_b32 s12, v255, 1
	v_readlane_b32 s13, v255, 2
	v_cndmask_b32_e32 v148, v148, v149, vcc
	v_add_u32_e32 v148, v148, v143
	v_ashrrev_i32_e32 v149, 31, v148
	v_lshlrev_b64 v[148:149], 11, v[148:149]
	v_lshl_add_u64 v[148:149], s[12:13], 0, v[148:149]
	v_lshl_add_u64 v[148:149], v[140:141], 1, v[148:149]
	v_cvt_pk_bf16_f32 v126, v126, v127
	v_cvt_pk_bf16_f32 v127, v128, v129
	v_cvt_pk_bf16_f32 v128, v122, v123
	v_cvt_pk_bf16_f32 v129, v124, v125
	v_cvt_pk_bf16_f32 v118, v118, v119
	v_cvt_pk_bf16_f32 v119, v120, v121
	v_cvt_pk_bf16_f32 v120, v114, v115
	v_cvt_pk_bf16_f32 v121, v116, v117
	global_store_dwordx4 v[148:149], v[126:129], off
	global_store_dwordx4 v[148:149], v[118:121], off offset:256

; #define PG8_STAGE(bufoff, gbase, voff) do { _Pragma("unroll") for (int _i = 0; _i < 2; ++_i) \
;     __builtin_amdgcn_global_load_lds((const unsigned*)((const char*)(gbase) + (voff)[_i]), (LAS unsigned*)(lds + (bufoff) + ldsw + _i * 8192), 16, 0, 0); } while (0)
; #define PG8_LDA(dst, b, h) do { _Pragma("unroll") for (int m = 0; m < 4; ++m) _Pragma("unroll") for (int k = 0; k < 2; ++k) dst[m][k] = *(const LAS bf16x8*)(lds + PG8_SA(b, h) + aoff + m * 2048 + k * 1024); } while (0)
; #define PG8_LDB(dst, b, h) do { _Pragma("unroll") for (int n = 0; n < 2; ++n) _Pragma("unroll") for (int k = 0; k < 2; ++k) dst[n][k] = *(const LAS bf16x8*)(lds + PG8_SB(b, h) + boff + n * 2048 + k * 1024); } while (0)
; #define PG8_MMA(ai, bj, At, Bt) do { __builtin_amdgcn_s_setprio(1); _Pragma("unroll") for (int m = 0; m < 4; ++m) _Pragma("unroll") for (int n = 0; n < 2; ++n) _Pragma("unroll") for (int k = 0; k < 2; ++k) \
;     acc[ai][bj][m][n] = __builtin_amdgcn_mfma_f32_16x16x32_bf16(Bt[n][k], At[m][k], acc[ai][bj][m][n], 0, 0, 0); __builtin_amdgcn_s_setprio(0); } while (0)
; #define PG8_WAIT_L(n) asm volatile("s_waitcnt lgkmcnt(" #n ")" ::: "memory")
; #define PG8_BAR __builtin_amdgcn_s_barrier()
; #define PG8_SCHED __builtin_amdgcn_sched_barrier(0)
; template <class Epi, bool SPLITA = false>
; __device__ __forceinline__ void gemm_phase(const int tid, LAS unsigned char* lds, const Gemm g, const Order& S, const Epi& E) {
;     ...
;       const char* a1 = PG8_TA(t + 1);
;       const char* a2 = last ? nA : PG8_TA(t + 2); const char* b2 = last ? nB : cB + (size_t)(t + 2) * kstep;
;       const char* a3 = last ? nA + kstep : PG8_TA(t + 3); const char* b3 = b2 + kstep;
;       PG8_LDB(B0, 0, 0); PG8_SCHED; PG8_LDA(At, 0, 0); PG8_STAGE(PG8_SA(1, 1), a1 + hstepA, voffA);
;       PG8_WAIT_L(8); PG8_BAR; PG8_WAIT_L(0); PG8_MMA(0, 0, At, B0); PG8_BAR; PG8_SCHED;
;       PG8_LDB(B1, 0, 1); PG8_STAGE(PG8_SB(0, 0), b2, voffB);
;       PG8_BAR; PG8_WAIT_L(0); PG8_MMA(0, 1, At, B1); PG8_BAR;
;       PG8_LDA(At, 0, 1); PG8_STAGE(PG8_SA(0, 0), a2, voffA);
;       PG8_BAR; PG8_WAIT_L(0); PG8_MMA(1, 0, At, B0); PG8_BAR; PG8_SCHED;
.LBB0_400:
	s_add_i32 s29, s18, 2
	s_add_u32 s16, s14, 0x100
	s_addc_u32 s17, s15, 0
	s_add_u32 s19, s12, s14
	s_addc_u32 s20, s13, s15
	s_add_u32 s21, s19, 0x100
	s_addc_u32 s22, s20, 0
	s_add_u32 s19, s19, 0x180
	s_addc_u32 s20, s20, 0
	s_add_i32 s23, 0, 0x10000
	v_add_u32_e32 v160, s23, v146
	ds_read_b128 v[148:151], v160
	ds_read_b128 v[152:155], v160 offset:1024
	ds_read_b128 v[156:159], v160 offset:2048
	ds_read_b128 v[160:163], v160 offset:3072
	s_cmp_eq_u32 s52, s18
	s_cselect_b32 s18, 0, s16
	s_cselect_b32 s41, s11, s20
	s_cselect_b32 s40, s9, s19
	s_cselect_b32 s19, 0, s17
	s_cselect_b32 s42, s0, s21
	s_cselect_b32 s43, s1, s22
	s_add_u32 s18, s6, s18
	s_addc_u32 s19, s7, s19
	v_lshl_add_u64 v[192:193], v[140:141], 0, s[14:15]
	s_add_i32 m0, s30, 0xc000
	ds_read_b128 v[164:167], v147
	ds_read_b128 v[168:171], v147 offset:1024
	ds_read_b128 v[172:175], v147 offset:2048
	ds_read_b128 v[176:179], v147 offset:3072
	ds_read_b128 v[180:183], v147 offset:4096
	ds_read_b128 v[184:187], v147 offset:5120
	ds_read_b128 v[188:191], v147 offset:6144
	ds_read_b128 v[212:215], v147 offset:7168
	global_load_lds_dwordx4 v[192:193], off
	v_lshl_add_u64 v[192:193], v[142:143], 0, s[14:15]
	s_add_i32 m0, s30, 0xe000
	s_nop 0
	global_load_lds_dwordx4 v[192:193], off
	s_waitcnt lgkmcnt(8)
	s_barrier
	s_waitcnt lgkmcnt(0)
	s_setprio 1
	s_waitcnt lgkmcnt(0)
	v_mfma_f32_16x16x32_bf16 v[122:125], v[148:151], v[164:167], v[122:125]
	v_mfma_f32_16x16x32_bf16 v[126:129], v[156:159], v[164:167], v[126:129]
	v_mfma_f32_16x16x32_bf16 v[110:113], v[148:151], v[172:175], v[110:113]
	v_mfma_f32_16x16x32_bf16 v[106:109], v[156:159], v[172:175], v[106:109]
	v_mfma_f32_16x16x32_bf16 v[94:97], v[148:151], v[180:183], v[94:97]
	v_mfma_f32_16x16x32_bf16 v[90:93], v[156:159], v[180:183], v[90:93]
	v_mfma_f32_16x16x32_bf16 v[78:81], v[148:151], v[188:191], v[78:81]
	v_mfma_f32_16x16x32_bf16 v[74:77], v[156:159], v[188:191], v[74:77]
	v_mfma_f32_16x16x32_bf16 v[122:125], v[152:155], v[168:171], v[122:125]
	v_mfma_f32_16x16x32_bf16 v[126:129], v[160:163], v[168:171], v[126:129]
	v_mfma_f32_16x16x32_bf16 v[110:113], v[152:155], v[176:179], v[110:113]
	v_mfma_f32_16x16x32_bf16 v[106:109], v[160:163], v[176:179], v[106:109]
	v_mfma_f32_16x16x32_bf16 v[94:97], v[152:155], v[184:187], v[94:97]
	v_mfma_f32_16x16x32_bf16 v[90:93], v[160:163], v[184:187], v[90:93]
	v_mfma_f32_16x16x32_bf16 v[78:81], v[152:155], v[212:215], v[78:81]
	v_mfma_f32_16x16x32_bf16 v[74:77], v[160:163], v[212:215], v[74:77]
	s_setprio 0
	s_barrier
	s_add_i32 s20, 0, 0x14000
	v_add_u32_e32 v192, s20, v146
	s_add_i32 s14, s23, s28
	ds_read_b128 v[216:219], v192
	ds_read_b128 v[220:223], v192 offset:1024
	ds_read_b128 v[224:227], v192 offset:2048
	ds_read_b128 v[228:231], v192 offset:3072
	s_mov_b32 m0, s14
	s_nop 0
	global_load_lds_dwordx4 v134, s[18:19]
	s_add_i32 m0, s14, 0x2000
	s_nop 0
	global_load_lds_dwordx4 v130, s[18:19]
	s_barrier
	s_waitcnt lgkmcnt(0)
	s_setprio 1
	s_waitcnt lgkmcnt(0)
	v_mfma_f32_16x16x32_bf16 v[118:121], v[216:219], v[164:167], v[118:121]
	v_mfma_f32_16x16x32_bf16 v[114:117], v[224:227], v[164:167], v[114:117]
	v_mfma_f32_16x16x32_bf16 v[102:105], v[216:219], v[172:175], v[102:105]
	v_mfma_f32_16x16x32_bf16 v[98:101], v[224:227], v[172:175], v[98:101]
	v_mfma_f32_16x16x32_bf16 v[86:89], v[216:219], v[180:183], v[86:89]
	v_mfma_f32_16x16x32_bf16 v[82:85], v[224:227], v[180:183], v[82:85]
	v_mfma_f32_16x16x32_bf16 v[70:73], v[216:219], v[188:191], v[70:73]
	v_mfma_f32_16x16x32_bf16 v[66:69], v[224:227], v[188:191], v[66:69]
	v_mfma_f32_16x16x32_bf16 v[118:121], v[220:223], v[168:171], v[118:121]
	v_mfma_f32_16x16x32_bf16 v[114:117], v[228:231], v[168:171], v[114:117]
	v_mfma_f32_16x16x32_bf16 v[102:105], v[220:223], v[176:179], v[102:105]
	v_mfma_f32_16x16x32_bf16 v[98:101], v[228:231], v[176:179], v[98:101]
	v_mfma_f32_16x16x32_bf16 v[86:89], v[220:223], v[184:187], v[86:89]
	v_mfma_f32_16x16x32_bf16 v[82:85], v[228:231], v[184:187], v[82:85]
	v_mfma_f32_16x16x32_bf16 v[70:73], v[220:223], v[212:215], v[70:73]
	v_mfma_f32_16x16x32_bf16 v[66:69], v[228:231], v[212:215], v[66:69]
	s_setprio 0
	s_mov_b32 m0, s30
	s_barrier
	ds_read_b128 v[164:167], v147 offset:16384
	ds_read_b128 v[168:171], v147 offset:17408
	ds_read_b128 v[172:175], v147 offset:18432
	ds_read_b128 v[176:179], v147 offset:19456
	ds_read_b128 v[180:183], v147 offset:20480
	ds_read_b128 v[184:187], v147 offset:21504
	ds_read_b128 v[188:191], v147 offset:22528
	ds_read_b128 v[212:215], v147 offset:23552
	global_load_lds_dwordx4 v0, s[42:43]
	s_mov_b32 m0, s31
	s_nop 0
	global_load_lds_dwordx4 v132, s[42:43]
	s_barrier
	s_waitcnt lgkmcnt(0)
	s_setprio 1
	s_waitcnt lgkmcnt(0)
	v_mfma_f32_16x16x32_bf16 v[62:65], v[148:151], v[164:167], v[62:65]
	v_mfma_f32_16x16x32_bf16 v[58:61], v[156:159], v[164:167], v[58:61]
	v_mfma_f32_16x16x32_bf16 v[46:49], v[148:151], v[172:175], v[46:49]
	v_mfma_f32_16x16x32_bf16 v[42:45], v[156:159], v[172:175], v[42:45]
	v_mfma_f32_16x16x32_bf16 v[30:33], v[148:151], v[180:183], v[30:33]
	v_mfma_f32_16x16x32_bf16 v[26:29], v[156:159], v[180:183], v[26:29]
	v_mfma_f32_16x16x32_bf16 v[14:17], v[148:151], v[188:191], v[14:17]
	v_mfma_f32_16x16x32_bf16 v[10:13], v[156:159], v[188:191], v[10:13]
	v_mfma_f32_16x16x32_bf16 v[62:65], v[152:155], v[168:171], v[62:65]
	v_mfma_f32_16x16x32_bf16 v[58:61], v[160:163], v[168:171], v[58:61]
	v_mfma_f32_16x16x32_bf16 v[46:49], v[152:155], v[176:179], v[46:49]
	v_mfma_f32_16x16x32_bf16 v[42:45], v[160:163], v[176:179], v[42:45]
	v_mfma_f32_16x16x32_bf16 v[30:33], v[152:155], v[184:187], v[30:33]
	v_mfma_f32_16x16x32_bf16 v[26:29], v[160:163], v[184:187], v[26:29]
	v_mfma_f32_16x16x32_bf16 v[14:17], v[152:155], v[212:215], v[14:17]
	v_mfma_f32_16x16x32_bf16 v[10:13], v[160:163], v[212:215], v[10:13]
	s_setprio 0
	s_barrier
; #define PG8_STAGE(bufoff, gbase, voff) do { _Pragma("unroll") for (int _i = 0; _i < 2; ++_i) \
;     __builtin_amdgcn_global_load_lds((const unsigned*)((const char*)(gbase) + (voff)[_i]), (LAS unsigned*)(lds + (bufoff) + ldsw + _i * 8192), 16, 0, 0); } while (0)
; #define PG8_LDA(dst, b, h) do { _Pragma("unroll") for (int m = 0; m < 4; ++m) _Pragma("unroll") for (int k = 0; k < 2; ++k) dst[m][k] = *(const LAS bf16x8*)(lds + PG8_SA(b, h) + aoff + m * 2048 + k * 1024); } while (0)
; #define PG8_LDB(dst, b, h) do { _Pragma("unroll") for (int n = 0; n < 2; ++n) _Pragma("unroll") for (int k = 0; k < 2; ++k) dst[n][k] = *(const LAS bf16x8*)(lds + PG8_SB(b, h) + boff + n * 2048 + k * 1024); } while (0)
; #define PG8_MMA(ai, bj, At, Bt) do { __builtin_amdgcn_s_setprio(1); _Pragma("unroll") for (int m = 0; m < 4; ++m) _Pragma("unroll") for (int n = 0; n < 2; ++n) _Pragma("unroll") for (int k = 0; k < 2; ++k) \
;     acc[ai][bj][m][n] = __builtin_amdgcn_mfma_f32_16x16x32_bf16(Bt[n][k], At[m][k], acc[ai][bj][m][n], 0, 0, 0); __builtin_amdgcn_s_setprio(0); } while (0)
; #define PG8_WAIT_V(n) asm volatile("s_waitcnt vmcnt(" #n ")" ::: "memory")
; #define PG8_WAIT_L(n) asm volatile("s_waitcnt lgkmcnt(" #n ")" ::: "memory")
; #define PG8_BAR __builtin_amdgcn_s_barrier()
; #define PG8_SCHED __builtin_amdgcn_sched_barrier(0)
; template <class Epi, bool SPLITA = false>
; __device__ __forceinline__ void gemm_phase(const int tid, LAS unsigned char* lds, const Gemm g, const Order& S, const Epi& E) {
;     ...
;       PG8_STAGE(PG8_SB(0, 1), b2 + hstepB, voffB);
;       PG8_WAIT_V(6); PG8_BAR; PG8_MMA(1, 1, At, B1); PG8_BAR;
;       PG8_LDB(B0, 1, 0); PG8_SCHED; PG8_LDA(At, 1, 0); PG8_STAGE(PG8_SA(0, 1), a2 + hstepA, voffA);
;       PG8_WAIT_L(8); PG8_BAR; PG8_WAIT_L(0); PG8_MMA(0, 0, At, B0); PG8_BAR; PG8_SCHED;
;       PG8_LDB(B1, 1, 1); PG8_STAGE(PG8_SB(1, 0), b3, voffB);
	s_add_u32 s14, s18, 0x8000
	s_addc_u32 s15, s19, 0
	s_add_i32 s20, s20, s28
	s_mov_b32 m0, s20
	s_nop 0
	global_load_lds_dwordx4 v134, s[14:15]
	s_add_i32 m0, s20, 0x2000
	s_nop 0
	global_load_lds_dwordx4 v130, s[14:15]
	s_waitcnt vmcnt(6)
	s_barrier
	s_setprio 1
	v_mfma_f32_16x16x32_bf16 v[54:57], v[216:219], v[164:167], v[54:57]
	v_mfma_f32_16x16x32_bf16 v[50:53], v[224:227], v[164:167], v[50:53]
	v_mfma_f32_16x16x32_bf16 v[38:41], v[216:219], v[172:175], v[38:41]
	v_mfma_f32_16x16x32_bf16 v[34:37], v[224:227], v[172:175], v[34:37]
	v_mfma_f32_16x16x32_bf16 v[22:25], v[216:219], v[180:183], v[22:25]
	v_mfma_f32_16x16x32_bf16 v[18:21], v[224:227], v[180:183], v[18:21]
	v_mfma_f32_16x16x32_bf16 v[6:9], v[216:219], v[188:191], v[6:9]
	v_mfma_f32_16x16x32_bf16 v[2:5], v[224:227], v[188:191], v[2:5]
	v_mfma_f32_16x16x32_bf16 v[54:57], v[220:223], v[168:171], v[54:57]
	v_mfma_f32_16x16x32_bf16 v[50:53], v[228:231], v[168:171], v[50:53]
	v_mfma_f32_16x16x32_bf16 v[38:41], v[220:223], v[176:179], v[38:41]
	v_mfma_f32_16x16x32_bf16 v[34:37], v[228:231], v[176:179], v[34:37]
	v_mfma_f32_16x16x32_bf16 v[22:25], v[220:223], v[184:187], v[22:25]
	v_mfma_f32_16x16x32_bf16 v[18:21], v[228:231], v[184:187], v[18:21]
	v_mfma_f32_16x16x32_bf16 v[6:9], v[220:223], v[212:215], v[6:9]
	v_mfma_f32_16x16x32_bf16 v[2:5], v[228:231], v[212:215], v[2:5]
	s_setprio 0
	s_add_i32 s20, 0, 0x18000
	v_add_u32_e32 v160, s20, v146
	s_barrier
	ds_read_b128 v[148:151], v160
	ds_read_b128 v[152:155], v160 offset:1024
	ds_read_b128 v[156:159], v160 offset:2048
	ds_read_b128 v[160:163], v160 offset:3072
	s_add_u32 s14, s42, 0x40000
	s_addc_u32 s15, s43, 0
	s_mov_b32 m0, s44
	ds_read_b128 v[164:167], v147 offset:32768
	ds_read_b128 v[168:171], v147 offset:33792
	ds_read_b128 v[172:175], v147 offset:34816
	ds_read_b128 v[176:179], v147 offset:35840
	ds_read_b128 v[180:183], v147 offset:36864
	ds_read_b128 v[184:187], v147 offset:37888
	ds_read_b128 v[188:191], v147 offset:38912
	ds_read_b128 v[212:215], v147 offset:39936
	global_load_lds_dwordx4 v0, s[14:15]
	s_mov_b32 m0, s45
	s_nop 0
	global_load_lds_dwordx4 v132, s[14:15]
	s_waitcnt lgkmcnt(8)
	s_barrier
	s_waitcnt lgkmcnt(0)
	s_setprio 1
	s_waitcnt lgkmcnt(0)
	v_mfma_f32_16x16x32_bf16 v[122:125], v[148:151], v[164:167], v[122:125]
	v_mfma_f32_16x16x32_bf16 v[126:129], v[156:159], v[164:167], v[126:129]
	v_mfma_f32_16x16x32_bf16 v[110:113], v[148:151], v[172:175], v[110:113]
	v_mfma_f32_16x16x32_bf16 v[106:109], v[156:159], v[172:175], v[106:109]
	v_mfma_f32_16x16x32_bf16 v[94:97], v[148:151], v[180:183], v[94:97]
	v_mfma_f32_16x16x32_bf16 v[90:93], v[156:159], v[180:183], v[90:93]
	v_mfma_f32_16x16x32_bf16 v[78:81], v[148:151], v[188:191], v[78:81]
	v_mfma_f32_16x16x32_bf16 v[74:77], v[156:159], v[188:191], v[74:77]
	v_mfma_f32_16x16x32_bf16 v[122:125], v[152:155], v[168:171], v[122:125]
	v_mfma_f32_16x16x32_bf16 v[126:129], v[160:163], v[168:171], v[126:129]
	v_mfma_f32_16x16x32_bf16 v[110:113], v[152:155], v[176:179], v[110:113]
	v_mfma_f32_16x16x32_bf16 v[106:109], v[160:163], v[176:179], v[106:109]
	v_mfma_f32_16x16x32_bf16 v[94:97], v[152:155], v[184:187], v[94:97]
	v_mfma_f32_16x16x32_bf16 v[90:93], v[160:163], v[184:187], v[90:93]
	v_mfma_f32_16x16x32_bf16 v[78:81], v[152:155], v[212:215], v[78:81]
	v_mfma_f32_16x16x32_bf16 v[74:77], v[160:163], v[212:215], v[74:77]
	s_setprio 0
	s_barrier
	s_add_i32 s21, 0, 0x1c000
	s_add_i32 s14, s20, s28
	v_add_u32_e32 v195, s21, v146
	s_add_i32 m0, s14, 0xffffff80
	ds_read_b128 v[216:219], v195
	ds_read_b128 v[220:223], v195 offset:1024
	ds_read_b128 v[224:227], v195 offset:2048
	ds_read_b128 v[228:231], v195 offset:3072
	global_load_lds_dwordx4 v134, s[18:19] offset:128
	s_add_i32 m0, s14, 0x1f80
	s_nop 0
	global_load_lds_dwordx4 v130, s[18:19] offset:128
	s_barrier
; #define PG8_STAGE(bufoff, gbase, voff) do { _Pragma("unroll") for (int _i = 0; _i < 2; ++_i) \
;     __builtin_amdgcn_global_load_lds((const unsigned*)((const char*)(gbase) + (voff)[_i]), (LAS unsigned*)(lds + (bufoff) + ldsw + _i * 8192), 16, 0, 0); } while (0)
; #define PG8_LDA(dst, b, h) do { _Pragma("unroll") for (int m = 0; m < 4; ++m) _Pragma("unroll") for (int k = 0; k < 2; ++k) dst[m][k] = *(const LAS bf16x8*)(lds + PG8_SA(b, h) + aoff + m * 2048 + k * 1024); } while (0)
; #define PG8_MMA(ai, bj, At, Bt) do { __builtin_amdgcn_s_setprio(1); _Pragma("unroll") for (int m = 0; m < 4; ++m) _Pragma("unroll") for (int n = 0; n < 2; ++n) _Pragma("unroll") for (int k = 0; k < 2; ++k) \
;     acc[ai][bj][m][n] = __builtin_amdgcn_mfma_f32_16x16x32_bf16(Bt[n][k], At[m][k], acc[ai][bj][m][n], 0, 0, 0); __builtin_amdgcn_s_setprio(0); } while (0)
; #define PG8_WAIT_V(n) asm volatile("s_waitcnt vmcnt(" #n ")" ::: "memory")
; #define PG8_WAIT_L(n) asm volatile("s_waitcnt lgkmcnt(" #n ")" ::: "memory")
; #define PG8_BAR __builtin_amdgcn_s_barrier()
; #define PG8_SCHED __builtin_amdgcn_sched_barrier(0)
; template <class Epi, bool SPLITA = false>
; __device__ __forceinline__ void gemm_phase(const int tid, LAS unsigned char* lds, const Gemm g, const Order& S, const Epi& E) {
;     ...
;       PG8_BAR; PG8_WAIT_L(0); PG8_MMA(0, 1, At, B1); PG8_BAR;
;       PG8_LDA(At, 1, 1); PG8_STAGE(PG8_SA(1, 0), a3, voffA);
;       PG8_BAR; PG8_WAIT_L(0); PG8_MMA(1, 0, At, B0); PG8_BAR; PG8_SCHED;
;       PG8_STAGE(PG8_SB(1, 1), b3 + hstepB, voffB);
;       PG8_WAIT_V(6); PG8_BAR; PG8_MMA(1, 1, At, B1); PG8_BAR;
	s_waitcnt lgkmcnt(0)
	s_setprio 1
	s_waitcnt lgkmcnt(0)
	v_mfma_f32_16x16x32_bf16 v[118:121], v[216:219], v[164:167], v[118:121]
	v_mfma_f32_16x16x32_bf16 v[114:117], v[224:227], v[164:167], v[114:117]
	v_mfma_f32_16x16x32_bf16 v[102:105], v[216:219], v[172:175], v[102:105]
	v_mfma_f32_16x16x32_bf16 v[98:101], v[224:227], v[172:175], v[98:101]
	v_mfma_f32_16x16x32_bf16 v[86:89], v[216:219], v[180:183], v[86:89]
	v_mfma_f32_16x16x32_bf16 v[82:85], v[224:227], v[180:183], v[82:85]
	v_mfma_f32_16x16x32_bf16 v[70:73], v[216:219], v[188:191], v[70:73]
	v_mfma_f32_16x16x32_bf16 v[66:69], v[224:227], v[188:191], v[66:69]
	v_mfma_f32_16x16x32_bf16 v[118:121], v[220:223], v[168:171], v[118:121]
	v_mfma_f32_16x16x32_bf16 v[114:117], v[228:231], v[168:171], v[114:117]
	v_mfma_f32_16x16x32_bf16 v[102:105], v[220:223], v[176:179], v[102:105]
	v_mfma_f32_16x16x32_bf16 v[98:101], v[228:231], v[176:179], v[98:101]
	v_mfma_f32_16x16x32_bf16 v[86:89], v[220:223], v[184:187], v[86:89]
	v_mfma_f32_16x16x32_bf16 v[82:85], v[228:231], v[184:187], v[82:85]
	v_mfma_f32_16x16x32_bf16 v[70:73], v[220:223], v[212:215], v[70:73]
	v_mfma_f32_16x16x32_bf16 v[66:69], v[228:231], v[212:215], v[66:69]
	s_setprio 0
	s_mov_b32 m0, s49
	s_barrier
	ds_read_b128 v[164:167], v147 offset:49152
	ds_read_b128 v[168:171], v147 offset:50176
	ds_read_b128 v[172:175], v147 offset:51200
	ds_read_b128 v[176:179], v147 offset:52224
	ds_read_b128 v[180:183], v147 offset:53248
	ds_read_b128 v[184:187], v147 offset:54272
	ds_read_b128 v[188:191], v147 offset:55296
	ds_read_b128 v[212:215], v147 offset:56320
	global_load_lds_dwordx4 v0, s[40:41]
	s_mov_b32 m0, s51
	s_nop 0
	global_load_lds_dwordx4 v132, s[40:41]
	s_barrier
	s_waitcnt lgkmcnt(0)
	s_setprio 1
	s_waitcnt lgkmcnt(0)
	v_mfma_f32_16x16x32_bf16 v[62:65], v[148:151], v[164:167], v[62:65]
	v_mfma_f32_16x16x32_bf16 v[58:61], v[156:159], v[164:167], v[58:61]
	v_mfma_f32_16x16x32_bf16 v[46:49], v[148:151], v[172:175], v[46:49]
	v_mfma_f32_16x16x32_bf16 v[42:45], v[156:159], v[172:175], v[42:45]
	v_mfma_f32_16x16x32_bf16 v[30:33], v[148:151], v[180:183], v[30:33]
	v_mfma_f32_16x16x32_bf16 v[26:29], v[156:159], v[180:183], v[26:29]
	v_mfma_f32_16x16x32_bf16 v[14:17], v[148:151], v[188:191], v[14:17]
	v_mfma_f32_16x16x32_bf16 v[10:13], v[156:159], v[188:191], v[10:13]
	v_mfma_f32_16x16x32_bf16 v[62:65], v[152:155], v[168:171], v[62:65]
	v_mfma_f32_16x16x32_bf16 v[58:61], v[160:163], v[168:171], v[58:61]
	v_mfma_f32_16x16x32_bf16 v[46:49], v[152:155], v[176:179], v[46:49]
	v_mfma_f32_16x16x32_bf16 v[42:45], v[160:163], v[176:179], v[42:45]
	v_mfma_f32_16x16x32_bf16 v[30:33], v[152:155], v[184:187], v[30:33]
	v_mfma_f32_16x16x32_bf16 v[26:29], v[160:163], v[184:187], v[26:29]
	v_mfma_f32_16x16x32_bf16 v[14:17], v[152:155], v[212:215], v[14:17]
	v_mfma_f32_16x16x32_bf16 v[10:13], v[160:163], v[212:215], v[10:13]
	s_setprio 0
	s_barrier
	s_add_u32 s14, s18, 0x8080
	s_addc_u32 s15, s19, 0
	s_add_i32 s18, s21, s28
	s_mov_b32 m0, s18
	s_nop 0
	global_load_lds_dwordx4 v134, s[14:15]
	s_add_i32 m0, s18, 0x2000
	s_nop 0
	global_load_lds_dwordx4 v130, s[14:15]
	s_waitcnt vmcnt(6)
	s_barrier
	s_setprio 1
	v_mfma_f32_16x16x32_bf16 v[54:57], v[216:219], v[164:167], v[54:57]
	v_mfma_f32_16x16x32_bf16 v[50:53], v[224:227], v[164:167], v[50:53]
	v_mfma_f32_16x16x32_bf16 v[38:41], v[216:219], v[172:175], v[38:41]
	v_mfma_f32_16x16x32_bf16 v[34:37], v[224:227], v[172:175], v[34:37]
	v_mfma_f32_16x16x32_bf16 v[22:25], v[216:219], v[180:183], v[22:25]
	v_mfma_f32_16x16x32_bf16 v[18:21], v[224:227], v[180:183], v[18:21]
	v_mfma_f32_16x16x32_bf16 v[6:9], v[216:219], v[188:191], v[6:9]
	v_mfma_f32_16x16x32_bf16 v[2:5], v[224:227], v[188:191], v[2:5]
	v_mfma_f32_16x16x32_bf16 v[54:57], v[220:223], v[168:171], v[54:57]
	v_mfma_f32_16x16x32_bf16 v[50:53], v[228:231], v[168:171], v[50:53]
	v_mfma_f32_16x16x32_bf16 v[38:41], v[220:223], v[176:179], v[38:41]
	v_mfma_f32_16x16x32_bf16 v[34:37], v[228:231], v[176:179], v[34:37]
	v_mfma_f32_16x16x32_bf16 v[22:25], v[220:223], v[184:187], v[22:25]
	v_mfma_f32_16x16x32_bf16 v[18:21], v[228:231], v[184:187], v[18:21]
	v_mfma_f32_16x16x32_bf16 v[6:9], v[220:223], v[212:215], v[6:9]
	v_mfma_f32_16x16x32_bf16 v[2:5], v[228:231], v[212:215], v[2:5]
	s_setprio 0
	s_cmp_ge_i32 s29, s46
	s_mov_b64 s[14:15], s[16:17]
	s_mov_b32 s18, s29
	s_barrier
	s_cbranch_scc0 .LBB0_400
	s_mov_b64 s[20:21], s[34:35]
	v_mov_b32_e32 v219, v196
	s_branch .LBB0_389

; #define PG8_STAGE(bufoff, gbase, voff) do { _Pragma("unroll") for (int _i = 0; _i < 2; ++_i) \
;     __builtin_amdgcn_global_load_lds((const unsigned*)((const char*)(gbase) + (voff)[_i]), (LAS unsigned*)(lds + (bufoff) + ldsw + _i * 8192), 16, 0, 0); } while (0)
; #define PG8_LDA(dst, b, h) do { _Pragma("unroll") for (int m = 0; m < 4; ++m) _Pragma("unroll") for (int k = 0; k < 2; ++k) dst[m][k] = *(const LAS bf16x8*)(lds + PG8_SA(b, h) + aoff + m * 2048 + k * 1024); } while (0)
; #define PG8_LDB(dst, b, h) do { _Pragma("unroll") for (int n = 0; n < 2; ++n) _Pragma("unroll") for (int k = 0; k < 2; ++k) dst[n][k] = *(const LAS bf16x8*)(lds + PG8_SB(b, h) + boff + n * 2048 + k * 1024); } while (0)
; #define PG8_MMA(ai, bj, At, Bt) do { __builtin_amdgcn_s_setprio(1); _Pragma("unroll") for (int m = 0; m < 4; ++m) _Pragma("unroll") for (int n = 0; n < 2; ++n) _Pragma("unroll") for (int k = 0; k < 2; ++k) \
;     acc[ai][bj][m][n] = __builtin_amdgcn_mfma_f32_16x16x32_bf16(Bt[n][k], At[m][k], acc[ai][bj][m][n], 0, 0, 0); __builtin_amdgcn_s_setprio(0); } while (0)
; #define PG8_WAIT_L(n) asm volatile("s_waitcnt lgkmcnt(" #n ")" ::: "memory")
; #define PG8_BAR __builtin_amdgcn_s_barrier()
; #define PG8_SCHED __builtin_amdgcn_sched_barrier(0)
; template <class Epi, bool SPLITA = false>
; __device__ __forceinline__ void gemm_phase(const int tid, LAS unsigned char* lds, const Gemm g, const Order& S, const Epi& E) {
;     ...
;       const char* a1 = PG8_TA(t + 1);
;       const char* a2 = last ? nA : PG8_TA(t + 2); const char* b2 = last ? nB : cB + (size_t)(t + 2) * kstep;
;       const char* a3 = last ? nA + kstep : PG8_TA(t + 3); const char* b3 = b2 + kstep;
;       PG8_LDB(B0, 0, 0); PG8_SCHED; PG8_LDA(At, 0, 0); PG8_STAGE(PG8_SA(1, 1), a1 + hstepA, voffA);
;       PG8_WAIT_L(8); PG8_BAR; PG8_WAIT_L(0); PG8_MMA(0, 0, At, B0); PG8_BAR; PG8_SCHED;
;       PG8_LDB(B1, 0, 1); PG8_STAGE(PG8_SB(0, 0), b2, voffB);
;       PG8_BAR; PG8_WAIT_L(0); PG8_MMA(0, 1, At, B1); PG8_BAR;
;       PG8_LDA(At, 0, 1); PG8_STAGE(PG8_SA(0, 0), a2, voffA);
;       PG8_BAR; PG8_WAIT_L(0); PG8_MMA(1, 0, At, B0); PG8_BAR; PG8_SCHED;
.LBB0_463:
	s_add_u32 s20, s16, s40
	s_addc_u32 s21, s17, s41
	s_add_u32 s22, s20, 0x100
	s_addc_u32 s23, s21, 0
	s_add_u32 s29, vcc_lo, s40
	s_addc_u32 s42, vcc_hi, s41
	s_add_u32 s20, s20, 0x180
	s_addc_u32 s21, s21, 0
	s_add_i32 s94, 0, 0x10000
	v_add_u32_e32 v156, s94, v182
	ds_read_b128 v[62:65], v156
	ds_read_b128 v[74:77], v156 offset:1024
	ds_read_b128 v[78:81], v156 offset:2048
	ds_read_b128 v[156:159], v156 offset:3072
	s_cmpk_eq_i32 s40, 0xf00
	s_cselect_b32 s49, s93, s21
	s_cselect_b32 s48, s91, s20
	s_cselect_b32 s43, s9, s42
	s_cselect_b32 s42, s28, s29
	s_cselect_b32 s55, s1, s23
	s_cselect_b32 s54, s11, s22
	v_lshl_add_u64 v[192:193], v[58:59], 0, s[40:41]
	s_add_i32 m0, s19, 0xc000
	ds_read_b128 v[160:163], v183
	ds_read_b128 v[164:167], v183 offset:1024
	ds_read_b128 v[168:171], v183 offset:2048
	ds_read_b128 v[172:175], v183 offset:3072
	ds_read_b128 v[176:179], v183 offset:4096
	ds_read_b128 v[184:187], v183 offset:5120
	ds_read_b128 v[188:191], v183 offset:6144
	ds_read_b128 v[212:215], v183 offset:7168
	global_load_lds_dwordx4 v[192:193], off
	v_lshl_add_u64 v[192:193], v[60:61], 0, s[40:41]
	s_add_i32 m0, s19, 0xe000
	s_nop 0
	global_load_lds_dwordx4 v[192:193], off
	s_waitcnt lgkmcnt(8)
	s_barrier
	s_waitcnt lgkmcnt(0)
	s_setprio 1
	s_waitcnt lgkmcnt(0)
	v_mfma_f32_16x16x32_bf16 v[142:145], v[62:65], v[160:163], v[142:145]
	v_mfma_f32_16x16x32_bf16 v[138:141], v[78:81], v[160:163], v[138:141]
	v_mfma_f32_16x16x32_bf16 v[126:129], v[62:65], v[168:171], v[126:129]
	v_mfma_f32_16x16x32_bf16 v[122:125], v[78:81], v[168:171], v[122:125]
	v_mfma_f32_16x16x32_bf16 v[110:113], v[62:65], v[176:179], v[110:113]
	v_mfma_f32_16x16x32_bf16 v[106:109], v[78:81], v[176:179], v[106:109]
	v_mfma_f32_16x16x32_bf16 v[94:97], v[62:65], v[188:191], v[94:97]
	v_mfma_f32_16x16x32_bf16 v[90:93], v[78:81], v[188:191], v[90:93]
	v_mfma_f32_16x16x32_bf16 v[142:145], v[74:77], v[164:167], v[142:145]
	v_mfma_f32_16x16x32_bf16 v[138:141], v[156:159], v[164:167], v[138:141]
	v_mfma_f32_16x16x32_bf16 v[126:129], v[74:77], v[172:175], v[126:129]
	v_mfma_f32_16x16x32_bf16 v[122:125], v[156:159], v[172:175], v[122:125]
	v_mfma_f32_16x16x32_bf16 v[110:113], v[74:77], v[184:187], v[110:113]
	v_mfma_f32_16x16x32_bf16 v[106:109], v[156:159], v[184:187], v[106:109]
	v_mfma_f32_16x16x32_bf16 v[94:97], v[74:77], v[212:215], v[94:97]
	v_mfma_f32_16x16x32_bf16 v[90:93], v[156:159], v[212:215], v[90:93]
	s_setprio 0
	s_barrier
	s_add_i32 s20, 0, 0x14000
	v_add_u32_e32 v192, s20, v182
	s_add_i32 s21, s94, s30
	ds_read_b128 v[216:219], v192
	ds_read_b128 v[220:223], v192 offset:1024
	ds_read_b128 v[224:227], v192 offset:2048
	ds_read_b128 v[228:231], v192 offset:3072
	s_mov_b32 m0, s21
	s_nop 0
	global_load_lds_dwordx4 v0, s[42:43]
	s_add_i32 m0, s21, 0x2000
	s_nop 0
	global_load_lds_dwordx4 v150, s[42:43]
	s_barrier
	s_waitcnt lgkmcnt(0)
	s_setprio 1
	s_waitcnt lgkmcnt(0)
	v_mfma_f32_16x16x32_bf16 v[134:137], v[216:219], v[160:163], v[134:137]
	v_mfma_f32_16x16x32_bf16 v[130:133], v[224:227], v[160:163], v[130:133]
	v_mfma_f32_16x16x32_bf16 v[118:121], v[216:219], v[168:171], v[118:121]
	v_mfma_f32_16x16x32_bf16 v[114:117], v[224:227], v[168:171], v[114:117]
	v_mfma_f32_16x16x32_bf16 v[102:105], v[216:219], v[176:179], v[102:105]
	v_mfma_f32_16x16x32_bf16 v[98:101], v[224:227], v[176:179], v[98:101]
	v_mfma_f32_16x16x32_bf16 v[86:89], v[216:219], v[188:191], v[86:89]
	v_mfma_f32_16x16x32_bf16 v[82:85], v[224:227], v[188:191], v[82:85]
	v_mfma_f32_16x16x32_bf16 v[134:137], v[220:223], v[164:167], v[134:137]
	v_mfma_f32_16x16x32_bf16 v[130:133], v[228:231], v[164:167], v[130:133]
	v_mfma_f32_16x16x32_bf16 v[118:121], v[220:223], v[172:175], v[118:121]
	v_mfma_f32_16x16x32_bf16 v[114:117], v[228:231], v[172:175], v[114:117]
	v_mfma_f32_16x16x32_bf16 v[102:105], v[220:223], v[184:187], v[102:105]
	v_mfma_f32_16x16x32_bf16 v[98:101], v[228:231], v[184:187], v[98:101]
	v_mfma_f32_16x16x32_bf16 v[86:89], v[220:223], v[212:215], v[86:89]
	v_mfma_f32_16x16x32_bf16 v[82:85], v[228:231], v[212:215], v[82:85]
	s_setprio 0
	s_mov_b32 m0, s19
	s_barrier
	ds_read_b128 v[160:163], v183 offset:16384
	ds_read_b128 v[164:167], v183 offset:17408
	ds_read_b128 v[168:171], v183 offset:18432
	ds_read_b128 v[172:175], v183 offset:19456
	ds_read_b128 v[176:179], v183 offset:20480
	ds_read_b128 v[184:187], v183 offset:21504
	ds_read_b128 v[188:191], v183 offset:22528
	ds_read_b128 v[212:215], v183 offset:23552
	global_load_lds_dwordx4 v146, s[54:55]
	s_mov_b32 m0, s31
	s_nop 0
	global_load_lds_dwordx4 v148, s[54:55]
	s_barrier
	s_waitcnt lgkmcnt(0)
	s_setprio 1
	s_waitcnt lgkmcnt(0)
	v_mfma_f32_16x16x32_bf16 v[70:73], v[62:65], v[160:163], v[70:73]
	v_mfma_f32_16x16x32_bf16 v[66:69], v[78:81], v[160:163], v[66:69]
	v_mfma_f32_16x16x32_bf16 v[46:49], v[62:65], v[168:171], v[46:49]
	v_mfma_f32_16x16x32_bf16 v[42:45], v[78:81], v[168:171], v[42:45]
	v_mfma_f32_16x16x32_bf16 v[30:33], v[62:65], v[176:179], v[30:33]
	v_mfma_f32_16x16x32_bf16 v[26:29], v[78:81], v[176:179], v[26:29]
	v_mfma_f32_16x16x32_bf16 v[14:17], v[62:65], v[188:191], v[14:17]
	v_mfma_f32_16x16x32_bf16 v[10:13], v[78:81], v[188:191], v[10:13]
	v_mfma_f32_16x16x32_bf16 v[70:73], v[74:77], v[164:167], v[70:73]
	v_mfma_f32_16x16x32_bf16 v[66:69], v[156:159], v[164:167], v[66:69]
	v_mfma_f32_16x16x32_bf16 v[46:49], v[74:77], v[172:175], v[46:49]
	v_mfma_f32_16x16x32_bf16 v[42:45], v[156:159], v[172:175], v[42:45]
	v_mfma_f32_16x16x32_bf16 v[30:33], v[74:77], v[184:187], v[30:33]
	v_mfma_f32_16x16x32_bf16 v[26:29], v[156:159], v[184:187], v[26:29]
	v_mfma_f32_16x16x32_bf16 v[14:17], v[74:77], v[212:215], v[14:17]
	v_mfma_f32_16x16x32_bf16 v[10:13], v[156:159], v[212:215], v[10:13]
	s_setprio 0
	s_barrier
; #define PG8_STAGE(bufoff, gbase, voff) do { _Pragma("unroll") for (int _i = 0; _i < 2; ++_i) \
;     __builtin_amdgcn_global_load_lds((const unsigned*)((const char*)(gbase) + (voff)[_i]), (LAS unsigned*)(lds + (bufoff) + ldsw + _i * 8192), 16, 0, 0); } while (0)
; #define PG8_LDA(dst, b, h) do { _Pragma("unroll") for (int m = 0; m < 4; ++m) _Pragma("unroll") for (int k = 0; k < 2; ++k) dst[m][k] = *(const LAS bf16x8*)(lds + PG8_SA(b, h) + aoff + m * 2048 + k * 1024); } while (0)
; #define PG8_LDB(dst, b, h) do { _Pragma("unroll") for (int n = 0; n < 2; ++n) _Pragma("unroll") for (int k = 0; k < 2; ++k) dst[n][k] = *(const LAS bf16x8*)(lds + PG8_SB(b, h) + boff + n * 2048 + k * 1024); } while (0)
; #define PG8_MMA(ai, bj, At, Bt) do { __builtin_amdgcn_s_setprio(1); _Pragma("unroll") for (int m = 0; m < 4; ++m) _Pragma("unroll") for (int n = 0; n < 2; ++n) _Pragma("unroll") for (int k = 0; k < 2; ++k) \
;     acc[ai][bj][m][n] = __builtin_amdgcn_mfma_f32_16x16x32_bf16(Bt[n][k], At[m][k], acc[ai][bj][m][n], 0, 0, 0); __builtin_amdgcn_s_setprio(0); } while (0)
; #define PG8_WAIT_V(n) asm volatile("s_waitcnt vmcnt(" #n ")" ::: "memory")
; #define PG8_WAIT_L(n) asm volatile("s_waitcnt lgkmcnt(" #n ")" ::: "memory")
; #define PG8_BAR __builtin_amdgcn_s_barrier()
; #define PG8_SCHED __builtin_amdgcn_sched_barrier(0)
; template <class Epi, bool SPLITA = false>
; __device__ __forceinline__ void gemm_phase(const int tid, LAS unsigned char* lds, const Gemm g, const Order& S, const Epi& E) {
;     ...
;       PG8_STAGE(PG8_SB(0, 1), b2 + hstepB, voffB);
;       PG8_WAIT_V(6); PG8_BAR; PG8_MMA(1, 1, At, B1); PG8_BAR;
;       PG8_LDB(B0, 1, 0); PG8_SCHED; PG8_LDA(At, 1, 0); PG8_STAGE(PG8_SA(0, 1), a2 + hstepA, voffA);
;       PG8_WAIT_L(8); PG8_BAR; PG8_WAIT_L(0); PG8_MMA(0, 0, At, B0); PG8_BAR; PG8_SCHED;
;       PG8_LDB(B1, 1, 1); PG8_STAGE(PG8_SB(1, 0), b3, voffB);
	s_add_u32 s22, s42, 0x80000
	s_addc_u32 s23, s43, 0
	s_add_i32 s20, s20, s30
	s_mov_b32 m0, s20
	s_nop 0
	global_load_lds_dwordx4 v0, s[22:23]
	s_add_i32 m0, s20, 0x2000
	s_nop 0
	global_load_lds_dwordx4 v150, s[22:23]
	s_waitcnt vmcnt(6)
	s_barrier
	s_setprio 1
	v_mfma_f32_16x16x32_bf16 v[54:57], v[216:219], v[160:163], v[54:57]
	v_mfma_f32_16x16x32_bf16 v[50:53], v[224:227], v[160:163], v[50:53]
	v_mfma_f32_16x16x32_bf16 v[38:41], v[216:219], v[168:171], v[38:41]
	v_mfma_f32_16x16x32_bf16 v[34:37], v[224:227], v[168:171], v[34:37]
	v_mfma_f32_16x16x32_bf16 v[22:25], v[216:219], v[176:179], v[22:25]
	v_mfma_f32_16x16x32_bf16 v[18:21], v[224:227], v[176:179], v[18:21]
	v_mfma_f32_16x16x32_bf16 v[6:9], v[216:219], v[188:191], v[6:9]
	v_mfma_f32_16x16x32_bf16 v[2:5], v[224:227], v[188:191], v[2:5]
	v_mfma_f32_16x16x32_bf16 v[54:57], v[220:223], v[164:167], v[54:57]
	v_mfma_f32_16x16x32_bf16 v[50:53], v[228:231], v[164:167], v[50:53]
	v_mfma_f32_16x16x32_bf16 v[38:41], v[220:223], v[172:175], v[38:41]
	v_mfma_f32_16x16x32_bf16 v[34:37], v[228:231], v[172:175], v[34:37]
	v_mfma_f32_16x16x32_bf16 v[22:25], v[220:223], v[184:187], v[22:25]
	v_mfma_f32_16x16x32_bf16 v[18:21], v[228:231], v[184:187], v[18:21]
	v_mfma_f32_16x16x32_bf16 v[6:9], v[220:223], v[212:215], v[6:9]
	v_mfma_f32_16x16x32_bf16 v[2:5], v[228:231], v[212:215], v[2:5]
	s_setprio 0
	s_add_i32 s20, 0, 0x18000
	v_add_u32_e32 v156, s20, v182
	s_barrier
	ds_read_b128 v[62:65], v156
	ds_read_b128 v[74:77], v156 offset:1024
	ds_read_b128 v[78:81], v156 offset:2048
	ds_read_b128 v[156:159], v156 offset:3072
	s_add_u32 s22, s54, 0x80000
	s_addc_u32 s23, s55, 0
	s_mov_b32 m0, s44
	ds_read_b128 v[160:163], v183 offset:32768
	ds_read_b128 v[164:167], v183 offset:33792
	ds_read_b128 v[168:171], v183 offset:34816
	ds_read_b128 v[172:175], v183 offset:35840
	ds_read_b128 v[176:179], v183 offset:36864
	ds_read_b128 v[184:187], v183 offset:37888
	ds_read_b128 v[188:191], v183 offset:38912
	ds_read_b128 v[212:215], v183 offset:39936
	global_load_lds_dwordx4 v146, s[22:23]
	s_mov_b32 m0, s45
	s_nop 0
	global_load_lds_dwordx4 v148, s[22:23]
	s_waitcnt lgkmcnt(8)
	s_barrier
	s_waitcnt lgkmcnt(0)
	s_setprio 1
	s_waitcnt lgkmcnt(0)
	v_mfma_f32_16x16x32_bf16 v[142:145], v[62:65], v[160:163], v[142:145]
	v_mfma_f32_16x16x32_bf16 v[138:141], v[78:81], v[160:163], v[138:141]
	v_mfma_f32_16x16x32_bf16 v[126:129], v[62:65], v[168:171], v[126:129]
	v_mfma_f32_16x16x32_bf16 v[122:125], v[78:81], v[168:171], v[122:125]
	v_mfma_f32_16x16x32_bf16 v[110:113], v[62:65], v[176:179], v[110:113]
	v_mfma_f32_16x16x32_bf16 v[106:109], v[78:81], v[176:179], v[106:109]
	v_mfma_f32_16x16x32_bf16 v[94:97], v[62:65], v[188:191], v[94:97]
	v_mfma_f32_16x16x32_bf16 v[90:93], v[78:81], v[188:191], v[90:93]
	v_mfma_f32_16x16x32_bf16 v[142:145], v[74:77], v[164:167], v[142:145]
	v_mfma_f32_16x16x32_bf16 v[138:141], v[156:159], v[164:167], v[138:141]
	v_mfma_f32_16x16x32_bf16 v[126:129], v[74:77], v[172:175], v[126:129]
	v_mfma_f32_16x16x32_bf16 v[122:125], v[156:159], v[172:175], v[122:125]
	v_mfma_f32_16x16x32_bf16 v[110:113], v[74:77], v[184:187], v[110:113]
	v_mfma_f32_16x16x32_bf16 v[106:109], v[156:159], v[184:187], v[106:109]
	v_mfma_f32_16x16x32_bf16 v[94:97], v[74:77], v[212:215], v[94:97]
	v_mfma_f32_16x16x32_bf16 v[90:93], v[156:159], v[212:215], v[90:93]
	s_setprio 0
	s_barrier
	s_add_i32 s21, 0, 0x1c000
	s_add_i32 s20, s20, s30
	v_add_u32_e32 v195, s21, v182
	s_add_i32 m0, s20, 0xffffff80
	ds_read_b128 v[216:219], v195
	ds_read_b128 v[220:223], v195 offset:1024
	ds_read_b128 v[224:227], v195 offset:2048
	ds_read_b128 v[228:231], v195 offset:3072
	global_load_lds_dwordx4 v0, s[42:43] offset:128
	s_add_i32 m0, s20, 0x1f80
	s_nop 0
	global_load_lds_dwordx4 v150, s[42:43] offset:128
	s_barrier
; #define PG8_STAGE(bufoff, gbase, voff) do { _Pragma("unroll") for (int _i = 0; _i < 2; ++_i) \
;     __builtin_amdgcn_global_load_lds((const unsigned*)((const char*)(gbase) + (voff)[_i]), (LAS unsigned*)(lds + (bufoff) + ldsw + _i * 8192), 16, 0, 0); } while (0)
; #define PG8_LDA(dst, b, h) do { _Pragma("unroll") for (int m = 0; m < 4; ++m) _Pragma("unroll") for (int k = 0; k < 2; ++k) dst[m][k] = *(const LAS bf16x8*)(lds + PG8_SA(b, h) + aoff + m * 2048 + k * 1024); } while (0)
; #define PG8_MMA(ai, bj, At, Bt) do { __builtin_amdgcn_s_setprio(1); _Pragma("unroll") for (int m = 0; m < 4; ++m) _Pragma("unroll") for (int n = 0; n < 2; ++n) _Pragma("unroll") for (int k = 0; k < 2; ++k) \
;     acc[ai][bj][m][n] = __builtin_amdgcn_mfma_f32_16x16x32_bf16(Bt[n][k], At[m][k], acc[ai][bj][m][n], 0, 0, 0); __builtin_amdgcn_s_setprio(0); } while (0)
; #define PG8_WAIT_V(n) asm volatile("s_waitcnt vmcnt(" #n ")" ::: "memory")
; #define PG8_WAIT_L(n) asm volatile("s_waitcnt lgkmcnt(" #n ")" ::: "memory")
; #define PG8_BAR __builtin_amdgcn_s_barrier()
; #define PG8_SCHED __builtin_amdgcn_sched_barrier(0)
; template <class Epi, bool SPLITA = false>
; __device__ __forceinline__ void gemm_phase(const int tid, LAS unsigned char* lds, const Gemm g, const Order& S, const Epi& E) {
;     ...
;       PG8_BAR; PG8_WAIT_L(0); PG8_MMA(0, 1, At, B1); PG8_BAR;
;       PG8_LDA(At, 1, 1); PG8_STAGE(PG8_SA(1, 0), a3, voffA);
;       PG8_BAR; PG8_WAIT_L(0); PG8_MMA(1, 0, At, B0); PG8_BAR; PG8_SCHED;
;       PG8_STAGE(PG8_SB(1, 1), b3 + hstepB, voffB);
;       PG8_WAIT_V(6); PG8_BAR; PG8_MMA(1, 1, At, B1); PG8_BAR;
;   __device__ __forceinline__ void operator()(const Acc& acc, const Unit& u, int wr, int wc, int fr_, int fq_) const {
;     ...
;     if (u.pn < 4) { base = Q; ld = 1024; c0 = u.pn * 256; }
;     else if (u.pn == 4) { base = Kb; ld = 256; c0 = 0; }
;     else if (u.pn == 5) { base = Vb; ld = 256; c0 = 0; }
;     else if (u.pn < 10) { base = F; ld = 1024; c0 = (u.pn - 6) * 256; }
;     else { base = Gt; ld = 4096; c0 = (u.pn - 10) * 256; gate = true; }
	s_waitcnt lgkmcnt(0)
	s_setprio 1
	s_waitcnt lgkmcnt(0)
	v_mfma_f32_16x16x32_bf16 v[134:137], v[216:219], v[160:163], v[134:137]
	v_mfma_f32_16x16x32_bf16 v[130:133], v[224:227], v[160:163], v[130:133]
	v_mfma_f32_16x16x32_bf16 v[118:121], v[216:219], v[168:171], v[118:121]
	v_mfma_f32_16x16x32_bf16 v[114:117], v[224:227], v[168:171], v[114:117]
	v_mfma_f32_16x16x32_bf16 v[102:105], v[216:219], v[176:179], v[102:105]
	v_mfma_f32_16x16x32_bf16 v[98:101], v[224:227], v[176:179], v[98:101]
	v_mfma_f32_16x16x32_bf16 v[86:89], v[216:219], v[188:191], v[86:89]
	v_mfma_f32_16x16x32_bf16 v[82:85], v[224:227], v[188:191], v[82:85]
	v_mfma_f32_16x16x32_bf16 v[134:137], v[220:223], v[164:167], v[134:137]
	v_mfma_f32_16x16x32_bf16 v[130:133], v[228:231], v[164:167], v[130:133]
	v_mfma_f32_16x16x32_bf16 v[118:121], v[220:223], v[172:175], v[118:121]
	v_mfma_f32_16x16x32_bf16 v[114:117], v[228:231], v[172:175], v[114:117]
	v_mfma_f32_16x16x32_bf16 v[102:105], v[220:223], v[184:187], v[102:105]
	v_mfma_f32_16x16x32_bf16 v[98:101], v[228:231], v[184:187], v[98:101]
	v_mfma_f32_16x16x32_bf16 v[86:89], v[220:223], v[212:215], v[86:89]
	v_mfma_f32_16x16x32_bf16 v[82:85], v[228:231], v[212:215], v[82:85]
	s_setprio 0
	s_mov_b32 m0, s51
	s_barrier
	ds_read_b128 v[160:163], v183 offset:49152
	ds_read_b128 v[164:167], v183 offset:50176
	ds_read_b128 v[168:171], v183 offset:51200
	ds_read_b128 v[172:175], v183 offset:52224
	ds_read_b128 v[176:179], v183 offset:53248
	ds_read_b128 v[184:187], v183 offset:54272
	ds_read_b128 v[188:191], v183 offset:55296
	ds_read_b128 v[212:215], v183 offset:56320
	global_load_lds_dwordx4 v146, s[48:49]
	s_mov_b32 m0, s52
	s_nop 0
	global_load_lds_dwordx4 v148, s[48:49]
	s_barrier
	s_waitcnt lgkmcnt(0)
	s_setprio 1
	s_waitcnt lgkmcnt(0)
	v_mfma_f32_16x16x32_bf16 v[70:73], v[62:65], v[160:163], v[70:73]
	v_mfma_f32_16x16x32_bf16 v[66:69], v[78:81], v[160:163], v[66:69]
	v_mfma_f32_16x16x32_bf16 v[46:49], v[62:65], v[168:171], v[46:49]
	v_mfma_f32_16x16x32_bf16 v[42:45], v[78:81], v[168:171], v[42:45]
	v_mfma_f32_16x16x32_bf16 v[30:33], v[62:65], v[176:179], v[30:33]
	v_mfma_f32_16x16x32_bf16 v[26:29], v[78:81], v[176:179], v[26:29]
	v_mfma_f32_16x16x32_bf16 v[14:17], v[62:65], v[188:191], v[14:17]
	v_mfma_f32_16x16x32_bf16 v[10:13], v[78:81], v[188:191], v[10:13]
	v_mfma_f32_16x16x32_bf16 v[70:73], v[74:77], v[164:167], v[70:73]
	v_mfma_f32_16x16x32_bf16 v[66:69], v[156:159], v[164:167], v[66:69]
	v_mfma_f32_16x16x32_bf16 v[46:49], v[74:77], v[172:175], v[46:49]
	v_mfma_f32_16x16x32_bf16 v[42:45], v[156:159], v[172:175], v[42:45]
	v_mfma_f32_16x16x32_bf16 v[30:33], v[74:77], v[184:187], v[30:33]
	v_mfma_f32_16x16x32_bf16 v[26:29], v[156:159], v[184:187], v[26:29]
	v_mfma_f32_16x16x32_bf16 v[14:17], v[74:77], v[212:215], v[14:17]
	v_mfma_f32_16x16x32_bf16 v[10:13], v[156:159], v[212:215], v[10:13]
	s_setprio 0
	s_barrier
	s_add_u32 s22, s42, 0x80080
	s_addc_u32 s23, s43, 0
	s_add_i32 s20, s21, s30
	s_mov_b32 m0, s20
	s_nop 0
	global_load_lds_dwordx4 v0, s[22:23]
	s_add_i32 m0, s20, 0x2000
	s_nop 0
	global_load_lds_dwordx4 v150, s[22:23]
	s_waitcnt vmcnt(6)
	s_barrier
	s_setprio 1
	v_mfma_f32_16x16x32_bf16 v[54:57], v[216:219], v[160:163], v[54:57]
	v_mfma_f32_16x16x32_bf16 v[50:53], v[224:227], v[160:163], v[50:53]
	v_mfma_f32_16x16x32_bf16 v[38:41], v[216:219], v[168:171], v[38:41]
	v_mfma_f32_16x16x32_bf16 v[34:37], v[224:227], v[168:171], v[34:37]
	v_mfma_f32_16x16x32_bf16 v[22:25], v[216:219], v[176:179], v[22:25]
	v_mfma_f32_16x16x32_bf16 v[18:21], v[224:227], v[176:179], v[18:21]
	v_mfma_f32_16x16x32_bf16 v[6:9], v[216:219], v[188:191], v[6:9]
	v_mfma_f32_16x16x32_bf16 v[2:5], v[224:227], v[188:191], v[2:5]
	v_mfma_f32_16x16x32_bf16 v[54:57], v[220:223], v[164:167], v[54:57]
	v_mfma_f32_16x16x32_bf16 v[50:53], v[228:231], v[164:167], v[50:53]
	v_mfma_f32_16x16x32_bf16 v[38:41], v[220:223], v[172:175], v[38:41]
	v_mfma_f32_16x16x32_bf16 v[34:37], v[228:231], v[172:175], v[34:37]
	v_mfma_f32_16x16x32_bf16 v[22:25], v[220:223], v[184:187], v[22:25]
	v_mfma_f32_16x16x32_bf16 v[18:21], v[228:231], v[184:187], v[18:21]
	v_mfma_f32_16x16x32_bf16 v[6:9], v[220:223], v[212:215], v[6:9]
	v_mfma_f32_16x16x32_bf16 v[2:5], v[228:231], v[212:215], v[2:5]
	s_setprio 0
	s_add_i32 s4, s4, 2
	s_add_u32 s40, s40, 0x100
	s_addc_u32 s41, s41, 0
	s_cmp_gt_u32 s4, 29
	s_barrier
	s_cbranch_scc0 .LBB0_463
	v_mov_b32_e32 v158, v181
	v_mov_b32_e32 v58, v180
	s_cmp_gt_i32 s0, 3
	s_mov_b64 s[48:49], -1
	s_mov_b64 s[20:21], s[34:35]
	s_cbranch_scc0 .LBB0_475
	s_cmp_lt_i32 s0, 5
	s_mov_b64 s[48:49], 0
	s_cbranch_scc1 .LBB0_474
	s_cmp_lg_u32 s0, 5
	s_mov_b64 s[54:55], -1
	s_cbranch_scc0 .LBB0_472
	s_lshl_b32 s4, s0, 8
	s_cmp_gt_u32 s0, 9
	s_mov_b64 s[40:41], -1
	s_mov_b64 s[42:43], -1
	s_cbranch_scc0 .LBB0_469
	s_add_i32 s1, s4, 0xfffff600
	s_mov_b64 s[42:43], 0
